# GEMM k-loops: last two column groups issued row-major so each A fragment retires early and its next-iteration load is issued between MFMAs (spread loads)
# baseline (speedup 1.0000x reference)
.LBB0_215:
	s_mul_hi_i32 s0, s8, 0x2aaaaaab
	s_lshr_b32 s1, s0, 31
	s_ashr_i32 s0, s0, 5
	s_add_i32 s0, s0, s1
	s_lshl_b32 s1, s0, 3
	s_sub_i32 s2, 17, s1
	s_min_u32 s2, s2, 8
	v_cvt_f32_ubyte0_e32 v0, s2
	v_rcp_iflag_f32_e32 v0, v0
	s_sub_i32 s5, 0, s2
	s_mulk_i32 s0, 0xff40
	s_add_i32 s3, s0, s8
	v_mul_f32_e32 v0, 0x4f7ffffe, v0
	v_cvt_u32_f32_e32 v0, v0
	s_abs_i32 s4, s3
	s_ashr_i32 s0, s3, 31
	v_mov_b32_e32 v181, v179
	v_readfirstlane_b32 s6, v0
	s_mul_i32 s5, s5, s6
	s_mul_hi_u32 s5, s6, s5
	s_add_i32 s6, s6, s5
	s_mul_hi_u32 s5, s4, s6
	s_mul_i32 s6, s5, s2
	s_sub_i32 s4, s4, s6
	s_add_i32 s6, s5, 1
	s_sub_i32 s7, s4, s2
	s_cmp_ge_u32 s4, s2
	s_cselect_b32 s5, s6, s5
	s_cselect_b32 s4, s7, s4
	s_add_i32 s6, s5, 1
	s_cmp_ge_u32 s4, s2
	s_cselect_b32 s4, s6, s5
	s_xor_b32 s4, s4, s0
	s_sub_i32 s0, s4, s0
	s_mul_i32 s2, s2, s0
	s_sub_i32 s2, s3, s2
	s_add_i32 s1, s1, s11
	s_add_i32 s2, s1, s2
	v_ashrrev_i32_e32 v233, 6, v181
	v_lshlrev_b32_e32 v0, 1, v233
	v_lshl_add_u32 v0, s2, 3, v0
	v_ashrrev_i32_e32 v1, 31, v0
	v_bfe_u32 v183, v181, 5, 1
	v_lshlrev_b64 v[0:1], 16, v[0:1]
	v_and_b32_e32 v231, 31, v181
	v_lshl_add_u64 v[0:1], s[64:65], 0, v[0:1]
	v_lshlrev_b32_e32 v176, 9, v183
	s_ashr_i32 s1, s0, 31
	v_lshl_add_u64 v[0:1], v[0:1], 0, v[176:177]
	v_lshlrev_b32_e32 v176, 4, v231
	v_ashrrev_i32_e32 v12, 2, v181
	s_lshl_b64 s[4:5], s[0:1], 18
	v_lshl_add_u64 v[184:185], v[0:1], 0, v[176:177]
	s_add_u32 s4, s9, s4
	v_lshlrev_b32_e32 v0, 5, v12
	s_addc_u32 s5, s10, s5
	v_ashrrev_i32_e32 v1, 31, v0
	v_lshlrev_b32_e32 v2, 4, v181
	v_lshl_add_u64 v[0:1], v[0:1], 1, s[4:5]
	v_and_b32_e32 v176, 48, v2
	v_lshl_add_u64 v[186:187], v[0:1], 0, v[176:177]
	s_movk_i32 s1, 0x2000
	v_add_co_u32_e32 v8, vcc, s1, v186
	v_mul_u32_u24_e32 v10, 40, v231
	s_nop 0
	v_addc_co_u32_e32 v9, vcc, 0, v187, vcc
	v_lshlrev_b32_e32 v11, 4, v183
	v_lshl_add_u32 v235, v10, 1, v11
	v_add_co_u32_e32 v10, vcc, s41, v184
	s_movk_i32 s3, 0x50
	s_nop 0
	v_addc_co_u32_e32 v11, vcc, 0, v185, vcc
	v_and_b32_e32 v232, 63, v181
	v_lshlrev_b32_e32 v234, 3, v181
	v_mov_b32_e32 v176, 0x800
	v_lshl_add_u64 v[188:189], v[186:187], 0, v[176:177]
	v_bfe_u32 v197, v181, 4, 1
	v_lshlrev_b32_e32 v176, 9, v183
	v_lshl_add_u32 v176, v197, 8, v176
	v_lshl_add_u64 v[184:185], v[184:185], 0, v[176:177]
	v_lshrrev_b32_e32 v235, 2, v181
	v_bfe_u32 v197, v181, 4, 2
	v_lshlrev_b32_e32 v197, 1, v197
	v_mov_b32_e32 v176, 0x78
	v_lshrrev_b32_e32 v197, v197, v176
	v_and_b32_e32 v197, 3, v197
	v_and_b32_e32 v196, 3, v181
	v_xor_b32_e32 v197, v197, v196
	v_lshlrev_b32_e32 v197, 4, v197
	v_lshl_add_u32 v235, v235, 6, v197
	v_bfe_u32 v197, v181, 2, 2
	v_lshlrev_b32_e32 v197, 1, v197
	v_lshrrev_b32_e32 v197, v197, v176
	v_and_b32_e32 v197, 3, v197
	v_bfe_u32 v196, v181, 4, 2
	v_xor_b32_e32 v197, v197, v196
	v_lshlrev_b32_e32 v197, 4, v197
	v_and_b32_e32 v196, 15, v181
	v_lshl_add_u32 v196, v196, 6, v197
	v_mov_b32_e32 v176, s41
	v_lshl_add_u64 v[186:187], v[184:185], 0, v[176:177]
	s_mov_b32 s96, 0
	v_lshl_add_u64 v[166:167], v[188:189], 0, s[96:97]
	global_load_dwordx4 v[160:163], v[166:167], off offset:-2048
	global_load_dwordx4 v[164:167], v[166:167], off offset:2048
	v_lshl_add_u64 v[198:199], v[184:185], 0, s[96:97]
	v_lshl_add_u64 v[200:201], v[186:187], 0, s[96:97]
	global_load_dwordx4 v[128:131], v[198:199], off
	global_load_dwordx4 v[132:135], v[198:199], off offset:256
	global_load_dwordx4 v[136:139], v[200:201], off
	global_load_dwordx4 v[140:143], v[200:201], off offset:256
	s_movk_i32 s96, 0x2000
	v_lshl_add_u64 v[174:175], v[188:189], 0, s[96:97]
	global_load_dwordx4 v[168:171], v[174:175], off offset:-2048
	global_load_dwordx4 v[172:175], v[174:175], off offset:2048
	s_movk_i32 s96, 0x800
	v_lshl_add_u64 v[198:199], v[184:185], 0, s[96:97]
	v_lshl_add_u64 v[200:201], v[186:187], 0, s[96:97]
	global_load_dwordx4 v[144:147], v[198:199], off
	global_load_dwordx4 v[148:151], v[198:199], off offset:256
	global_load_dwordx4 v[152:155], v[200:201], off
	global_load_dwordx4 v[156:159], v[200:201], off offset:256
	v_mov_b32_e32 v0, 0
	v_mov_b32_e32 v1, 0
	v_mov_b32_e32 v2, 0
	v_mov_b32_e32 v3, 0
	v_mov_b32_e32 v4, 0
	v_mov_b32_e32 v5, 0
	v_mov_b32_e32 v6, 0
	v_mov_b32_e32 v7, 0
	v_mov_b32_e32 v8, 0
	v_mov_b32_e32 v9, 0
	v_mov_b32_e32 v10, 0
	v_mov_b32_e32 v11, 0
	v_mov_b32_e32 v12, 0
	v_mov_b32_e32 v13, 0
	v_mov_b32_e32 v14, 0
	v_mov_b32_e32 v15, 0
	v_mov_b32_e32 v16, 0
	v_mov_b32_e32 v17, 0
	v_mov_b32_e32 v18, 0
	v_mov_b32_e32 v19, 0
	v_mov_b32_e32 v20, 0
	v_mov_b32_e32 v21, 0
	v_mov_b32_e32 v22, 0
	v_mov_b32_e32 v23, 0
	v_mov_b32_e32 v24, 0
	v_mov_b32_e32 v25, 0
	v_mov_b32_e32 v26, 0
	v_mov_b32_e32 v27, 0
	v_mov_b32_e32 v28, 0
	v_mov_b32_e32 v29, 0
	v_mov_b32_e32 v30, 0
	v_mov_b32_e32 v31, 0
	v_mov_b32_e32 v32, 0
	v_mov_b32_e32 v33, 0
	v_mov_b32_e32 v34, 0
	v_mov_b32_e32 v35, 0
	v_mov_b32_e32 v36, 0
	v_mov_b32_e32 v37, 0
	v_mov_b32_e32 v38, 0
	v_mov_b32_e32 v39, 0
	v_mov_b32_e32 v40, 0
	v_mov_b32_e32 v41, 0
	v_mov_b32_e32 v42, 0
	v_mov_b32_e32 v43, 0
	v_mov_b32_e32 v44, 0
	v_mov_b32_e32 v45, 0
	v_mov_b32_e32 v46, 0
	v_mov_b32_e32 v47, 0
	v_mov_b32_e32 v48, 0
	v_mov_b32_e32 v49, 0
	v_mov_b32_e32 v50, 0
	v_mov_b32_e32 v51, 0
	v_mov_b32_e32 v52, 0
	v_mov_b32_e32 v53, 0
	v_mov_b32_e32 v54, 0
	v_mov_b32_e32 v55, 0
	v_mov_b32_e32 v56, 0
	v_mov_b32_e32 v57, 0
	v_mov_b32_e32 v58, 0
	v_mov_b32_e32 v59, 0
	v_mov_b32_e32 v60, 0
	v_mov_b32_e32 v61, 0
	v_mov_b32_e32 v62, 0
	v_mov_b32_e32 v63, 0
	v_mov_b32_e32 v64, 0
	v_mov_b32_e32 v65, 0
	v_mov_b32_e32 v66, 0
	v_mov_b32_e32 v67, 0
	v_mov_b32_e32 v68, 0
	v_mov_b32_e32 v69, 0
	v_mov_b32_e32 v70, 0
	v_mov_b32_e32 v71, 0
	v_mov_b32_e32 v72, 0
	v_mov_b32_e32 v73, 0
	v_mov_b32_e32 v74, 0
	v_mov_b32_e32 v75, 0
	v_mov_b32_e32 v76, 0
	v_mov_b32_e32 v77, 0
	v_mov_b32_e32 v78, 0
	v_mov_b32_e32 v79, 0
	v_mov_b32_e32 v80, 0
	v_mov_b32_e32 v81, 0
	v_mov_b32_e32 v82, 0
	v_mov_b32_e32 v83, 0
	v_mov_b32_e32 v84, 0
	v_mov_b32_e32 v85, 0
	v_mov_b32_e32 v86, 0
	v_mov_b32_e32 v87, 0
	v_mov_b32_e32 v88, 0
	v_mov_b32_e32 v89, 0
	v_mov_b32_e32 v90, 0
	v_mov_b32_e32 v91, 0
	v_mov_b32_e32 v92, 0
	v_mov_b32_e32 v93, 0
	v_mov_b32_e32 v94, 0
	v_mov_b32_e32 v95, 0
	v_mov_b32_e32 v96, 0
	v_mov_b32_e32 v97, 0
	v_mov_b32_e32 v98, 0
	v_mov_b32_e32 v99, 0
	v_mov_b32_e32 v100, 0
	v_mov_b32_e32 v101, 0
	v_mov_b32_e32 v102, 0
	v_mov_b32_e32 v103, 0
	v_mov_b32_e32 v104, 0
	v_mov_b32_e32 v105, 0
	v_mov_b32_e32 v106, 0
	v_mov_b32_e32 v107, 0
	v_mov_b32_e32 v108, 0
	v_mov_b32_e32 v109, 0
	v_mov_b32_e32 v110, 0
	v_mov_b32_e32 v111, 0
	v_mov_b32_e32 v112, 0
	v_mov_b32_e32 v113, 0
	v_mov_b32_e32 v114, 0
	v_mov_b32_e32 v115, 0
	v_mov_b32_e32 v116, 0
	v_mov_b32_e32 v117, 0
	v_mov_b32_e32 v118, 0
	v_mov_b32_e32 v119, 0
	v_mov_b32_e32 v120, 0
	v_mov_b32_e32 v121, 0
	v_mov_b32_e32 v122, 0
	v_mov_b32_e32 v123, 0
	v_mov_b32_e32 v124, 0
	v_mov_b32_e32 v125, 0
	v_mov_b32_e32 v126, 0
	v_mov_b32_e32 v127, 0
	s_mov_b32 s1, 0
	s_waitcnt vmcnt(10)
	ds_write_b128 v235, v[160:163]
	ds_write_b128 v235, v[164:167] offset:4096
	s_waitcnt lgkmcnt(0)
	s_barrier
.Lg16_proj_k:
	s_add_i32 s3, s1, 2
	s_min_u32 s4, s3, 30
	s_lshl_b32 s96, s4, 13
	v_lshl_add_u64 v[166:167], v[188:189], 0, s[96:97]
	global_load_dwordx4 v[160:163], v[166:167], off offset:-2048
	global_load_dwordx4 v[164:167], v[166:167], off offset:2048
	ds_read_b128 v[236:239], v196 offset:0
	ds_read_b128 v[240:243], v196 offset:1024
	ds_read_b128 v[244:247], v196 offset:2048
	ds_read_b128 v[248:251], v196 offset:3072
	s_lshl_b32 s96, s4, 11
	v_lshl_add_u64 v[198:199], v[184:185], 0, s[96:97]
	v_lshl_add_u64 v[200:201], v[186:187], 0, s[96:97]
	s_waitcnt vmcnt(8) lgkmcnt(3)
	v_mfma_f32_16x16x32_bf16 v[16:19], v[128:131], v[236:239], v[16:19]
	v_mfma_f32_16x16x32_bf16 v[24:27], v[132:135], v[236:239], v[24:27]
	v_mfma_f32_16x16x32_bf16 v[0:3], v[136:139], v[236:239], v[0:3]
	v_mfma_f32_16x16x32_bf16 v[8:11], v[140:143], v[236:239], v[8:11]
	ds_read_b128 v[236:239], v196 offset:4096
	s_waitcnt lgkmcnt(3)
	v_mfma_f32_16x16x32_bf16 v[20:23], v[128:131], v[240:243], v[20:23]
	v_mfma_f32_16x16x32_bf16 v[28:31], v[132:135], v[240:243], v[28:31]
	v_mfma_f32_16x16x32_bf16 v[4:7], v[136:139], v[240:243], v[4:7]
	v_mfma_f32_16x16x32_bf16 v[12:15], v[140:143], v[240:243], v[12:15]
	ds_read_b128 v[240:243], v196 offset:5120
	s_waitcnt lgkmcnt(3)
	v_mfma_f32_16x16x32_bf16 v[112:115], v[128:131], v[244:247], v[112:115]
	v_mfma_f32_16x16x32_bf16 v[120:123], v[132:135], v[244:247], v[120:123]
	v_mfma_f32_16x16x32_bf16 v[96:99], v[136:139], v[244:247], v[96:99]
	v_mfma_f32_16x16x32_bf16 v[104:107], v[140:143], v[244:247], v[104:107]
	ds_read_b128 v[244:247], v196 offset:6144
	s_waitcnt lgkmcnt(3)
	v_mfma_f32_16x16x32_bf16 v[116:119], v[128:131], v[248:251], v[116:119]
	v_mfma_f32_16x16x32_bf16 v[124:127], v[132:135], v[248:251], v[124:127]
	v_mfma_f32_16x16x32_bf16 v[100:103], v[136:139], v[248:251], v[100:103]
	v_mfma_f32_16x16x32_bf16 v[108:111], v[140:143], v[248:251], v[108:111]
	ds_read_b128 v[248:251], v196 offset:7168
	s_waitcnt vmcnt(6)
	ds_write_b128 v235, v[168:171] offset:8192
	ds_write_b128 v235, v[172:175] offset:12288
	s_waitcnt lgkmcnt(5)
	v_mfma_f32_16x16x32_bf16 v[80:83], v[128:131], v[236:239], v[80:83]
	v_mfma_f32_16x16x32_bf16 v[88:91], v[132:135], v[236:239], v[88:91]
	v_mfma_f32_16x16x32_bf16 v[48:51], v[136:139], v[236:239], v[48:51]
	v_mfma_f32_16x16x32_bf16 v[56:59], v[140:143], v[236:239], v[56:59]
	s_waitcnt lgkmcnt(4)
	v_mfma_f32_16x16x32_bf16 v[84:87], v[128:131], v[240:243], v[84:87]
	v_mfma_f32_16x16x32_bf16 v[92:95], v[132:135], v[240:243], v[92:95]
	v_mfma_f32_16x16x32_bf16 v[52:55], v[136:139], v[240:243], v[52:55]
	v_mfma_f32_16x16x32_bf16 v[60:63], v[140:143], v[240:243], v[60:63]
	s_waitcnt lgkmcnt(2)
	v_mfma_f32_16x16x32_bf16 v[64:67], v[128:131], v[244:247], v[64:67]
	v_mfma_f32_16x16x32_bf16 v[68:71], v[128:131], v[248:251], v[68:71]
	global_load_dwordx4 v[128:131], v[198:199], off
	v_mfma_f32_16x16x32_bf16 v[72:75], v[132:135], v[244:247], v[72:75]
	v_mfma_f32_16x16x32_bf16 v[76:79], v[132:135], v[248:251], v[76:79]
	global_load_dwordx4 v[132:135], v[198:199], off offset:256
	v_mfma_f32_16x16x32_bf16 v[32:35], v[136:139], v[244:247], v[32:35]
	v_mfma_f32_16x16x32_bf16 v[36:39], v[136:139], v[248:251], v[36:39]
	global_load_dwordx4 v[136:139], v[200:201], off
	v_mfma_f32_16x16x32_bf16 v[40:43], v[140:143], v[244:247], v[40:43]
	v_mfma_f32_16x16x32_bf16 v[44:47], v[140:143], v[248:251], v[44:47]
	global_load_dwordx4 v[140:143], v[200:201], off offset:256
	s_waitcnt lgkmcnt(0)
	s_barrier
	s_add_i32 s3, s1, 3
	s_min_u32 s4, s3, 31
	s_lshl_b32 s96, s4, 13
	v_lshl_add_u64 v[174:175], v[188:189], 0, s[96:97]
	global_load_dwordx4 v[168:171], v[174:175], off offset:-2048
	global_load_dwordx4 v[172:175], v[174:175], off offset:2048
	ds_read_b128 v[236:239], v196 offset:8192
	ds_read_b128 v[240:243], v196 offset:9216
	ds_read_b128 v[244:247], v196 offset:10240
	ds_read_b128 v[248:251], v196 offset:11264
	s_lshl_b32 s96, s4, 11
	v_lshl_add_u64 v[198:199], v[184:185], 0, s[96:97]
	v_lshl_add_u64 v[200:201], v[186:187], 0, s[96:97]
	s_waitcnt vmcnt(8) lgkmcnt(3)
	v_mfma_f32_16x16x32_bf16 v[16:19], v[144:147], v[236:239], v[16:19]
	v_mfma_f32_16x16x32_bf16 v[24:27], v[148:151], v[236:239], v[24:27]
	v_mfma_f32_16x16x32_bf16 v[0:3], v[152:155], v[236:239], v[0:3]
	v_mfma_f32_16x16x32_bf16 v[8:11], v[156:159], v[236:239], v[8:11]
	ds_read_b128 v[236:239], v196 offset:12288
	s_waitcnt lgkmcnt(3)
	v_mfma_f32_16x16x32_bf16 v[20:23], v[144:147], v[240:243], v[20:23]
	v_mfma_f32_16x16x32_bf16 v[28:31], v[148:151], v[240:243], v[28:31]
	v_mfma_f32_16x16x32_bf16 v[4:7], v[152:155], v[240:243], v[4:7]
	v_mfma_f32_16x16x32_bf16 v[12:15], v[156:159], v[240:243], v[12:15]
	ds_read_b128 v[240:243], v196 offset:13312
	s_waitcnt lgkmcnt(3)
	v_mfma_f32_16x16x32_bf16 v[112:115], v[144:147], v[244:247], v[112:115]
	v_mfma_f32_16x16x32_bf16 v[120:123], v[148:151], v[244:247], v[120:123]
	v_mfma_f32_16x16x32_bf16 v[96:99], v[152:155], v[244:247], v[96:99]
	v_mfma_f32_16x16x32_bf16 v[104:107], v[156:159], v[244:247], v[104:107]
	ds_read_b128 v[244:247], v196 offset:14336
	s_waitcnt lgkmcnt(3)
	v_mfma_f32_16x16x32_bf16 v[116:119], v[144:147], v[248:251], v[116:119]
	v_mfma_f32_16x16x32_bf16 v[124:127], v[148:151], v[248:251], v[124:127]
	v_mfma_f32_16x16x32_bf16 v[100:103], v[152:155], v[248:251], v[100:103]
	v_mfma_f32_16x16x32_bf16 v[108:111], v[156:159], v[248:251], v[108:111]
	ds_read_b128 v[248:251], v196 offset:15360
	s_waitcnt vmcnt(6)
	ds_write_b128 v235, v[160:163] offset:0
	ds_write_b128 v235, v[164:167] offset:4096
	s_waitcnt lgkmcnt(5)
	v_mfma_f32_16x16x32_bf16 v[80:83], v[144:147], v[236:239], v[80:83]
	v_mfma_f32_16x16x32_bf16 v[88:91], v[148:151], v[236:239], v[88:91]
	v_mfma_f32_16x16x32_bf16 v[48:51], v[152:155], v[236:239], v[48:51]
	v_mfma_f32_16x16x32_bf16 v[56:59], v[156:159], v[236:239], v[56:59]
	s_waitcnt lgkmcnt(4)
	v_mfma_f32_16x16x32_bf16 v[84:87], v[144:147], v[240:243], v[84:87]
	v_mfma_f32_16x16x32_bf16 v[92:95], v[148:151], v[240:243], v[92:95]
	v_mfma_f32_16x16x32_bf16 v[52:55], v[152:155], v[240:243], v[52:55]
	v_mfma_f32_16x16x32_bf16 v[60:63], v[156:159], v[240:243], v[60:63]
	s_waitcnt lgkmcnt(2)
	v_mfma_f32_16x16x32_bf16 v[64:67], v[144:147], v[244:247], v[64:67]
	v_mfma_f32_16x16x32_bf16 v[68:71], v[144:147], v[248:251], v[68:71]
	global_load_dwordx4 v[144:147], v[198:199], off
	v_mfma_f32_16x16x32_bf16 v[72:75], v[148:151], v[244:247], v[72:75]
	v_mfma_f32_16x16x32_bf16 v[76:79], v[148:151], v[248:251], v[76:79]
	global_load_dwordx4 v[148:151], v[198:199], off offset:256
	v_mfma_f32_16x16x32_bf16 v[32:35], v[152:155], v[244:247], v[32:35]
	v_mfma_f32_16x16x32_bf16 v[36:39], v[152:155], v[248:251], v[36:39]
	global_load_dwordx4 v[152:155], v[200:201], off
	v_mfma_f32_16x16x32_bf16 v[40:43], v[156:159], v[244:247], v[40:43]
	v_mfma_f32_16x16x32_bf16 v[44:47], v[156:159], v[248:251], v[44:47]
	global_load_dwordx4 v[156:159], v[200:201], off offset:256
	s_add_i32 s1, s1, 2
	s_cmp_lt_u32 s1, 32
	s_waitcnt lgkmcnt(0)
	s_barrier
	s_cbranch_scc1 .Lg16_proj_k
	s_nop 7
	v_permlane16_swap_b32_e32 v16, v20
	v_permlane16_swap_b32_e32 v17, v21
	v_permlane16_swap_b32_e32 v18, v22
	v_permlane16_swap_b32_e32 v19, v23
	v_permlane16_swap_b32_e32 v24, v28
	v_permlane16_swap_b32_e32 v25, v29
	v_permlane16_swap_b32_e32 v26, v30
	v_permlane16_swap_b32_e32 v27, v31
	v_permlane16_swap_b32_e32 v112, v116
	v_permlane16_swap_b32_e32 v113, v117
	v_permlane16_swap_b32_e32 v114, v118
	v_permlane16_swap_b32_e32 v115, v119
	v_permlane16_swap_b32_e32 v120, v124
	v_permlane16_swap_b32_e32 v121, v125
	v_permlane16_swap_b32_e32 v122, v126
	v_permlane16_swap_b32_e32 v123, v127
	v_permlane16_swap_b32_e32 v80, v84
	v_permlane16_swap_b32_e32 v81, v85
	v_permlane16_swap_b32_e32 v82, v86
	v_permlane16_swap_b32_e32 v83, v87
	v_permlane16_swap_b32_e32 v88, v92
	v_permlane16_swap_b32_e32 v89, v93
	v_permlane16_swap_b32_e32 v90, v94
	v_permlane16_swap_b32_e32 v91, v95
	v_permlane16_swap_b32_e32 v64, v68
	v_permlane16_swap_b32_e32 v65, v69
	v_permlane16_swap_b32_e32 v66, v70
	v_permlane16_swap_b32_e32 v67, v71
	v_permlane16_swap_b32_e32 v72, v76
	v_permlane16_swap_b32_e32 v73, v77
	v_permlane16_swap_b32_e32 v74, v78
	v_permlane16_swap_b32_e32 v75, v79
	v_permlane16_swap_b32_e32 v0, v4
	v_permlane16_swap_b32_e32 v1, v5
	v_permlane16_swap_b32_e32 v2, v6
	v_permlane16_swap_b32_e32 v3, v7
	v_permlane16_swap_b32_e32 v8, v12
	v_permlane16_swap_b32_e32 v9, v13
	v_permlane16_swap_b32_e32 v10, v14
	v_permlane16_swap_b32_e32 v11, v15
	v_permlane16_swap_b32_e32 v96, v100
	v_permlane16_swap_b32_e32 v97, v101
	v_permlane16_swap_b32_e32 v98, v102
	v_permlane16_swap_b32_e32 v99, v103
	v_permlane16_swap_b32_e32 v104, v108
	v_permlane16_swap_b32_e32 v105, v109
	v_permlane16_swap_b32_e32 v106, v110
	v_permlane16_swap_b32_e32 v107, v111
	v_permlane16_swap_b32_e32 v48, v52
	v_permlane16_swap_b32_e32 v49, v53
	v_permlane16_swap_b32_e32 v50, v54
	v_permlane16_swap_b32_e32 v51, v55
	v_permlane16_swap_b32_e32 v56, v60
	v_permlane16_swap_b32_e32 v57, v61
	v_permlane16_swap_b32_e32 v58, v62
	v_permlane16_swap_b32_e32 v59, v63
	v_permlane16_swap_b32_e32 v32, v36
	v_permlane16_swap_b32_e32 v33, v37
	v_permlane16_swap_b32_e32 v34, v38
	v_permlane16_swap_b32_e32 v35, v39
	v_permlane16_swap_b32_e32 v40, v44
	v_permlane16_swap_b32_e32 v41, v45
	v_permlane16_swap_b32_e32 v42, v46
	v_permlane16_swap_b32_e32 v43, v47
	v_permlane32_swap_b32_e32 v16, v20
	v_permlane32_swap_b32_e32 v17, v21
	v_permlane32_swap_b32_e32 v18, v22
	v_permlane32_swap_b32_e32 v19, v23
	v_permlane32_swap_b32_e32 v24, v28
	v_permlane32_swap_b32_e32 v25, v29
	v_permlane32_swap_b32_e32 v26, v30
	v_permlane32_swap_b32_e32 v27, v31
	v_permlane32_swap_b32_e32 v112, v116
	v_permlane32_swap_b32_e32 v113, v117
	v_permlane32_swap_b32_e32 v114, v118
	v_permlane32_swap_b32_e32 v115, v119
	v_permlane32_swap_b32_e32 v120, v124
	v_permlane32_swap_b32_e32 v121, v125
	v_permlane32_swap_b32_e32 v122, v126
	v_permlane32_swap_b32_e32 v123, v127
	v_permlane32_swap_b32_e32 v80, v84
	v_permlane32_swap_b32_e32 v81, v85
	v_permlane32_swap_b32_e32 v82, v86
	v_permlane32_swap_b32_e32 v83, v87
	v_permlane32_swap_b32_e32 v88, v92
	v_permlane32_swap_b32_e32 v89, v93
	v_permlane32_swap_b32_e32 v90, v94
	v_permlane32_swap_b32_e32 v91, v95
	v_permlane32_swap_b32_e32 v64, v68
	v_permlane32_swap_b32_e32 v65, v69
	v_permlane32_swap_b32_e32 v66, v70
	v_permlane32_swap_b32_e32 v67, v71
	v_permlane32_swap_b32_e32 v72, v76
	v_permlane32_swap_b32_e32 v73, v77
	v_permlane32_swap_b32_e32 v74, v78
	v_permlane32_swap_b32_e32 v75, v79
	v_permlane32_swap_b32_e32 v0, v4
	v_permlane32_swap_b32_e32 v1, v5
	v_permlane32_swap_b32_e32 v2, v6
	v_permlane32_swap_b32_e32 v3, v7
	v_permlane32_swap_b32_e32 v8, v12
	v_permlane32_swap_b32_e32 v9, v13
	v_permlane32_swap_b32_e32 v10, v14
	v_permlane32_swap_b32_e32 v11, v15
	v_permlane32_swap_b32_e32 v96, v100
	v_permlane32_swap_b32_e32 v97, v101
	v_permlane32_swap_b32_e32 v98, v102
	v_permlane32_swap_b32_e32 v99, v103
	v_permlane32_swap_b32_e32 v104, v108
	v_permlane32_swap_b32_e32 v105, v109
	v_permlane32_swap_b32_e32 v106, v110
	v_permlane32_swap_b32_e32 v107, v111
	v_permlane32_swap_b32_e32 v48, v52
	v_permlane32_swap_b32_e32 v49, v53
	v_permlane32_swap_b32_e32 v50, v54
	v_permlane32_swap_b32_e32 v51, v55
	v_permlane32_swap_b32_e32 v56, v60
	v_permlane32_swap_b32_e32 v57, v61
	v_permlane32_swap_b32_e32 v58, v62
	v_permlane32_swap_b32_e32 v59, v63
	v_permlane32_swap_b32_e32 v32, v36
	v_permlane32_swap_b32_e32 v33, v37
	v_permlane32_swap_b32_e32 v34, v38
	v_permlane32_swap_b32_e32 v35, v39
	v_permlane32_swap_b32_e32 v40, v44
	v_permlane32_swap_b32_e32 v41, v45
	v_permlane32_swap_b32_e32 v42, v46
	v_permlane32_swap_b32_e32 v43, v47
	s_waitcnt vmcnt(0)
	s_lshl_b32 s12, s2, 8
	s_cmp_eq_u32 s0, 23
	s_mov_b64 s[2:3], -1
	s_cbranch_scc1 .LBB0_347
	s_movk_i32 s1, 0x2400
	s_waitcnt vmcnt(6)
	v_and_b32_e32 v130, 0xffffffc0, v181
	s_cmp_gt_i32 s0, 10
	v_mul_lo_u32 v129, v233, s1
	v_and_b32_e32 v128, 56, v234
	v_add_u32_e32 v131, s12, v130
	s_cselect_b64 s[2:3], -1, 0
	s_cmp_gt_u32 s0, 19
	v_mul_u32_u24_e32 v130, 0x120, v183
	s_waitcnt vmcnt(0)
	v_lshl_or_b32 v132, v128, 1, v129
	v_lshl_or_b32 v128, s0, 7, v128
	s_cselect_b64 s[0:1], -1, 0
	v_lshl_add_u32 v129, v130, 1, v129
	v_lshl_or_b32 v130, v231, 1, v129
	v_cvt_pk_bf16_f32 v112, v112, s0
	ds_write_b16 v130, v112 offset:64
	v_cvt_pk_bf16_f32 v112, v17, s0
	v_cvt_pk_bf16_f32 v96, v96, s0
	ds_write_b16 v130, v112 offset:144
	v_cvt_pk_bf16_f32 v112, v113, s0
	ds_write_b16 v130, v96 offset:4672
	v_cvt_pk_bf16_f32 v96, v1, s0
	ds_write_b16 v130, v112 offset:208
	v_cvt_pk_bf16_f32 v112, v18, s0
	ds_write_b16 v130, v96 offset:4752
	v_cvt_pk_bf16_f32 v96, v97, s0
	ds_write_b16 v130, v112 offset:288
	v_cvt_pk_bf16_f32 v112, v114, s0
	ds_write_b16 v130, v96 offset:4816
	v_cvt_pk_bf16_f32 v96, v2, s0
	ds_write_b16 v130, v112 offset:352
	v_cvt_pk_bf16_f32 v112, v19, s0
	ds_write_b16 v130, v96 offset:4896
	v_cvt_pk_bf16_f32 v96, v98, s0
	ds_write_b16 v130, v112 offset:432
	v_cvt_pk_bf16_f32 v112, v115, s0
	ds_write_b16 v130, v96 offset:4960
	v_cvt_pk_bf16_f32 v96, v3, s0
	ds_write_b16 v130, v112 offset:496
	v_cvt_pk_bf16_f32 v112, v20, s0
	ds_write_b16 v130, v96 offset:5040
	v_cvt_pk_bf16_f32 v96, v99, s0
	ds_write_b16 v130, v112 offset:1152
	v_cvt_pk_bf16_f32 v112, v116, s0
	ds_write_b16 v130, v96 offset:5104
	v_cvt_pk_bf16_f32 v96, v4, s0
	ds_write_b16 v130, v112 offset:1216
	v_cvt_pk_bf16_f32 v112, v21, s0
	ds_write_b16 v130, v96 offset:5760
	v_cvt_pk_bf16_f32 v96, v100, s0
	ds_write_b16 v130, v112 offset:1296
	v_cvt_pk_bf16_f32 v112, v117, s0
	ds_write_b16 v130, v96 offset:5824
	v_cvt_pk_bf16_f32 v96, v5, s0
	ds_write_b16 v130, v112 offset:1360
	v_cvt_pk_bf16_f32 v112, v22, s0
	ds_write_b16 v130, v96 offset:5904
	v_cvt_pk_bf16_f32 v96, v101, s0
	ds_write_b16 v130, v112 offset:1440
	v_cvt_pk_bf16_f32 v112, v118, s0
	ds_write_b16 v130, v96 offset:5968
	v_cvt_pk_bf16_f32 v96, v6, s0
	ds_write_b16 v130, v112 offset:1504
	v_cvt_pk_bf16_f32 v112, v23, s0
	ds_write_b16 v130, v96 offset:6048
	v_cvt_pk_bf16_f32 v96, v102, s0
	ds_write_b16 v130, v112 offset:1584
	v_cvt_pk_bf16_f32 v112, v119, s0
	ds_write_b16 v130, v96 offset:6112
	v_cvt_pk_bf16_f32 v96, v7, s0
	ds_write_b16 v130, v112 offset:1648
	v_cvt_pk_bf16_f32 v112, v24, s0
	ds_write_b16 v130, v96 offset:6192
	v_cvt_pk_bf16_f32 v96, v103, s0
	ds_write_b16 v130, v112 offset:2304
	v_cvt_pk_bf16_f32 v112, v120, s0
	ds_write_b16 v130, v96 offset:6256
	v_cvt_pk_bf16_f32 v96, v8, s0
	ds_write_b16 v130, v112 offset:2368
	v_cvt_pk_bf16_f32 v112, v25, s0
	ds_write_b16 v130, v96 offset:6912
	v_cvt_pk_bf16_f32 v96, v104, s0
	ds_write_b16 v130, v112 offset:2448
	v_cvt_pk_bf16_f32 v112, v121, s0
	ds_write_b16 v130, v96 offset:6976
	v_cvt_pk_bf16_f32 v96, v9, s0
	ds_write_b16 v130, v112 offset:2512
	v_cvt_pk_bf16_f32 v112, v26, s0
	ds_write_b16 v130, v96 offset:7056
	v_cvt_pk_bf16_f32 v96, v105, s0
	ds_write_b16 v130, v112 offset:2592
	v_cvt_pk_bf16_f32 v112, v122, s0
	ds_write_b16 v130, v96 offset:7120
	v_cvt_pk_bf16_f32 v96, v10, s0
	ds_write_b16 v130, v112 offset:2656
	v_cvt_pk_bf16_f32 v112, v27, s0
	ds_write_b16 v130, v96 offset:7200
	v_cvt_pk_bf16_f32 v96, v106, s0
	ds_write_b16 v130, v112 offset:2736
	v_cvt_pk_bf16_f32 v112, v123, s0
	ds_write_b16 v130, v96 offset:7264
	v_cvt_pk_bf16_f32 v96, v11, s0
	ds_write_b16 v130, v112 offset:2800
	v_cvt_pk_bf16_f32 v112, v28, s0
	ds_write_b16 v130, v96 offset:7344
	v_cvt_pk_bf16_f32 v96, v107, s0
	ds_write_b16 v130, v112 offset:3456
	v_cvt_pk_bf16_f32 v112, v124, s0
	ds_write_b16 v130, v96 offset:7408
	v_cvt_pk_bf16_f32 v96, v12, s0
	ds_write_b16 v130, v112 offset:3520
	v_cvt_pk_bf16_f32 v112, v29, s0
	ds_write_b16 v130, v96 offset:8064
	v_cvt_pk_bf16_f32 v96, v108, s0
	ds_write_b16 v130, v112 offset:3600
	v_cvt_pk_bf16_f32 v112, v125, s0
	ds_write_b16 v130, v96 offset:8128
	v_cvt_pk_bf16_f32 v96, v13, s0
	ds_write_b16 v130, v112 offset:3664
	v_cvt_pk_bf16_f32 v112, v30, s0
	ds_write_b16 v130, v96 offset:8208
	v_cvt_pk_bf16_f32 v96, v109, s0
	ds_write_b16 v130, v112 offset:3744
	v_cvt_pk_bf16_f32 v112, v126, s0
	ds_write_b16 v130, v96 offset:8272
	v_cvt_pk_bf16_f32 v96, v14, s0
	ds_write_b16 v130, v112 offset:3808
	v_cvt_pk_bf16_f32 v112, v31, s0
	ds_write_b16 v130, v96 offset:8352
	v_cvt_pk_bf16_f32 v96, v110, s0
	ds_write_b16 v130, v112 offset:3888
	v_cvt_pk_bf16_f32 v112, v127, s0
	ds_write_b16 v130, v96 offset:8416
	v_cvt_pk_bf16_f32 v96, v15, s0
	v_cvt_pk_bf16_f32 v133, v16, s0
	ds_write_b16 v130, v112 offset:3952
	v_cvt_pk_bf16_f32 v112, v0, s0
	ds_write_b16 v130, v96 offset:8496
	v_cvt_pk_bf16_f32 v96, v111, s0
	ds_write_b16 v130, v133
	ds_write_b16 v130, v112 offset:4608
	ds_write_b16 v130, v96 offset:8560
	v_lshrrev_b32_e32 v109, 3, v232
	s_waitcnt lgkmcnt(0)
	v_mad_u32_u24 v96, v109, s42, v132
	ds_read_b128 v[96:99], v96
	v_mov_b32_e32 v176, v128
	v_or_b32_e32 v110, v131, v109
	s_mov_b64 s[4:5], -1
	s_and_b64 vcc, exec, s[2:3]
	s_cbranch_vccz .LBB0_224
	s_and_b64 vcc, exec, s[0:1]
	s_cbranch_vccz .LBB0_221
	v_readlane_b32 s16, v254, 15
	v_readlane_b32 s18, v254, 17
	v_readlane_b32 s19, v254, 18
	v_readlane_b32 s17, v254, 16
	v_readlane_b32 s20, v254, 19
	v_mov_b64_e32 v[100:101], s[18:19]
	v_mad_i64_i32 v[100:101], s[4:5], v110, s89, v[100:101]
	s_movk_i32 s4, 0xec00
	v_lshl_add_u64 v[100:101], v[176:177], 1, v[100:101]
	s_mov_b32 s5, -1
	v_readlane_b32 s21, v254, 20
	v_readlane_b32 s22, v254, 21
	v_readlane_b32 s23, v254, 22
	v_readlane_b32 s24, v254, 23
	v_readlane_b32 s25, v254, 24
	v_readlane_b32 s26, v254, 25
	v_readlane_b32 s27, v254, 26
	v_readlane_b32 s28, v254, 27
	v_readlane_b32 s29, v254, 28
	v_readlane_b32 s30, v254, 29
	v_readlane_b32 s31, v254, 30
	v_lshl_add_u64 v[100:101], v[100:101], 0, s[4:5]
	s_mov_b64 s[4:5], 0

.LBB0_923:
	s_ashr_i32 s2, s4, 31
	s_lshr_b32 s2, s2, 26
	s_add_i32 s2, s4, s2
	s_ashr_i32 s3, s2, 6
	s_lshl_b32 s3, s3, 3
	s_sub_i32 s8, s25, s3
	s_min_i32 s8, s8, 8
	s_abs_i32 s9, s8
	v_cvt_f32_u32_e32 v0, s9
	s_sub_i32 s12, 0, s9
	s_andn2_b32 s2, s2, 63
	s_sub_i32 s10, s4, s2
	v_rcp_iflag_f32_e32 v0, v0
	s_abs_i32 s2, s10
	s_xor_b32 s11, s10, s8
	s_ashr_i32 s11, s11, 31
	v_mul_f32_e32 v0, 0x4f7ffffe, v0
	v_cvt_u32_f32_e32 v0, v0
	v_mov_b32_e32 v181, v179
	v_readfirstlane_b32 s13, v0
	s_mul_i32 s12, s12, s13
	s_mul_hi_u32 s12, s13, s12
	s_add_i32 s13, s13, s12
	s_mul_hi_u32 s12, s2, s13
	s_mul_i32 s13, s12, s9
	s_sub_i32 s2, s2, s13
	s_add_i32 s14, s12, 1
	s_sub_i32 s13, s2, s9
	s_cmp_ge_u32 s2, s9
	s_cselect_b32 s12, s14, s12
	s_cselect_b32 s2, s13, s2
	s_add_i32 s13, s12, 1
	s_cmp_ge_u32 s2, s9
	s_cselect_b32 s2, s13, s12
	s_xor_b32 s2, s2, s11
	s_sub_i32 s2, s2, s11
	s_mul_i32 s8, s8, s2
	s_add_i32 s3, s3, s7
	s_sub_i32 s8, s10, s8
	v_ashrrev_i32_e32 v237, 6, v181
	s_add_i32 s8, s3, s8
	v_lshlrev_b32_e32 v0, 1, v237
	v_lshl_add_u32 v0, s8, 3, v0
	v_ashrrev_i32_e32 v1, 31, v0
	v_bfe_u32 v183, v181, 5, 1
	v_lshlrev_b64 v[0:1], 16, v[0:1]
	v_and_b32_e32 v238, 31, v181
	v_lshl_add_u64 v[0:1], s[64:65], 0, v[0:1]
	v_lshlrev_b32_e32 v176, 9, v183
	s_ashr_i32 s3, s2, 31
	v_lshl_add_u64 v[0:1], v[0:1], 0, v[176:177]
	v_lshlrev_b32_e32 v176, 4, v238
	v_ashrrev_i32_e32 v40, 2, v181
	s_lshl_b64 s[10:11], s[2:3], 18
	v_lshl_add_u64 v[184:185], v[0:1], 0, v[176:177]
	s_add_u32 s10, s5, s10
	v_lshlrev_b32_e32 v0, 5, v40
	s_addc_u32 s11, s6, s11
	v_ashrrev_i32_e32 v1, 31, v0
	v_lshlrev_b32_e32 v2, 4, v181
	v_lshl_add_u64 v[0:1], v[0:1], 1, s[10:11]
	v_and_b32_e32 v176, 48, v2
	v_lshl_add_u64 v[186:187], v[0:1], 0, v[176:177]
	s_movk_i32 s3, 0x2000
	v_add_co_u32_e32 v36, vcc, s3, v186
	v_mul_u32_u24_e32 v38, 40, v238
	s_nop 0
	v_addc_co_u32_e32 v37, vcc, 0, v187, vcc
	v_lshlrev_b32_e32 v39, 4, v183
	v_lshl_add_u32 v240, v38, 1, v39
	v_add_co_u32_e32 v38, vcc, s41, v184
	s_movk_i32 s9, 0x50
	s_nop 0
	v_addc_co_u32_e32 v39, vcc, 0, v185, vcc
	v_and_b32_e32 v239, 63, v181
	v_mov_b32_e32 v176, 0x800
	v_lshl_add_u64 v[188:189], v[186:187], 0, v[176:177]
	v_bfe_u32 v247, v181, 4, 1
	v_lshlrev_b32_e32 v176, 9, v183
	v_lshl_add_u32 v176, v247, 8, v176
	v_lshl_add_u64 v[184:185], v[184:185], 0, v[176:177]
	v_lshrrev_b32_e32 v241, 2, v181
	v_bfe_u32 v247, v181, 4, 2
	v_lshlrev_b32_e32 v247, 1, v247
	v_mov_b32_e32 v176, 0x78
	v_lshrrev_b32_e32 v247, v247, v176
	v_and_b32_e32 v247, 3, v247
	v_and_b32_e32 v246, 3, v181
	v_xor_b32_e32 v247, v247, v246
	v_lshlrev_b32_e32 v247, 4, v247
	v_lshl_add_u32 v241, v241, 6, v247
	v_bfe_u32 v247, v181, 2, 2
	v_lshlrev_b32_e32 v247, 1, v247
	v_lshrrev_b32_e32 v247, v247, v176
	v_and_b32_e32 v247, 3, v247
	v_bfe_u32 v246, v181, 4, 2
	v_xor_b32_e32 v247, v247, v246
	v_lshlrev_b32_e32 v247, 4, v247
	v_and_b32_e32 v246, 15, v181
	v_lshl_add_u32 v246, v246, 6, v247
	v_mov_b32_e32 v176, s41
	v_lshl_add_u64 v[186:187], v[184:185], 0, v[176:177]
	s_mov_b32 s96, 0
	v_lshl_add_u64 v[166:167], v[188:189], 0, s[96:97]
	global_load_dwordx4 v[160:163], v[166:167], off offset:-2048
	global_load_dwordx4 v[164:167], v[166:167], off offset:2048
	v_lshl_add_u64 v[248:249], v[184:185], 0, s[96:97]
	v_lshl_add_u64 v[250:251], v[186:187], 0, s[96:97]
	global_load_dwordx4 v[128:131], v[248:249], off
	global_load_dwordx4 v[132:135], v[248:249], off offset:256
	global_load_dwordx4 v[136:139], v[250:251], off
	global_load_dwordx4 v[140:143], v[250:251], off offset:256
	s_movk_i32 s96, 0x2000
	v_lshl_add_u64 v[174:175], v[188:189], 0, s[96:97]
	global_load_dwordx4 v[168:171], v[174:175], off offset:-2048
	global_load_dwordx4 v[172:175], v[174:175], off offset:2048
	s_movk_i32 s96, 0x800
	v_lshl_add_u64 v[248:249], v[184:185], 0, s[96:97]
	v_lshl_add_u64 v[250:251], v[186:187], 0, s[96:97]
	global_load_dwordx4 v[144:147], v[248:249], off
	global_load_dwordx4 v[148:151], v[248:249], off offset:256
	global_load_dwordx4 v[152:155], v[250:251], off
	global_load_dwordx4 v[156:159], v[250:251], off offset:256
	v_mov_b32_e32 v0, 0
	v_mov_b32_e32 v1, 0
	v_mov_b32_e32 v2, 0
	v_mov_b32_e32 v3, 0
	v_mov_b32_e32 v4, 0
	v_mov_b32_e32 v5, 0
	v_mov_b32_e32 v6, 0
	v_mov_b32_e32 v7, 0
	v_mov_b32_e32 v8, 0
	v_mov_b32_e32 v9, 0
	v_mov_b32_e32 v10, 0
	v_mov_b32_e32 v11, 0
	v_mov_b32_e32 v12, 0
	v_mov_b32_e32 v13, 0
	v_mov_b32_e32 v14, 0
	v_mov_b32_e32 v15, 0
	v_mov_b32_e32 v16, 0
	v_mov_b32_e32 v17, 0
	v_mov_b32_e32 v18, 0
	v_mov_b32_e32 v19, 0
	v_mov_b32_e32 v20, 0
	v_mov_b32_e32 v21, 0
	v_mov_b32_e32 v22, 0
	v_mov_b32_e32 v23, 0
	v_mov_b32_e32 v24, 0
	v_mov_b32_e32 v25, 0
	v_mov_b32_e32 v26, 0
	v_mov_b32_e32 v27, 0
	v_mov_b32_e32 v28, 0
	v_mov_b32_e32 v29, 0
	v_mov_b32_e32 v30, 0
	v_mov_b32_e32 v31, 0
	v_mov_b32_e32 v32, 0
	v_mov_b32_e32 v33, 0
	v_mov_b32_e32 v34, 0
	v_mov_b32_e32 v35, 0
	v_mov_b32_e32 v36, 0
	v_mov_b32_e32 v37, 0
	v_mov_b32_e32 v38, 0
	v_mov_b32_e32 v39, 0
	v_mov_b32_e32 v40, 0
	v_mov_b32_e32 v41, 0
	v_mov_b32_e32 v42, 0
	v_mov_b32_e32 v43, 0
	v_mov_b32_e32 v44, 0
	v_mov_b32_e32 v45, 0
	v_mov_b32_e32 v46, 0
	v_mov_b32_e32 v47, 0
	v_mov_b32_e32 v48, 0
	v_mov_b32_e32 v49, 0
	v_mov_b32_e32 v50, 0
	v_mov_b32_e32 v51, 0
	v_mov_b32_e32 v52, 0
	v_mov_b32_e32 v53, 0
	v_mov_b32_e32 v54, 0
	v_mov_b32_e32 v55, 0
	v_mov_b32_e32 v56, 0
	v_mov_b32_e32 v57, 0
	v_mov_b32_e32 v58, 0
	v_mov_b32_e32 v59, 0
	v_mov_b32_e32 v60, 0
	v_mov_b32_e32 v61, 0
	v_mov_b32_e32 v62, 0
	v_mov_b32_e32 v63, 0
	v_mov_b32_e32 v64, 0
	v_mov_b32_e32 v65, 0
	v_mov_b32_e32 v66, 0
	v_mov_b32_e32 v67, 0
	v_mov_b32_e32 v68, 0
	v_mov_b32_e32 v69, 0
	v_mov_b32_e32 v70, 0
	v_mov_b32_e32 v71, 0
	v_mov_b32_e32 v72, 0
	v_mov_b32_e32 v73, 0
	v_mov_b32_e32 v74, 0
	v_mov_b32_e32 v75, 0
	v_mov_b32_e32 v76, 0
	v_mov_b32_e32 v77, 0
	v_mov_b32_e32 v78, 0
	v_mov_b32_e32 v79, 0
	v_mov_b32_e32 v80, 0
	v_mov_b32_e32 v81, 0
	v_mov_b32_e32 v82, 0
	v_mov_b32_e32 v83, 0
	v_mov_b32_e32 v84, 0
	v_mov_b32_e32 v85, 0
	v_mov_b32_e32 v86, 0
	v_mov_b32_e32 v87, 0
	v_mov_b32_e32 v88, 0
	v_mov_b32_e32 v89, 0
	v_mov_b32_e32 v90, 0
	v_mov_b32_e32 v91, 0
	v_mov_b32_e32 v92, 0
	v_mov_b32_e32 v93, 0
	v_mov_b32_e32 v94, 0
	v_mov_b32_e32 v95, 0
	v_mov_b32_e32 v96, 0
	v_mov_b32_e32 v97, 0
	v_mov_b32_e32 v98, 0
	v_mov_b32_e32 v99, 0
	v_mov_b32_e32 v100, 0
	v_mov_b32_e32 v101, 0
	v_mov_b32_e32 v102, 0
	v_mov_b32_e32 v103, 0
	v_mov_b32_e32 v104, 0
	v_mov_b32_e32 v105, 0
	v_mov_b32_e32 v106, 0
	v_mov_b32_e32 v107, 0
	v_mov_b32_e32 v108, 0
	v_mov_b32_e32 v109, 0
	v_mov_b32_e32 v110, 0
	v_mov_b32_e32 v111, 0
	v_mov_b32_e32 v112, 0
	v_mov_b32_e32 v113, 0
	v_mov_b32_e32 v114, 0
	v_mov_b32_e32 v115, 0
	v_mov_b32_e32 v116, 0
	v_mov_b32_e32 v117, 0
	v_mov_b32_e32 v118, 0
	v_mov_b32_e32 v119, 0
	v_mov_b32_e32 v120, 0
	v_mov_b32_e32 v121, 0
	v_mov_b32_e32 v122, 0
	v_mov_b32_e32 v123, 0
	v_mov_b32_e32 v124, 0
	v_mov_b32_e32 v125, 0
	v_mov_b32_e32 v126, 0
	v_mov_b32_e32 v127, 0
	s_mov_b32 s3, 0
	s_waitcnt vmcnt(10)
	ds_write_b128 v241, v[160:163]
	ds_write_b128 v241, v[164:167] offset:4096
	s_waitcnt lgkmcnt(0)
	s_barrier
.Lg16_out_k:
	s_add_i32 s9, s3, 2
	s_min_u32 s10, s9, 30
	s_lshl_b32 s96, s10, 13
	v_lshl_add_u64 v[166:167], v[188:189], 0, s[96:97]
	global_load_dwordx4 v[160:163], v[166:167], off offset:-2048
	global_load_dwordx4 v[164:167], v[166:167], off offset:2048
	ds_read_b128 v[196:199], v246 offset:0
	ds_read_b128 v[200:203], v246 offset:1024
	ds_read_b128 v[204:207], v246 offset:2048
	ds_read_b128 v[242:245], v246 offset:3072
	s_lshl_b32 s96, s10, 11
	v_lshl_add_u64 v[248:249], v[184:185], 0, s[96:97]
	v_lshl_add_u64 v[250:251], v[186:187], 0, s[96:97]
	s_waitcnt vmcnt(8) lgkmcnt(3)
	v_mfma_f32_16x16x32_bf16 v[112:115], v[128:131], v[196:199], v[112:115]
	v_mfma_f32_16x16x32_bf16 v[120:123], v[132:135], v[196:199], v[120:123]
	v_mfma_f32_16x16x32_bf16 v[48:51], v[136:139], v[196:199], v[48:51]
	v_mfma_f32_16x16x32_bf16 v[56:59], v[140:143], v[196:199], v[56:59]
	ds_read_b128 v[196:199], v246 offset:4096
	s_waitcnt lgkmcnt(3)
	v_mfma_f32_16x16x32_bf16 v[116:119], v[128:131], v[200:203], v[116:119]
	v_mfma_f32_16x16x32_bf16 v[124:127], v[132:135], v[200:203], v[124:127]
	v_mfma_f32_16x16x32_bf16 v[52:55], v[136:139], v[200:203], v[52:55]
	v_mfma_f32_16x16x32_bf16 v[60:63], v[140:143], v[200:203], v[60:63]
	ds_read_b128 v[200:203], v246 offset:5120
	s_waitcnt lgkmcnt(3)
	v_mfma_f32_16x16x32_bf16 v[96:99], v[128:131], v[204:207], v[96:99]
	v_mfma_f32_16x16x32_bf16 v[104:107], v[132:135], v[204:207], v[104:107]
	v_mfma_f32_16x16x32_bf16 v[32:35], v[136:139], v[204:207], v[32:35]
	v_mfma_f32_16x16x32_bf16 v[40:43], v[140:143], v[204:207], v[40:43]
	ds_read_b128 v[204:207], v246 offset:6144
	s_waitcnt lgkmcnt(3)
	v_mfma_f32_16x16x32_bf16 v[100:103], v[128:131], v[242:245], v[100:103]
	v_mfma_f32_16x16x32_bf16 v[108:111], v[132:135], v[242:245], v[108:111]
	v_mfma_f32_16x16x32_bf16 v[36:39], v[136:139], v[242:245], v[36:39]
	v_mfma_f32_16x16x32_bf16 v[44:47], v[140:143], v[242:245], v[44:47]
	ds_read_b128 v[242:245], v246 offset:7168
	s_waitcnt vmcnt(6)
	ds_write_b128 v241, v[168:171] offset:8192
	ds_write_b128 v241, v[172:175] offset:12288
	s_waitcnt lgkmcnt(5)
	v_mfma_f32_16x16x32_bf16 v[80:83], v[128:131], v[196:199], v[80:83]
	v_mfma_f32_16x16x32_bf16 v[88:91], v[132:135], v[196:199], v[88:91]
	v_mfma_f32_16x16x32_bf16 v[16:19], v[136:139], v[196:199], v[16:19]
	v_mfma_f32_16x16x32_bf16 v[24:27], v[140:143], v[196:199], v[24:27]
	s_waitcnt lgkmcnt(4)
	v_mfma_f32_16x16x32_bf16 v[84:87], v[128:131], v[200:203], v[84:87]
	v_mfma_f32_16x16x32_bf16 v[92:95], v[132:135], v[200:203], v[92:95]
	v_mfma_f32_16x16x32_bf16 v[20:23], v[136:139], v[200:203], v[20:23]
	v_mfma_f32_16x16x32_bf16 v[28:31], v[140:143], v[200:203], v[28:31]
	s_waitcnt lgkmcnt(2)
	v_mfma_f32_16x16x32_bf16 v[64:67], v[128:131], v[204:207], v[64:67]
	v_mfma_f32_16x16x32_bf16 v[68:71], v[128:131], v[242:245], v[68:71]
	global_load_dwordx4 v[128:131], v[248:249], off
	v_mfma_f32_16x16x32_bf16 v[72:75], v[132:135], v[204:207], v[72:75]
	v_mfma_f32_16x16x32_bf16 v[76:79], v[132:135], v[242:245], v[76:79]
	global_load_dwordx4 v[132:135], v[248:249], off offset:256
	v_mfma_f32_16x16x32_bf16 v[0:3], v[136:139], v[204:207], v[0:3]
	v_mfma_f32_16x16x32_bf16 v[4:7], v[136:139], v[242:245], v[4:7]
	global_load_dwordx4 v[136:139], v[250:251], off
	v_mfma_f32_16x16x32_bf16 v[8:11], v[140:143], v[204:207], v[8:11]
	v_mfma_f32_16x16x32_bf16 v[12:15], v[140:143], v[242:245], v[12:15]
	global_load_dwordx4 v[140:143], v[250:251], off offset:256
	s_waitcnt lgkmcnt(0)
	s_barrier
	s_add_i32 s9, s3, 3
	s_min_u32 s10, s9, 31
	s_lshl_b32 s96, s10, 13
	v_lshl_add_u64 v[174:175], v[188:189], 0, s[96:97]
	global_load_dwordx4 v[168:171], v[174:175], off offset:-2048
	global_load_dwordx4 v[172:175], v[174:175], off offset:2048
	ds_read_b128 v[196:199], v246 offset:8192
	ds_read_b128 v[200:203], v246 offset:9216
	ds_read_b128 v[204:207], v246 offset:10240
	ds_read_b128 v[242:245], v246 offset:11264
	s_lshl_b32 s96, s10, 11
	v_lshl_add_u64 v[248:249], v[184:185], 0, s[96:97]
	v_lshl_add_u64 v[250:251], v[186:187], 0, s[96:97]
	s_waitcnt vmcnt(8) lgkmcnt(3)
	v_mfma_f32_16x16x32_bf16 v[112:115], v[144:147], v[196:199], v[112:115]
	v_mfma_f32_16x16x32_bf16 v[120:123], v[148:151], v[196:199], v[120:123]
	v_mfma_f32_16x16x32_bf16 v[48:51], v[152:155], v[196:199], v[48:51]
	v_mfma_f32_16x16x32_bf16 v[56:59], v[156:159], v[196:199], v[56:59]
	ds_read_b128 v[196:199], v246 offset:12288
	s_waitcnt lgkmcnt(3)
	v_mfma_f32_16x16x32_bf16 v[116:119], v[144:147], v[200:203], v[116:119]
	v_mfma_f32_16x16x32_bf16 v[124:127], v[148:151], v[200:203], v[124:127]
	v_mfma_f32_16x16x32_bf16 v[52:55], v[152:155], v[200:203], v[52:55]
	v_mfma_f32_16x16x32_bf16 v[60:63], v[156:159], v[200:203], v[60:63]
	ds_read_b128 v[200:203], v246 offset:13312
	s_waitcnt lgkmcnt(3)
	v_mfma_f32_16x16x32_bf16 v[96:99], v[144:147], v[204:207], v[96:99]
	v_mfma_f32_16x16x32_bf16 v[104:107], v[148:151], v[204:207], v[104:107]
	v_mfma_f32_16x16x32_bf16 v[32:35], v[152:155], v[204:207], v[32:35]
	v_mfma_f32_16x16x32_bf16 v[40:43], v[156:159], v[204:207], v[40:43]
	ds_read_b128 v[204:207], v246 offset:14336
	s_waitcnt lgkmcnt(3)
	v_mfma_f32_16x16x32_bf16 v[100:103], v[144:147], v[242:245], v[100:103]
	v_mfma_f32_16x16x32_bf16 v[108:111], v[148:151], v[242:245], v[108:111]
	v_mfma_f32_16x16x32_bf16 v[36:39], v[152:155], v[242:245], v[36:39]
	v_mfma_f32_16x16x32_bf16 v[44:47], v[156:159], v[242:245], v[44:47]
	ds_read_b128 v[242:245], v246 offset:15360
	s_waitcnt vmcnt(6)
	ds_write_b128 v241, v[160:163] offset:0
	ds_write_b128 v241, v[164:167] offset:4096
	s_waitcnt lgkmcnt(5)
	v_mfma_f32_16x16x32_bf16 v[80:83], v[144:147], v[196:199], v[80:83]
	v_mfma_f32_16x16x32_bf16 v[88:91], v[148:151], v[196:199], v[88:91]
	v_mfma_f32_16x16x32_bf16 v[16:19], v[152:155], v[196:199], v[16:19]
	v_mfma_f32_16x16x32_bf16 v[24:27], v[156:159], v[196:199], v[24:27]
	s_waitcnt lgkmcnt(4)
	v_mfma_f32_16x16x32_bf16 v[84:87], v[144:147], v[200:203], v[84:87]
	v_mfma_f32_16x16x32_bf16 v[92:95], v[148:151], v[200:203], v[92:95]
	v_mfma_f32_16x16x32_bf16 v[20:23], v[152:155], v[200:203], v[20:23]
	v_mfma_f32_16x16x32_bf16 v[28:31], v[156:159], v[200:203], v[28:31]
	s_waitcnt lgkmcnt(2)
	v_mfma_f32_16x16x32_bf16 v[64:67], v[144:147], v[204:207], v[64:67]
	v_mfma_f32_16x16x32_bf16 v[68:71], v[144:147], v[242:245], v[68:71]
	global_load_dwordx4 v[144:147], v[248:249], off
	v_mfma_f32_16x16x32_bf16 v[72:75], v[148:151], v[204:207], v[72:75]
	v_mfma_f32_16x16x32_bf16 v[76:79], v[148:151], v[242:245], v[76:79]
	global_load_dwordx4 v[148:151], v[248:249], off offset:256
	v_mfma_f32_16x16x32_bf16 v[0:3], v[152:155], v[204:207], v[0:3]
	v_mfma_f32_16x16x32_bf16 v[4:7], v[152:155], v[242:245], v[4:7]
	global_load_dwordx4 v[152:155], v[250:251], off
	v_mfma_f32_16x16x32_bf16 v[8:11], v[156:159], v[204:207], v[8:11]
	v_mfma_f32_16x16x32_bf16 v[12:15], v[156:159], v[242:245], v[12:15]
	global_load_dwordx4 v[156:159], v[250:251], off offset:256
	s_add_i32 s3, s3, 2
	s_cmp_lt_u32 s3, 32
	s_waitcnt lgkmcnt(0)
	s_barrier
	s_cbranch_scc1 .Lg16_out_k
	s_nop 7
	v_permlane16_swap_b32_e32 v112, v116
	v_permlane16_swap_b32_e32 v113, v117
	v_permlane16_swap_b32_e32 v114, v118
	v_permlane16_swap_b32_e32 v115, v119
	v_permlane16_swap_b32_e32 v120, v124
	v_permlane16_swap_b32_e32 v121, v125
	v_permlane16_swap_b32_e32 v122, v126
	v_permlane16_swap_b32_e32 v123, v127
	v_permlane16_swap_b32_e32 v96, v100
	v_permlane16_swap_b32_e32 v97, v101
	v_permlane16_swap_b32_e32 v98, v102
	v_permlane16_swap_b32_e32 v99, v103
	v_permlane16_swap_b32_e32 v104, v108
	v_permlane16_swap_b32_e32 v105, v109
	v_permlane16_swap_b32_e32 v106, v110
	v_permlane16_swap_b32_e32 v107, v111
	v_permlane16_swap_b32_e32 v80, v84
	v_permlane16_swap_b32_e32 v81, v85
	v_permlane16_swap_b32_e32 v82, v86
	v_permlane16_swap_b32_e32 v83, v87
	v_permlane16_swap_b32_e32 v88, v92
	v_permlane16_swap_b32_e32 v89, v93
	v_permlane16_swap_b32_e32 v90, v94
	v_permlane16_swap_b32_e32 v91, v95
	v_permlane16_swap_b32_e32 v64, v68
	v_permlane16_swap_b32_e32 v65, v69
	v_permlane16_swap_b32_e32 v66, v70
	v_permlane16_swap_b32_e32 v67, v71
	v_permlane16_swap_b32_e32 v72, v76
	v_permlane16_swap_b32_e32 v73, v77
	v_permlane16_swap_b32_e32 v74, v78
	v_permlane16_swap_b32_e32 v75, v79
	v_permlane16_swap_b32_e32 v48, v52
	v_permlane16_swap_b32_e32 v49, v53
	v_permlane16_swap_b32_e32 v50, v54
	v_permlane16_swap_b32_e32 v51, v55
	v_permlane16_swap_b32_e32 v56, v60
	v_permlane16_swap_b32_e32 v57, v61
	v_permlane16_swap_b32_e32 v58, v62
	v_permlane16_swap_b32_e32 v59, v63
	v_permlane16_swap_b32_e32 v32, v36
	v_permlane16_swap_b32_e32 v33, v37
	v_permlane16_swap_b32_e32 v34, v38
	v_permlane16_swap_b32_e32 v35, v39
	v_permlane16_swap_b32_e32 v40, v44
	v_permlane16_swap_b32_e32 v41, v45
	v_permlane16_swap_b32_e32 v42, v46
	v_permlane16_swap_b32_e32 v43, v47
	v_permlane16_swap_b32_e32 v16, v20
	v_permlane16_swap_b32_e32 v17, v21
	v_permlane16_swap_b32_e32 v18, v22
	v_permlane16_swap_b32_e32 v19, v23
	v_permlane16_swap_b32_e32 v24, v28
	v_permlane16_swap_b32_e32 v25, v29
	v_permlane16_swap_b32_e32 v26, v30
	v_permlane16_swap_b32_e32 v27, v31
	v_permlane16_swap_b32_e32 v0, v4
	v_permlane16_swap_b32_e32 v1, v5
	v_permlane16_swap_b32_e32 v2, v6
	v_permlane16_swap_b32_e32 v3, v7
	v_permlane16_swap_b32_e32 v8, v12
	v_permlane16_swap_b32_e32 v9, v13
	v_permlane16_swap_b32_e32 v10, v14
	v_permlane16_swap_b32_e32 v11, v15
	v_permlane32_swap_b32_e32 v112, v116
	v_permlane32_swap_b32_e32 v113, v117
	v_permlane32_swap_b32_e32 v114, v118
	v_permlane32_swap_b32_e32 v115, v119
	v_permlane32_swap_b32_e32 v120, v124
	v_permlane32_swap_b32_e32 v121, v125
	v_permlane32_swap_b32_e32 v122, v126
	v_permlane32_swap_b32_e32 v123, v127
	v_permlane32_swap_b32_e32 v96, v100
	v_permlane32_swap_b32_e32 v97, v101
	v_permlane32_swap_b32_e32 v98, v102
	v_permlane32_swap_b32_e32 v99, v103
	v_permlane32_swap_b32_e32 v104, v108
	v_permlane32_swap_b32_e32 v105, v109
	v_permlane32_swap_b32_e32 v106, v110
	v_permlane32_swap_b32_e32 v107, v111
	v_permlane32_swap_b32_e32 v80, v84
	v_permlane32_swap_b32_e32 v81, v85
	v_permlane32_swap_b32_e32 v82, v86
	v_permlane32_swap_b32_e32 v83, v87
	v_permlane32_swap_b32_e32 v88, v92
	v_permlane32_swap_b32_e32 v89, v93
	v_permlane32_swap_b32_e32 v90, v94
	v_permlane32_swap_b32_e32 v91, v95
	v_permlane32_swap_b32_e32 v64, v68
	v_permlane32_swap_b32_e32 v65, v69
	v_permlane32_swap_b32_e32 v66, v70
	v_permlane32_swap_b32_e32 v67, v71
	v_permlane32_swap_b32_e32 v72, v76
	v_permlane32_swap_b32_e32 v73, v77
	v_permlane32_swap_b32_e32 v74, v78
	v_permlane32_swap_b32_e32 v75, v79
	v_permlane32_swap_b32_e32 v48, v52
	v_permlane32_swap_b32_e32 v49, v53
	v_permlane32_swap_b32_e32 v50, v54
	v_permlane32_swap_b32_e32 v51, v55
	v_permlane32_swap_b32_e32 v56, v60
	v_permlane32_swap_b32_e32 v57, v61
	v_permlane32_swap_b32_e32 v58, v62
	v_permlane32_swap_b32_e32 v59, v63
	v_permlane32_swap_b32_e32 v32, v36
	v_permlane32_swap_b32_e32 v33, v37
	v_permlane32_swap_b32_e32 v34, v38
	v_permlane32_swap_b32_e32 v35, v39
	v_permlane32_swap_b32_e32 v40, v44
	v_permlane32_swap_b32_e32 v41, v45
	v_permlane32_swap_b32_e32 v42, v46
	v_permlane32_swap_b32_e32 v43, v47
	v_permlane32_swap_b32_e32 v16, v20
	v_permlane32_swap_b32_e32 v17, v21
	v_permlane32_swap_b32_e32 v18, v22
	v_permlane32_swap_b32_e32 v19, v23
	v_permlane32_swap_b32_e32 v24, v28
	v_permlane32_swap_b32_e32 v25, v29
	v_permlane32_swap_b32_e32 v26, v30
	v_permlane32_swap_b32_e32 v27, v31
	v_permlane32_swap_b32_e32 v0, v4
	v_permlane32_swap_b32_e32 v1, v5
	v_permlane32_swap_b32_e32 v2, v6
	v_permlane32_swap_b32_e32 v3, v7
	v_permlane32_swap_b32_e32 v8, v12
	v_permlane32_swap_b32_e32 v9, v13
	v_permlane32_swap_b32_e32 v10, v14
	v_permlane32_swap_b32_e32 v11, v15
	s_waitcnt vmcnt(0)
	s_movk_i32 s3, 0x2400
	s_waitcnt vmcnt(6)
	v_lshlrev_b32_e32 v128, 2, v181
	s_waitcnt vmcnt(0)
	v_and_b32_e32 v133, 0xffffffc0, v181
	v_mul_lo_u32 v129, v237, s3
	v_lshlrev_b32_e32 v130, 2, v238
	v_and_b32_e32 v128, 60, v128
	v_lshl_add_u32 v176, s8, 8, v133
	v_mul_u32_u24_e32 v133, 0x110, v183
	v_or_b32_e32 v131, v129, v130
	v_lshl_or_b32 v132, v128, 2, v129
	v_lshl_or_b32 v128, s2, 7, v128
	v_lshlrev_b32_e32 v133, 2, v133
	v_lshrrev_b32_e32 v175, 4, v239
	s_movk_i32 s2, 0x110
	v_add_u32_e32 v147, v131, v133
	v_add3_u32 v148, v129, v133, v130
	v_mad_u32_u24 v146, v175, s2, v132
	v_readlane_b32 s2, v254, 39
	v_readlane_b32 s8, v253, 36
	v_add_u32_e32 v149, 0x800, v147
	v_add_u32_e32 v150, 0x800, v148
	v_add_u32_e32 v151, 0xa00, v148
	v_mov_b32_e32 v160, s2
	v_readlane_b32 s2, v254, 37
	v_readlane_b32 s9, v253, 37
	v_readlane_b32 s10, v253, 38
	v_readlane_b32 s11, v253, 39
	v_readlane_b32 s12, v253, 40
	v_readlane_b32 s13, v253, 41
	v_readlane_b32 s14, v253, 42
	v_readlane_b32 s15, v253, 43
	v_readlane_b32 s16, v253, 44
	v_readlane_b32 s17, v253, 45
	ds_write2_b32 v147, v112, v113 offset1:68
	ds_write2_b32 v148, v96, v97 offset0:32 offset1:100
	ds_write2_b32 v147, v114, v115 offset0:136 offset1:204
	ds_write2_b32 v148, v98, v99 offset0:168 offset1:236
	ds_write2_b32 v149, v116, v117 offset0:32 offset1:100
	ds_write2_b32 v150, v100, v101 offset0:64 offset1:132
	ds_write2_b32 v149, v118, v119 offset0:168 offset1:236
	ds_write2_b32 v151, v102, v103 offset0:72 offset1:140
	v_or_b32_e32 v102, v176, v175
	v_mov_b32_e32 v161, s2
	v_readlane_b32 s2, v254, 40
	v_readlane_b32 s18, v253, 46
	v_readlane_b32 s19, v253, 47
	v_readlane_b32 s20, v253, 48
	v_readlane_b32 s21, v253, 49
	v_readlane_b32 s22, v253, 50
	v_readlane_b32 s23, v253, 51
	s_mov_b64 s[8:9], s[16:17]
	v_cmp_gt_i32_e32 vcc, s39, v102
	v_add_u32_e32 v96, 0xffff8000, v102
	v_ashrrev_i32_e32 v97, 31, v102
	v_mov_b32_e32 v162, s2
	v_readlane_b32 s2, v254, 38
	s_mov_b64 s[10:11], s[18:19]
	v_cndmask_b32_e32 v97, 0, v97, vcc
	v_cndmask_b32_e32 v96, v96, v102, vcc
	v_mov_b32_e32 v163, s2
	v_mov_b32_e32 v164, s63
	v_mov_b32_e32 v165, s11
	v_mov_b32_e32 v166, s62
	v_mov_b32_e32 v167, s10
	v_min_i32_e32 v102, 0x8000, v102
	v_add_u32_e32 v152, 0x1000, v147
	v_add_u32_e32 v153, 0x1000, v148
	v_add_u32_e32 v154, 0x1200, v147
	v_add_u32_e32 v155, 0x1200, v148
	v_add_u32_e32 v156, 0x1800, v147
	v_add_u32_e32 v157, 0x1800, v148
	v_add_u32_e32 v158, 0x1a00, v147
	v_add_u32_e32 v159, 0x1c00, v148
	v_ashrrev_i32_e32 v129, 31, v128
	v_cndmask_b32_e32 v99, v160, v161, vcc
	v_cndmask_b32_e32 v98, v162, v163, vcc
	v_lshlrev_b64 v[96:97], 12, v[96:97]
	v_cndmask_b32_e32 v101, v164, v165, vcc
	v_cndmask_b32_e32 v100, v166, v167, vcc
	v_ashrrev_i32_e32 v102, 12, v102
	ds_write2_b32 v152, v120, v121 offset0:64 offset1:132
	ds_write2_b32 v153, v104, v105 offset0:96 offset1:164
	ds_write2_b32 v154, v122, v123 offset0:72 offset1:140
	ds_write2_b32 v155, v106, v107 offset0:104 offset1:172
	ds_write2_b32 v156, v124, v125 offset0:96 offset1:164
	ds_write2_b32 v157, v108, v109 offset0:128 offset1:196
	ds_write2_b32 v158, v126, v127 offset0:104 offset1:172
	ds_write2_b32 v159, v110, v111 offset0:8 offset1:76
	v_lshl_add_u64 v[98:99], v[98:99], 0, v[96:97]
	v_lshl_add_u64 v[100:101], v[100:101], 0, v[96:97]
	v_lshlrev_b64 v[96:97], 2, v[128:129]
	v_mul_hi_i32_i24_e32 v103, 0x6000, v102
	v_mul_i32_i24_e32 v102, 0x6000, v102
	s_waitcnt lgkmcnt(0)
	v_lshl_add_u64 v[98:99], v[98:99], 0, v[96:97]
	v_lshl_add_u64 v[102:103], s[0:1], 0, v[102:103]
	v_lshl_add_u64 v[102:103], v[102:103], 0, v[96:97]
	ds_read_b128 v[104:107], v146
	global_load_dwordx4 v[108:111], v[98:99], off
	global_load_dwordx4 v[112:115], v[102:103], off
	v_or_b32_e32 v168, 4, v175
	v_lshl_add_u64 v[100:101], v[100:101], 0, v[96:97]
	v_or_b32_e32 v169, 8, v175
	v_or_b32_e32 v170, 12, v175
	v_or_b32_e32 v171, 16, v175
	v_or_b32_e32 v172, 20, v175
	v_or_b32_e32 v173, 24, v175
	v_or_b32_e32 v174, 28, v175
	v_or_b32_e32 v181, v176, v174
	v_readlane_b32 s2, v254, 11
	s_add_i32 s4, s4, s2
	s_cmp_lt_i32 s4, s26
	s_mov_b64 s[12:13], s[20:21]
	s_mov_b64 s[14:15], s[22:23]
	s_waitcnt vmcnt(0) lgkmcnt(0)
	v_pk_fma_f32 v[104:105], v[104:105], v[112:113], v[108:109]
	v_pk_fma_f32 v[106:107], v[106:107], v[114:115], v[110:111]
	v_or_b32_e32 v110, v176, v168
	global_store_dwordx4 v[100:101], v[104:107], off
	v_cmp_gt_i32_e32 vcc, s39, v110
	s_nop 0
	v_ashrrev_i32_e32 v104, 31, v110
	v_add_u32_e32 v106, 0xffff8000, v110
	v_cndmask_b32_e32 v105, 0, v104, vcc
	v_cndmask_b32_e32 v104, v106, v110, vcc
	v_cndmask_b32_e32 v107, v160, v161, vcc
	v_cndmask_b32_e32 v106, v162, v163, vcc
	v_lshlrev_b64 v[104:105], 12, v[104:105]
	v_cndmask_b32_e32 v109, v164, v165, vcc
	v_cndmask_b32_e32 v108, v166, v167, vcc
	v_lshl_add_u64 v[106:107], v[106:107], 0, v[104:105]
	v_lshl_add_u64 v[104:105], v[108:109], 0, v[104:105]
	v_min_i32_e32 v108, 0x8000, v110
	v_ashrrev_i32_e32 v108, 12, v108
	v_mul_hi_i32_i24_e32 v109, 0x6000, v108
	v_mul_i32_i24_e32 v108, 0x6000, v108
	v_lshl_add_u64 v[106:107], v[106:107], 0, v[96:97]
	v_lshl_add_u64 v[108:109], s[0:1], 0, v[108:109]
	v_lshl_add_u64 v[108:109], v[108:109], 0, v[96:97]
	ds_read_b128 v[110:113], v146 offset:1088
	global_load_dwordx4 v[114:117], v[106:107], off
	global_load_dwordx4 v[118:121], v[108:109], off
	v_lshl_add_u64 v[104:105], v[104:105], 0, v[96:97]
	s_waitcnt vmcnt(0) lgkmcnt(0)
	v_pk_fma_f32 v[110:111], v[110:111], v[118:119], v[114:115]
	v_pk_fma_f32 v[112:113], v[112:113], v[120:121], v[116:117]
	v_or_b32_e32 v118, v176, v169
	global_store_dwordx4 v[104:105], v[110:113], off
	v_cmp_gt_i32_e32 vcc, s39, v118
	s_nop 0
	v_ashrrev_i32_e32 v110, 31, v118
	v_add_u32_e32 v112, 0xffff8000, v118
	v_cndmask_b32_e32 v111, 0, v110, vcc
	v_cndmask_b32_e32 v110, v112, v118, vcc
	v_cndmask_b32_e32 v113, v160, v161, vcc
	v_cndmask_b32_e32 v112, v162, v163, vcc
	v_lshlrev_b64 v[110:111], 12, v[110:111]
	v_lshl_add_u64 v[112:113], v[112:113], 0, v[110:111]
	v_cndmask_b32_e32 v115, v164, v165, vcc
	v_cndmask_b32_e32 v114, v166, v167, vcc
	v_lshl_add_u64 v[116:117], v[114:115], 0, v[110:111]
	v_lshl_add_u64 v[110:111], v[112:113], 0, v[96:97]
	v_min_i32_e32 v112, 0x8000, v118
	v_ashrrev_i32_e32 v112, 12, v112
	v_mul_hi_i32_i24_e32 v113, 0x6000, v112
	v_mul_i32_i24_e32 v112, 0x6000, v112
	v_lshl_add_u64 v[112:113], s[0:1], 0, v[112:113]
	v_lshl_add_u64 v[114:115], v[112:113], 0, v[96:97]
	v_lshl_add_u64 v[112:113], v[116:117], 0, v[96:97]
	ds_read_b128 v[116:119], v146 offset:2176
	global_load_dwordx4 v[120:123], v[110:111], off
	global_load_dwordx4 v[124:127], v[114:115], off
	s_waitcnt vmcnt(0) lgkmcnt(0)
	v_pk_fma_f32 v[116:117], v[116:117], v[124:125], v[120:121]
	v_pk_fma_f32 v[118:119], v[118:119], v[126:127], v[122:123]
	v_or_b32_e32 v124, v176, v170
	global_store_dwordx4 v[112:113], v[116:119], off
	v_cmp_gt_i32_e32 vcc, s39, v124
	s_nop 0
	v_ashrrev_i32_e32 v116, 31, v124
	v_add_u32_e32 v118, 0xffff8000, v124
	v_cndmask_b32_e32 v117, 0, v116, vcc
	v_cndmask_b32_e32 v116, v118, v124, vcc
	v_cndmask_b32_e32 v119, v160, v161, vcc
	v_cndmask_b32_e32 v118, v162, v163, vcc
	v_lshlrev_b64 v[116:117], 12, v[116:117]
	v_lshl_add_u64 v[118:119], v[118:119], 0, v[116:117]
	v_cndmask_b32_e32 v121, v164, v165, vcc
	v_cndmask_b32_e32 v120, v166, v167, vcc
	v_lshl_add_u64 v[122:123], v[120:121], 0, v[116:117]
	v_lshl_add_u64 v[116:117], v[118:119], 0, v[96:97]
	v_min_i32_e32 v118, 0x8000, v124
	v_ashrrev_i32_e32 v118, 12, v118
	v_mul_hi_i32_i24_e32 v119, 0x6000, v118
	v_mul_i32_i24_e32 v118, 0x6000, v118
	v_lshl_add_u64 v[118:119], s[0:1], 0, v[118:119]
	v_lshl_add_u64 v[120:121], v[118:119], 0, v[96:97]
	v_lshl_add_u64 v[118:119], v[122:123], 0, v[96:97]
	ds_read_b128 v[122:125], v146 offset:3264
	global_load_dwordx4 v[126:129], v[116:117], off
	global_load_dwordx4 v[130:133], v[120:121], off
	s_waitcnt vmcnt(0) lgkmcnt(0)
	v_pk_fma_f32 v[122:123], v[122:123], v[130:131], v[126:127]
	v_pk_fma_f32 v[124:125], v[124:125], v[132:133], v[128:129]
	v_or_b32_e32 v130, v176, v171
	global_store_dwordx4 v[118:119], v[122:125], off
	v_cmp_gt_i32_e32 vcc, s39, v130
	s_nop 0
	v_ashrrev_i32_e32 v122, 31, v130
	v_add_u32_e32 v124, 0xffff8000, v130
	v_cndmask_b32_e32 v123, 0, v122, vcc
	v_cndmask_b32_e32 v122, v124, v130, vcc
	v_cndmask_b32_e32 v125, v160, v161, vcc
	v_cndmask_b32_e32 v124, v162, v163, vcc
	v_lshlrev_b64 v[122:123], 12, v[122:123]
	v_lshl_add_u64 v[124:125], v[124:125], 0, v[122:123]
	v_cndmask_b32_e32 v127, v164, v165, vcc
	v_cndmask_b32_e32 v126, v166, v167, vcc
	v_lshl_add_u64 v[128:129], v[126:127], 0, v[122:123]
	v_lshl_add_u64 v[122:123], v[124:125], 0, v[96:97]
	v_min_i32_e32 v124, 0x8000, v130
	v_ashrrev_i32_e32 v124, 12, v124
	v_mul_hi_i32_i24_e32 v125, 0x6000, v124
	v_mul_i32_i24_e32 v124, 0x6000, v124
	v_lshl_add_u64 v[124:125], s[0:1], 0, v[124:125]
	v_lshl_add_u64 v[126:127], v[124:125], 0, v[96:97]
	v_lshl_add_u64 v[124:125], v[128:129], 0, v[96:97]
	ds_read_b128 v[128:131], v146 offset:4352
	global_load_dwordx4 v[132:135], v[122:123], off
	global_load_dwordx4 v[136:139], v[126:127], off
	s_waitcnt vmcnt(0) lgkmcnt(0)
	v_pk_fma_f32 v[128:129], v[128:129], v[136:137], v[132:133]
	v_pk_fma_f32 v[130:131], v[130:131], v[138:139], v[134:135]
	v_or_b32_e32 v136, v176, v172
	global_store_dwordx4 v[124:125], v[128:131], off
	v_cmp_gt_i32_e32 vcc, s39, v136
	s_nop 0
	v_ashrrev_i32_e32 v128, 31, v136
	v_add_u32_e32 v130, 0xffff8000, v136
	v_cndmask_b32_e32 v129, 0, v128, vcc
	v_cndmask_b32_e32 v128, v130, v136, vcc
	v_cndmask_b32_e32 v131, v160, v161, vcc
	v_cndmask_b32_e32 v130, v162, v163, vcc
	v_lshlrev_b64 v[128:129], 12, v[128:129]
	v_lshl_add_u64 v[130:131], v[130:131], 0, v[128:129]
	v_cndmask_b32_e32 v133, v164, v165, vcc
	v_cndmask_b32_e32 v132, v166, v167, vcc
	v_lshl_add_u64 v[134:135], v[132:133], 0, v[128:129]
	v_lshl_add_u64 v[128:129], v[130:131], 0, v[96:97]
	v_min_i32_e32 v130, 0x8000, v136
	v_ashrrev_i32_e32 v130, 12, v130
	v_mul_hi_i32_i24_e32 v131, 0x6000, v130
	v_mul_i32_i24_e32 v130, 0x6000, v130
	v_lshl_add_u64 v[130:131], s[0:1], 0, v[130:131]
	v_lshl_add_u64 v[132:133], v[130:131], 0, v[96:97]
	v_lshl_add_u64 v[130:131], v[134:135], 0, v[96:97]
	ds_read_b128 v[134:137], v146 offset:5440
	global_load_dwordx4 v[138:141], v[128:129], off
	global_load_dwordx4 v[142:145], v[132:133], off
	s_waitcnt vmcnt(0) lgkmcnt(0)
	v_pk_fma_f32 v[134:135], v[134:135], v[142:143], v[138:139]
	v_pk_fma_f32 v[136:137], v[136:137], v[144:145], v[140:141]
	v_or_b32_e32 v142, v176, v173
	global_store_dwordx4 v[130:131], v[134:137], off
	v_cmp_gt_i32_e32 vcc, s39, v142
	s_nop 0
	v_ashrrev_i32_e32 v134, 31, v142
	v_add_u32_e32 v136, 0xffff8000, v142
	v_cndmask_b32_e32 v135, 0, v134, vcc
	v_cndmask_b32_e32 v134, v136, v142, vcc
	v_cndmask_b32_e32 v137, v160, v161, vcc
	v_cndmask_b32_e32 v136, v162, v163, vcc
	v_lshlrev_b64 v[134:135], 12, v[134:135]
	v_lshl_add_u64 v[136:137], v[136:137], 0, v[134:135]
	v_cndmask_b32_e32 v139, v164, v165, vcc
	v_cndmask_b32_e32 v138, v166, v167, vcc
	v_lshl_add_u64 v[140:141], v[138:139], 0, v[134:135]
	v_lshl_add_u64 v[134:135], v[136:137], 0, v[96:97]
	v_min_i32_e32 v136, 0x8000, v142
	v_ashrrev_i32_e32 v136, 12, v136
	v_mul_hi_i32_i24_e32 v137, 0x6000, v136
	v_mul_i32_i24_e32 v136, 0x6000, v136
	v_lshl_add_u64 v[136:137], s[0:1], 0, v[136:137]
	v_lshl_add_u64 v[138:139], v[136:137], 0, v[96:97]
	v_lshl_add_u64 v[136:137], v[140:141], 0, v[96:97]
	ds_read_b128 v[140:143], v146 offset:6528
	global_load_dwordx4 v[184:187], v[134:135], off
	global_load_dwordx4 v[196:199], v[138:139], off
	v_cmp_gt_i32_e32 vcc, s39, v181
	s_waitcnt vmcnt(0) lgkmcnt(0)
	v_pk_fma_f32 v[140:141], v[140:141], v[196:197], v[184:185]
	v_pk_fma_f32 v[142:143], v[142:143], v[198:199], v[186:187]
	global_store_dwordx4 v[136:137], v[140:143], off
	v_cndmask_b32_e32 v145, v164, v165, vcc
	v_cndmask_b32_e32 v144, v166, v167, vcc
	v_ashrrev_i32_e32 v140, 31, v181
	v_add_u32_e32 v142, 0xffff8000, v181
	v_cndmask_b32_e32 v141, 0, v140, vcc
	v_cndmask_b32_e32 v140, v142, v181, vcc
	v_cndmask_b32_e32 v143, v160, v161, vcc
	v_cndmask_b32_e32 v142, v162, v163, vcc
	v_lshlrev_b64 v[140:141], 12, v[140:141]
	v_lshl_add_u64 v[142:143], v[142:143], 0, v[140:141]
	v_lshl_add_u64 v[184:185], v[144:145], 0, v[140:141]
	v_lshl_add_u64 v[140:141], v[142:143], 0, v[96:97]
	v_min_i32_e32 v142, 0x8000, v181
	v_ashrrev_i32_e32 v142, 12, v142
	v_mul_hi_i32_i24_e32 v143, 0x6000, v142
	v_mul_i32_i24_e32 v142, 0x6000, v142
	v_lshl_add_u64 v[142:143], s[0:1], 0, v[142:143]
	v_lshl_add_u64 v[144:145], v[142:143], 0, v[96:97]
	v_lshl_add_u64 v[142:143], v[184:185], 0, v[96:97]
	ds_read_b128 v[184:187], v146 offset:7616
	global_load_dwordx4 v[196:199], v[140:141], off
	global_load_dwordx4 v[200:203], v[144:145], off
	s_waitcnt vmcnt(0) lgkmcnt(0)
	v_pk_fma_f32 v[184:185], v[184:185], v[200:201], v[196:197]
	v_pk_fma_f32 v[186:187], v[186:187], v[202:203], v[198:199]
	global_store_dwordx4 v[142:143], v[184:187], off
	s_waitcnt lgkmcnt(0)
	ds_write2_b32 v147, v80, v81 offset1:68
	ds_write2_b32 v148, v64, v65 offset0:32 offset1:100
	ds_write2_b32 v147, v82, v83 offset0:136 offset1:204
	ds_write2_b32 v148, v66, v67 offset0:168 offset1:236
	ds_write2_b32 v149, v84, v85 offset0:32 offset1:100
	ds_write2_b32 v150, v68, v69 offset0:64 offset1:132
	ds_write2_b32 v149, v86, v87 offset0:168 offset1:236
	ds_write2_b32 v151, v70, v71 offset0:72 offset1:140
	ds_write2_b32 v152, v88, v89 offset0:64 offset1:132
	ds_write2_b32 v153, v72, v73 offset0:96 offset1:164
	ds_write2_b32 v154, v90, v91 offset0:72 offset1:140
	ds_write2_b32 v155, v74, v75 offset0:104 offset1:172
	ds_write2_b32 v156, v92, v93 offset0:96 offset1:164
	ds_write2_b32 v157, v76, v77 offset0:128 offset1:196
	ds_write2_b32 v158, v94, v95 offset0:104 offset1:172
	ds_write2_b32 v159, v78, v79 offset0:8 offset1:76
	s_waitcnt lgkmcnt(0)
	ds_read_b128 v[64:67], v146
	global_load_dwordx4 v[68:71], v[98:99], off offset:256
	global_load_dwordx4 v[72:75], v[102:103], off offset:256
	s_waitcnt vmcnt(0) lgkmcnt(0)
	v_pk_fma_f32 v[64:65], v[64:65], v[72:73], v[68:69]
	v_pk_fma_f32 v[66:67], v[66:67], v[74:75], v[70:71]
	global_store_dwordx4 v[100:101], v[64:67], off offset:256
	ds_read_b128 v[64:67], v146 offset:1088
	global_load_dwordx4 v[68:71], v[106:107], off offset:256
	global_load_dwordx4 v[72:75], v[108:109], off offset:256
	s_waitcnt vmcnt(0) lgkmcnt(0)
	v_pk_fma_f32 v[64:65], v[64:65], v[72:73], v[68:69]
	v_pk_fma_f32 v[66:67], v[66:67], v[74:75], v[70:71]
	global_store_dwordx4 v[104:105], v[64:67], off offset:256
	ds_read_b128 v[64:67], v146 offset:2176
	global_load_dwordx4 v[68:71], v[110:111], off offset:256
	global_load_dwordx4 v[72:75], v[114:115], off offset:256
	s_waitcnt vmcnt(0) lgkmcnt(0)
	v_pk_fma_f32 v[64:65], v[64:65], v[72:73], v[68:69]
	v_pk_fma_f32 v[66:67], v[66:67], v[74:75], v[70:71]
	global_store_dwordx4 v[112:113], v[64:67], off offset:256
	ds_read_b128 v[64:67], v146 offset:3264
	global_load_dwordx4 v[68:71], v[116:117], off offset:256
	global_load_dwordx4 v[72:75], v[120:121], off offset:256
	s_waitcnt vmcnt(0) lgkmcnt(0)
	v_pk_fma_f32 v[64:65], v[64:65], v[72:73], v[68:69]
	v_pk_fma_f32 v[66:67], v[66:67], v[74:75], v[70:71]
	global_store_dwordx4 v[118:119], v[64:67], off offset:256
	ds_read_b128 v[64:67], v146 offset:4352
	global_load_dwordx4 v[68:71], v[122:123], off offset:256
	global_load_dwordx4 v[72:75], v[126:127], off offset:256
	s_waitcnt vmcnt(0) lgkmcnt(0)
	v_pk_fma_f32 v[64:65], v[64:65], v[72:73], v[68:69]
	v_pk_fma_f32 v[66:67], v[66:67], v[74:75], v[70:71]
	global_store_dwordx4 v[124:125], v[64:67], off offset:256
	ds_read_b128 v[64:67], v146 offset:5440
	global_load_dwordx4 v[68:71], v[128:129], off offset:256
	global_load_dwordx4 v[72:75], v[132:133], off offset:256
	s_waitcnt vmcnt(0) lgkmcnt(0)
	v_pk_fma_f32 v[64:65], v[64:65], v[72:73], v[68:69]
	v_pk_fma_f32 v[66:67], v[66:67], v[74:75], v[70:71]
	global_store_dwordx4 v[130:131], v[64:67], off offset:256
	ds_read_b128 v[64:67], v146 offset:6528
	global_load_dwordx4 v[68:71], v[134:135], off offset:256
	global_load_dwordx4 v[72:75], v[138:139], off offset:256
	s_waitcnt vmcnt(0) lgkmcnt(0)
	v_pk_fma_f32 v[64:65], v[64:65], v[72:73], v[68:69]
	v_pk_fma_f32 v[66:67], v[66:67], v[74:75], v[70:71]
	global_store_dwordx4 v[136:137], v[64:67], off offset:256
	ds_read_b128 v[64:67], v146 offset:7616
	global_load_dwordx4 v[68:71], v[140:141], off offset:256
	global_load_dwordx4 v[72:75], v[144:145], off offset:256
	s_waitcnt vmcnt(0) lgkmcnt(0)
	v_pk_fma_f32 v[64:65], v[64:65], v[72:73], v[68:69]
	v_pk_fma_f32 v[66:67], v[66:67], v[74:75], v[70:71]
	global_store_dwordx4 v[142:143], v[64:67], off offset:256
	v_or_b32_e32 v74, 32, v176
	s_waitcnt lgkmcnt(0)
	ds_write2_b32 v147, v48, v49 offset1:68
	ds_write2_b32 v148, v32, v33 offset0:32 offset1:100
	ds_write2_b32 v147, v50, v51 offset0:136 offset1:204
	ds_write2_b32 v148, v34, v35 offset0:168 offset1:236
	ds_write2_b32 v149, v52, v53 offset0:32 offset1:100
	ds_write2_b32 v150, v36, v37 offset0:64 offset1:132
	ds_write2_b32 v149, v54, v55 offset0:168 offset1:236
	ds_write2_b32 v151, v38, v39 offset0:72 offset1:140
	ds_write2_b32 v152, v56, v57 offset0:64 offset1:132
	ds_write2_b32 v153, v40, v41 offset0:96 offset1:164
	ds_write2_b32 v154, v58, v59 offset0:72 offset1:140
	ds_write2_b32 v155, v42, v43 offset0:104 offset1:172
	ds_write2_b32 v156, v60, v61 offset0:96 offset1:164
	ds_write2_b32 v157, v44, v45 offset0:128 offset1:196
	ds_write2_b32 v158, v62, v63 offset0:104 offset1:172
	ds_write2_b32 v159, v46, v47 offset0:8 offset1:76
	v_or_b32_e32 v40, v74, v175
	v_cmp_gt_i32_e32 vcc, s39, v40
	v_ashrrev_i32_e32 v32, 31, v40
	v_add_u32_e32 v34, 0xffff8000, v40
	v_cndmask_b32_e32 v33, 0, v32, vcc
	v_cndmask_b32_e32 v32, v34, v40, vcc
	v_cndmask_b32_e32 v35, v160, v161, vcc
	v_cndmask_b32_e32 v34, v162, v163, vcc
	v_lshlrev_b64 v[32:33], 12, v[32:33]
	v_lshl_add_u64 v[34:35], v[34:35], 0, v[32:33]
	v_cndmask_b32_e32 v37, v164, v165, vcc
	v_cndmask_b32_e32 v36, v166, v167, vcc
	v_lshl_add_u64 v[38:39], v[36:37], 0, v[32:33]
	v_lshl_add_u64 v[32:33], v[34:35], 0, v[96:97]
	v_min_i32_e32 v34, 0x8000, v40
	v_ashrrev_i32_e32 v34, 12, v34
	v_mul_hi_i32_i24_e32 v35, 0x6000, v34
	v_mul_i32_i24_e32 v34, 0x6000, v34
	s_waitcnt lgkmcnt(0)
	v_lshl_add_u64 v[34:35], s[0:1], 0, v[34:35]
	v_lshl_add_u64 v[36:37], v[34:35], 0, v[96:97]
	v_lshl_add_u64 v[34:35], v[38:39], 0, v[96:97]
	ds_read_b128 v[38:41], v146
	global_load_dwordx4 v[42:45], v[32:33], off
	global_load_dwordx4 v[46:49], v[36:37], off
	v_or_b32_e32 v75, v74, v173
	s_waitcnt vmcnt(0) lgkmcnt(0)
	v_pk_fma_f32 v[38:39], v[38:39], v[46:47], v[42:43]
	v_pk_fma_f32 v[40:41], v[40:41], v[48:49], v[44:45]
	v_or_b32_e32 v46, v74, v168
	global_store_dwordx4 v[34:35], v[38:41], off
	v_cmp_gt_i32_e32 vcc, s39, v46
	s_nop 0
	v_ashrrev_i32_e32 v38, 31, v46
	v_add_u32_e32 v40, 0xffff8000, v46
	v_cndmask_b32_e32 v39, 0, v38, vcc
	v_cndmask_b32_e32 v38, v40, v46, vcc
	v_cndmask_b32_e32 v41, v160, v161, vcc
	v_cndmask_b32_e32 v40, v162, v163, vcc
	v_lshlrev_b64 v[38:39], 12, v[38:39]
	v_lshl_add_u64 v[40:41], v[40:41], 0, v[38:39]
	v_cndmask_b32_e32 v43, v164, v165, vcc
	v_cndmask_b32_e32 v42, v166, v167, vcc
	v_lshl_add_u64 v[44:45], v[42:43], 0, v[38:39]
	v_lshl_add_u64 v[38:39], v[40:41], 0, v[96:97]
	v_min_i32_e32 v40, 0x8000, v46
	v_ashrrev_i32_e32 v40, 12, v40
	v_mul_hi_i32_i24_e32 v41, 0x6000, v40
	v_mul_i32_i24_e32 v40, 0x6000, v40
	v_lshl_add_u64 v[40:41], s[0:1], 0, v[40:41]
	v_lshl_add_u64 v[42:43], v[40:41], 0, v[96:97]
	v_lshl_add_u64 v[40:41], v[44:45], 0, v[96:97]
	ds_read_b128 v[44:47], v146 offset:1088
	global_load_dwordx4 v[48:51], v[38:39], off
	global_load_dwordx4 v[52:55], v[42:43], off
	s_waitcnt vmcnt(0) lgkmcnt(0)
	v_pk_fma_f32 v[44:45], v[44:45], v[52:53], v[48:49]
	v_pk_fma_f32 v[46:47], v[46:47], v[54:55], v[50:51]
	v_or_b32_e32 v52, v74, v169
	global_store_dwordx4 v[40:41], v[44:47], off
	v_cmp_gt_i32_e32 vcc, s39, v52
	s_nop 0
	v_ashrrev_i32_e32 v44, 31, v52
	v_add_u32_e32 v46, 0xffff8000, v52
	v_cndmask_b32_e32 v45, 0, v44, vcc
	v_cndmask_b32_e32 v44, v46, v52, vcc
	v_cndmask_b32_e32 v47, v160, v161, vcc
	v_cndmask_b32_e32 v46, v162, v163, vcc
	v_lshlrev_b64 v[44:45], 12, v[44:45]
	v_lshl_add_u64 v[46:47], v[46:47], 0, v[44:45]
	v_cndmask_b32_e32 v49, v164, v165, vcc
	v_cndmask_b32_e32 v48, v166, v167, vcc
	v_lshl_add_u64 v[50:51], v[48:49], 0, v[44:45]
	v_lshl_add_u64 v[44:45], v[46:47], 0, v[96:97]
	v_min_i32_e32 v46, 0x8000, v52
	v_ashrrev_i32_e32 v46, 12, v46
	v_mul_hi_i32_i24_e32 v47, 0x6000, v46
	v_mul_i32_i24_e32 v46, 0x6000, v46
	v_lshl_add_u64 v[46:47], s[0:1], 0, v[46:47]
	v_lshl_add_u64 v[48:49], v[46:47], 0, v[96:97]
	v_lshl_add_u64 v[46:47], v[50:51], 0, v[96:97]
	ds_read_b128 v[50:53], v146 offset:2176
	global_load_dwordx4 v[54:57], v[44:45], off
	global_load_dwordx4 v[58:61], v[48:49], off
	s_waitcnt vmcnt(0) lgkmcnt(0)
	v_pk_fma_f32 v[50:51], v[50:51], v[58:59], v[54:55]
	v_pk_fma_f32 v[52:53], v[52:53], v[60:61], v[56:57]
	v_or_b32_e32 v58, v74, v170
	global_store_dwordx4 v[46:47], v[50:53], off
	v_cmp_gt_i32_e32 vcc, s39, v58
	s_nop 0
	v_ashrrev_i32_e32 v50, 31, v58
	v_add_u32_e32 v52, 0xffff8000, v58
	v_cndmask_b32_e32 v51, 0, v50, vcc
	v_cndmask_b32_e32 v50, v52, v58, vcc
	v_cndmask_b32_e32 v53, v160, v161, vcc
	v_cndmask_b32_e32 v52, v162, v163, vcc
	v_lshlrev_b64 v[50:51], 12, v[50:51]
	v_lshl_add_u64 v[52:53], v[52:53], 0, v[50:51]
	v_cndmask_b32_e32 v55, v164, v165, vcc
	v_cndmask_b32_e32 v54, v166, v167, vcc
	v_lshl_add_u64 v[56:57], v[54:55], 0, v[50:51]
	v_lshl_add_u64 v[50:51], v[52:53], 0, v[96:97]
	v_min_i32_e32 v52, 0x8000, v58
	v_ashrrev_i32_e32 v52, 12, v52
	v_mul_hi_i32_i24_e32 v53, 0x6000, v52
	v_mul_i32_i24_e32 v52, 0x6000, v52
	v_lshl_add_u64 v[52:53], s[0:1], 0, v[52:53]
	v_lshl_add_u64 v[54:55], v[52:53], 0, v[96:97]
	v_lshl_add_u64 v[52:53], v[56:57], 0, v[96:97]
	ds_read_b128 v[56:59], v146 offset:3264
	global_load_dwordx4 v[60:63], v[50:51], off
	global_load_dwordx4 v[64:67], v[54:55], off
	s_waitcnt vmcnt(0) lgkmcnt(0)
	v_pk_fma_f32 v[56:57], v[56:57], v[64:65], v[60:61]
	v_pk_fma_f32 v[58:59], v[58:59], v[66:67], v[62:63]
	v_or_b32_e32 v64, v74, v171
	global_store_dwordx4 v[52:53], v[56:59], off
	v_cmp_gt_i32_e32 vcc, s39, v64
	s_nop 0
	v_ashrrev_i32_e32 v56, 31, v64
	v_add_u32_e32 v58, 0xffff8000, v64
	v_cndmask_b32_e32 v57, 0, v56, vcc
	v_cndmask_b32_e32 v56, v58, v64, vcc
	v_cndmask_b32_e32 v59, v160, v161, vcc
	v_cndmask_b32_e32 v58, v162, v163, vcc
	v_lshlrev_b64 v[56:57], 12, v[56:57]
	v_lshl_add_u64 v[58:59], v[58:59], 0, v[56:57]
	v_cndmask_b32_e32 v61, v164, v165, vcc
	v_cndmask_b32_e32 v60, v166, v167, vcc
	v_lshl_add_u64 v[62:63], v[60:61], 0, v[56:57]
	v_lshl_add_u64 v[56:57], v[58:59], 0, v[96:97]
	v_min_i32_e32 v58, 0x8000, v64
	v_ashrrev_i32_e32 v58, 12, v58
	v_mul_hi_i32_i24_e32 v59, 0x6000, v58
	v_mul_i32_i24_e32 v58, 0x6000, v58
	v_lshl_add_u64 v[58:59], s[0:1], 0, v[58:59]
	v_lshl_add_u64 v[60:61], v[58:59], 0, v[96:97]
	v_lshl_add_u64 v[58:59], v[62:63], 0, v[96:97]
	ds_read_b128 v[62:65], v146 offset:4352
	global_load_dwordx4 v[66:69], v[56:57], off
	global_load_dwordx4 v[70:73], v[60:61], off
	s_waitcnt vmcnt(0) lgkmcnt(0)
	v_pk_fma_f32 v[62:63], v[62:63], v[70:71], v[66:67]
	v_pk_fma_f32 v[64:65], v[64:65], v[72:73], v[68:69]
	v_or_b32_e32 v70, v74, v172
	global_store_dwordx4 v[58:59], v[62:65], off
	v_cmp_gt_i32_e32 vcc, s39, v70
	s_nop 0
	v_ashrrev_i32_e32 v62, 31, v70
	v_add_u32_e32 v64, 0xffff8000, v70
	v_cndmask_b32_e32 v63, 0, v62, vcc
	v_cndmask_b32_e32 v62, v64, v70, vcc
	v_cndmask_b32_e32 v65, v160, v161, vcc
	v_cndmask_b32_e32 v64, v162, v163, vcc
	v_lshlrev_b64 v[62:63], 12, v[62:63]
	v_lshl_add_u64 v[64:65], v[64:65], 0, v[62:63]
	v_cndmask_b32_e32 v67, v164, v165, vcc
	v_cndmask_b32_e32 v66, v166, v167, vcc
	v_lshl_add_u64 v[68:69], v[66:67], 0, v[62:63]
	v_lshl_add_u64 v[62:63], v[64:65], 0, v[96:97]
	v_min_i32_e32 v64, 0x8000, v70
	v_ashrrev_i32_e32 v64, 12, v64
	v_mul_hi_i32_i24_e32 v65, 0x6000, v64
	v_mul_i32_i24_e32 v64, 0x6000, v64
	v_lshl_add_u64 v[64:65], s[0:1], 0, v[64:65]
	v_lshl_add_u64 v[66:67], v[64:65], 0, v[96:97]
	v_lshl_add_u64 v[64:65], v[68:69], 0, v[96:97]
	ds_read_b128 v[68:71], v146 offset:5440
	global_load_dwordx4 v[76:79], v[62:63], off
	global_load_dwordx4 v[80:83], v[66:67], off
	v_cmp_gt_i32_e32 vcc, s39, v75
	s_waitcnt vmcnt(0) lgkmcnt(0)
	v_pk_fma_f32 v[68:69], v[68:69], v[80:81], v[76:77]
	v_pk_fma_f32 v[70:71], v[70:71], v[82:83], v[78:79]
	global_store_dwordx4 v[64:65], v[68:71], off
	v_cndmask_b32_e32 v73, v164, v165, vcc
	v_cndmask_b32_e32 v72, v166, v167, vcc
	v_ashrrev_i32_e32 v68, 31, v75
	v_add_u32_e32 v70, 0xffff8000, v75
	v_cndmask_b32_e32 v69, 0, v68, vcc
	v_cndmask_b32_e32 v68, v70, v75, vcc
	v_cndmask_b32_e32 v71, v160, v161, vcc
	v_cndmask_b32_e32 v70, v162, v163, vcc
	v_lshlrev_b64 v[68:69], 12, v[68:69]
	v_lshl_add_u64 v[70:71], v[70:71], 0, v[68:69]
	v_lshl_add_u64 v[76:77], v[72:73], 0, v[68:69]
	v_lshl_add_u64 v[68:69], v[70:71], 0, v[96:97]
	v_min_i32_e32 v70, 0x8000, v75
	v_ashrrev_i32_e32 v70, 12, v70
	v_mul_hi_i32_i24_e32 v71, 0x6000, v70
	v_mul_i32_i24_e32 v70, 0x6000, v70
	v_lshl_add_u64 v[70:71], s[0:1], 0, v[70:71]
	v_lshl_add_u64 v[72:73], v[70:71], 0, v[96:97]
	v_lshl_add_u64 v[70:71], v[76:77], 0, v[96:97]
	ds_read_b128 v[76:79], v146 offset:6528
	global_load_dwordx4 v[80:83], v[68:69], off
	global_load_dwordx4 v[84:87], v[72:73], off
	s_waitcnt vmcnt(0) lgkmcnt(0)
	v_pk_fma_f32 v[76:77], v[76:77], v[84:85], v[80:81]
	v_pk_fma_f32 v[78:79], v[78:79], v[86:87], v[82:83]
	v_or_b32_e32 v82, v74, v174
	global_store_dwordx4 v[70:71], v[76:79], off
	v_cmp_gt_i32_e32 vcc, s39, v82
	v_ashrrev_i32_e32 v74, 31, v82
	v_add_u32_e32 v76, 0xffff8000, v82
	v_cndmask_b32_e32 v75, 0, v74, vcc
	v_cndmask_b32_e32 v74, v76, v82, vcc
	v_cndmask_b32_e32 v77, v160, v161, vcc
	v_cndmask_b32_e32 v76, v162, v163, vcc
	v_lshlrev_b64 v[74:75], 12, v[74:75]
	v_lshl_add_u64 v[76:77], v[76:77], 0, v[74:75]
	v_cndmask_b32_e32 v79, v164, v165, vcc
	v_cndmask_b32_e32 v78, v166, v167, vcc
	v_lshl_add_u64 v[80:81], v[78:79], 0, v[74:75]
	v_lshl_add_u64 v[74:75], v[76:77], 0, v[96:97]
	v_min_i32_e32 v76, 0x8000, v82
	v_ashrrev_i32_e32 v76, 12, v76
	v_mul_hi_i32_i24_e32 v77, 0x6000, v76
	v_mul_i32_i24_e32 v76, 0x6000, v76
	v_lshl_add_u64 v[76:77], s[0:1], 0, v[76:77]
	v_lshl_add_u64 v[78:79], v[76:77], 0, v[96:97]
	v_lshl_add_u64 v[76:77], v[80:81], 0, v[96:97]
	ds_read_b128 v[80:83], v146 offset:7616
	global_load_dwordx4 v[84:87], v[74:75], off
	global_load_dwordx4 v[88:91], v[78:79], off
	s_waitcnt vmcnt(0) lgkmcnt(0)
	v_pk_fma_f32 v[80:81], v[80:81], v[88:89], v[84:85]
	v_pk_fma_f32 v[82:83], v[82:83], v[90:91], v[86:87]
	global_store_dwordx4 v[76:77], v[80:83], off
	s_waitcnt lgkmcnt(0)
	ds_write2_b32 v147, v16, v17 offset1:68
	ds_write2_b32 v148, v0, v1 offset0:32 offset1:100
	ds_write2_b32 v147, v18, v19 offset0:136 offset1:204
	ds_write2_b32 v148, v2, v3 offset0:168 offset1:236
	ds_write2_b32 v149, v20, v21 offset0:32 offset1:100
	ds_write2_b32 v150, v4, v5 offset0:64 offset1:132
	ds_write2_b32 v149, v22, v23 offset0:168 offset1:236
	ds_write2_b32 v151, v6, v7 offset0:72 offset1:140
	ds_write2_b32 v152, v24, v25 offset0:64 offset1:132
	ds_write2_b32 v153, v8, v9 offset0:96 offset1:164
	ds_write2_b32 v154, v26, v27 offset0:72 offset1:140
	ds_write2_b32 v155, v10, v11 offset0:104 offset1:172
	ds_write2_b32 v156, v28, v29 offset0:96 offset1:164
	ds_write2_b32 v157, v12, v13 offset0:128 offset1:196
	ds_write2_b32 v158, v30, v31 offset0:104 offset1:172
	ds_write2_b32 v159, v14, v15 offset0:8 offset1:76
	s_waitcnt lgkmcnt(0)
	ds_read_b128 v[0:3], v146
	global_load_dwordx4 v[4:7], v[32:33], off offset:256
	global_load_dwordx4 v[8:11], v[36:37], off offset:256
	s_waitcnt vmcnt(0) lgkmcnt(0)
	v_pk_fma_f32 v[0:1], v[0:1], v[8:9], v[4:5]
	v_pk_fma_f32 v[2:3], v[2:3], v[10:11], v[6:7]
	global_store_dwordx4 v[34:35], v[0:3], off offset:256
	ds_read_b128 v[0:3], v146 offset:1088
	global_load_dwordx4 v[4:7], v[38:39], off offset:256
	global_load_dwordx4 v[8:11], v[42:43], off offset:256
	s_waitcnt vmcnt(0) lgkmcnt(0)
	v_pk_fma_f32 v[0:1], v[0:1], v[8:9], v[4:5]
	v_pk_fma_f32 v[2:3], v[2:3], v[10:11], v[6:7]
	global_store_dwordx4 v[40:41], v[0:3], off offset:256
	ds_read_b128 v[0:3], v146 offset:2176
	global_load_dwordx4 v[4:7], v[44:45], off offset:256
	global_load_dwordx4 v[8:11], v[48:49], off offset:256
	s_waitcnt vmcnt(0) lgkmcnt(0)
	v_pk_fma_f32 v[0:1], v[0:1], v[8:9], v[4:5]
	v_pk_fma_f32 v[2:3], v[2:3], v[10:11], v[6:7]
	global_store_dwordx4 v[46:47], v[0:3], off offset:256
	ds_read_b128 v[0:3], v146 offset:3264
	global_load_dwordx4 v[4:7], v[50:51], off offset:256
	global_load_dwordx4 v[8:11], v[54:55], off offset:256
	s_waitcnt vmcnt(0) lgkmcnt(0)
	v_pk_fma_f32 v[0:1], v[0:1], v[8:9], v[4:5]
	v_pk_fma_f32 v[2:3], v[2:3], v[10:11], v[6:7]
	global_store_dwordx4 v[52:53], v[0:3], off offset:256
	ds_read_b128 v[0:3], v146 offset:4352
	global_load_dwordx4 v[4:7], v[56:57], off offset:256
	global_load_dwordx4 v[8:11], v[60:61], off offset:256
	s_waitcnt vmcnt(0) lgkmcnt(0)
	v_pk_fma_f32 v[0:1], v[0:1], v[8:9], v[4:5]
	v_pk_fma_f32 v[2:3], v[2:3], v[10:11], v[6:7]
	global_store_dwordx4 v[58:59], v[0:3], off offset:256
	ds_read_b128 v[0:3], v146 offset:5440
	global_load_dwordx4 v[4:7], v[62:63], off offset:256
	global_load_dwordx4 v[8:11], v[66:67], off offset:256
	s_waitcnt vmcnt(0) lgkmcnt(0)
	v_pk_fma_f32 v[0:1], v[0:1], v[8:9], v[4:5]
	v_pk_fma_f32 v[2:3], v[2:3], v[10:11], v[6:7]
	global_store_dwordx4 v[64:65], v[0:3], off offset:256
	ds_read_b128 v[0:3], v146 offset:6528
	global_load_dwordx4 v[4:7], v[68:69], off offset:256
	global_load_dwordx4 v[8:11], v[72:73], off offset:256
	s_waitcnt vmcnt(0) lgkmcnt(0)
	v_pk_fma_f32 v[0:1], v[0:1], v[8:9], v[4:5]
	v_pk_fma_f32 v[2:3], v[2:3], v[10:11], v[6:7]
	global_store_dwordx4 v[70:71], v[0:3], off offset:256
	ds_read_b128 v[0:3], v146 offset:7616
	global_load_dwordx4 v[4:7], v[74:75], off offset:256
	global_load_dwordx4 v[8:11], v[78:79], off offset:256
	s_waitcnt vmcnt(0) lgkmcnt(0)
	v_pk_fma_f32 v[0:1], v[0:1], v[8:9], v[4:5]
	v_pk_fma_f32 v[2:3], v[2:3], v[10:11], v[6:7]
	global_store_dwordx4 v[76:77], v[0:3], off offset:256
	s_waitcnt lgkmcnt(0)
	s_barrier
	s_cbranch_scc1 .LBB0_923

.LBB0_1031:
	s_mul_hi_i32 s0, s2, 0x2e8ba2e9
	s_lshr_b32 s1, s0, 31
	s_ashr_i32 s0, s0, 6
	s_add_i32 s0, s0, s1
	s_lshl_b32 s1, s0, 3
	s_sub_i32 s7, s25, s1
	s_min_i32 s7, s7, 8
	s_abs_i32 s8, s7
	v_cvt_f32_u32_e32 v0, s8
	s_sub_i32 s11, 0, s8
	s_mulk_i32 s0, 0xfea0
	s_add_i32 s9, s0, s2
	v_rcp_iflag_f32_e32 v0, v0
	s_abs_i32 s0, s9
	s_xor_b32 s10, s9, s7
	s_ashr_i32 s10, s10, 31
	v_mul_f32_e32 v0, 0x4f7ffffe, v0
	v_cvt_u32_f32_e32 v0, v0
	v_mov_b32_e32 v237, v179
	v_readfirstlane_b32 s12, v0
	s_mul_i32 s11, s11, s12
	s_mul_hi_u32 s11, s12, s11
	s_add_i32 s12, s12, s11
	s_mul_hi_u32 s11, s0, s12
	s_mul_i32 s12, s11, s8
	s_sub_i32 s0, s0, s12
	s_add_i32 s13, s11, 1
	s_sub_i32 s12, s0, s8
	s_cmp_ge_u32 s0, s8
	s_cselect_b32 s11, s13, s11
	s_cselect_b32 s0, s12, s0
	s_add_i32 s12, s11, 1
	s_cmp_ge_u32 s0, s8
	s_cselect_b32 s0, s12, s11
	s_xor_b32 s0, s0, s10
	s_sub_i32 s0, s0, s10
	s_mul_i32 s7, s7, s0
	s_sub_i32 s7, s9, s7
	s_add_i32 s1, s1, s6
	v_ashrrev_i32_e32 v238, 6, v237
	s_add_i32 s7, s1, s7
	v_lshlrev_b32_e32 v0, 1, v238
	v_lshl_add_u32 v0, s7, 3, v0
	v_ashrrev_i32_e32 v1, 31, v0
	v_bfe_u32 v183, v237, 5, 1
	v_lshlrev_b64 v[0:1], 16, v[0:1]
	v_and_b32_e32 v239, 31, v237
	v_lshl_add_u64 v[0:1], s[64:65], 0, v[0:1]
	v_lshlrev_b32_e32 v176, 9, v183
	s_ashr_i32 s1, s0, 31
	v_lshl_add_u64 v[0:1], v[0:1], 0, v[176:177]
	v_lshlrev_b32_e32 v176, 4, v239
	v_ashrrev_i32_e32 v38, 2, v237
	s_lshl_b64 s[8:9], s[0:1], 18
	v_lshl_add_u64 v[184:185], v[0:1], 0, v[176:177]
	s_add_u32 s8, s4, s8
	v_lshlrev_b32_e32 v0, 5, v38
	v_lshlrev_b32_e32 v2, 3, v237
	s_addc_u32 s9, s5, s9
	v_ashrrev_i32_e32 v1, 31, v0
	v_and_b32_e32 v181, 24, v2
	v_lshl_add_u64 v[0:1], v[0:1], 1, s[8:9]
	v_lshlrev_b32_e32 v176, 1, v181
	v_lshl_add_u64 v[186:187], v[0:1], 0, v[176:177]
	s_movk_i32 s1, 0x2000
	v_add_co_u32_e32 v34, vcc, s1, v186
	v_mul_u32_u24_e32 v36, 40, v239
	s_nop 0
	v_addc_co_u32_e32 v35, vcc, 0, v187, vcc
	v_lshlrev_b32_e32 v37, 4, v183
	v_lshl_add_u32 v241, v36, 1, v37
	v_add_co_u32_e32 v36, vcc, s41, v184
	s_movk_i32 s8, 0x50
	s_nop 0
	v_addc_co_u32_e32 v37, vcc, 0, v185, vcc
	v_mad_u64_u32 v[188:189], s[8:9], v38, s8, v[176:177]
	v_and_b32_e32 v240, 63, v237
	v_mov_b32_e32 v176, 0x800
	v_lshl_add_u64 v[188:189], v[186:187], 0, v[176:177]
	v_bfe_u32 v247, v237, 4, 1
	v_lshlrev_b32_e32 v176, 9, v183
	v_lshl_add_u32 v176, v247, 8, v176
	v_lshl_add_u64 v[184:185], v[184:185], 0, v[176:177]
	v_lshrrev_b32_e32 v241, 2, v237
	v_bfe_u32 v247, v237, 4, 2
	v_lshlrev_b32_e32 v247, 1, v247
	v_mov_b32_e32 v176, 0x78
	v_lshrrev_b32_e32 v247, v247, v176
	v_and_b32_e32 v247, 3, v247
	v_and_b32_e32 v246, 3, v237
	v_xor_b32_e32 v247, v247, v246
	v_lshlrev_b32_e32 v247, 4, v247
	v_lshl_add_u32 v241, v241, 6, v247
	v_bfe_u32 v247, v237, 2, 2
	v_lshlrev_b32_e32 v247, 1, v247
	v_lshrrev_b32_e32 v247, v247, v176
	v_and_b32_e32 v247, 3, v247
	v_bfe_u32 v246, v237, 4, 2
	v_xor_b32_e32 v247, v247, v246
	v_lshlrev_b32_e32 v247, 4, v247
	v_and_b32_e32 v246, 15, v237
	v_lshl_add_u32 v246, v246, 6, v247
	v_mov_b32_e32 v176, s41
	v_lshl_add_u64 v[186:187], v[184:185], 0, v[176:177]
	s_mov_b32 s96, 0
	v_lshl_add_u64 v[166:167], v[188:189], 0, s[96:97]
	global_load_dwordx4 v[160:163], v[166:167], off offset:-2048
	global_load_dwordx4 v[164:167], v[166:167], off offset:2048
	v_lshl_add_u64 v[248:249], v[184:185], 0, s[96:97]
	v_lshl_add_u64 v[250:251], v[186:187], 0, s[96:97]
	global_load_dwordx4 v[128:131], v[248:249], off
	global_load_dwordx4 v[132:135], v[248:249], off offset:256
	global_load_dwordx4 v[136:139], v[250:251], off
	global_load_dwordx4 v[140:143], v[250:251], off offset:256
	s_movk_i32 s96, 0x2000
	v_lshl_add_u64 v[174:175], v[188:189], 0, s[96:97]
	global_load_dwordx4 v[168:171], v[174:175], off offset:-2048
	global_load_dwordx4 v[172:175], v[174:175], off offset:2048
	s_movk_i32 s96, 0x800
	v_lshl_add_u64 v[248:249], v[184:185], 0, s[96:97]
	v_lshl_add_u64 v[250:251], v[186:187], 0, s[96:97]
	global_load_dwordx4 v[144:147], v[248:249], off
	global_load_dwordx4 v[148:151], v[248:249], off offset:256
	global_load_dwordx4 v[152:155], v[250:251], off
	global_load_dwordx4 v[156:159], v[250:251], off offset:256
	v_mov_b32_e32 v0, 0
	v_mov_b32_e32 v1, 0
	v_mov_b32_e32 v2, 0
	v_mov_b32_e32 v3, 0
	v_mov_b32_e32 v4, 0
	v_mov_b32_e32 v5, 0
	v_mov_b32_e32 v6, 0
	v_mov_b32_e32 v7, 0
	v_mov_b32_e32 v8, 0
	v_mov_b32_e32 v9, 0
	v_mov_b32_e32 v10, 0
	v_mov_b32_e32 v11, 0
	v_mov_b32_e32 v12, 0
	v_mov_b32_e32 v13, 0
	v_mov_b32_e32 v14, 0
	v_mov_b32_e32 v15, 0
	v_mov_b32_e32 v16, 0
	v_mov_b32_e32 v17, 0
	v_mov_b32_e32 v18, 0
	v_mov_b32_e32 v19, 0
	v_mov_b32_e32 v20, 0
	v_mov_b32_e32 v21, 0
	v_mov_b32_e32 v22, 0
	v_mov_b32_e32 v23, 0
	v_mov_b32_e32 v24, 0
	v_mov_b32_e32 v25, 0
	v_mov_b32_e32 v26, 0
	v_mov_b32_e32 v27, 0
	v_mov_b32_e32 v28, 0
	v_mov_b32_e32 v29, 0
	v_mov_b32_e32 v30, 0
	v_mov_b32_e32 v31, 0
	v_mov_b32_e32 v32, 0
	v_mov_b32_e32 v33, 0
	v_mov_b32_e32 v34, 0
	v_mov_b32_e32 v35, 0
	v_mov_b32_e32 v36, 0
	v_mov_b32_e32 v37, 0
	v_mov_b32_e32 v38, 0
	v_mov_b32_e32 v39, 0
	v_mov_b32_e32 v40, 0
	v_mov_b32_e32 v41, 0
	v_mov_b32_e32 v42, 0
	v_mov_b32_e32 v43, 0
	v_mov_b32_e32 v44, 0
	v_mov_b32_e32 v45, 0
	v_mov_b32_e32 v46, 0
	v_mov_b32_e32 v47, 0
	v_mov_b32_e32 v48, 0
	v_mov_b32_e32 v49, 0
	v_mov_b32_e32 v50, 0
	v_mov_b32_e32 v51, 0
	v_mov_b32_e32 v52, 0
	v_mov_b32_e32 v53, 0
	v_mov_b32_e32 v54, 0
	v_mov_b32_e32 v55, 0
	v_mov_b32_e32 v56, 0
	v_mov_b32_e32 v57, 0
	v_mov_b32_e32 v58, 0
	v_mov_b32_e32 v59, 0
	v_mov_b32_e32 v60, 0
	v_mov_b32_e32 v61, 0
	v_mov_b32_e32 v62, 0
	v_mov_b32_e32 v63, 0
	v_mov_b32_e32 v64, 0
	v_mov_b32_e32 v65, 0
	v_mov_b32_e32 v66, 0
	v_mov_b32_e32 v67, 0
	v_mov_b32_e32 v68, 0
	v_mov_b32_e32 v69, 0
	v_mov_b32_e32 v70, 0
	v_mov_b32_e32 v71, 0
	v_mov_b32_e32 v72, 0
	v_mov_b32_e32 v73, 0
	v_mov_b32_e32 v74, 0
	v_mov_b32_e32 v75, 0
	v_mov_b32_e32 v76, 0
	v_mov_b32_e32 v77, 0
	v_mov_b32_e32 v78, 0
	v_mov_b32_e32 v79, 0
	v_mov_b32_e32 v80, 0
	v_mov_b32_e32 v81, 0
	v_mov_b32_e32 v82, 0
	v_mov_b32_e32 v83, 0
	v_mov_b32_e32 v84, 0
	v_mov_b32_e32 v85, 0
	v_mov_b32_e32 v86, 0
	v_mov_b32_e32 v87, 0
	v_mov_b32_e32 v88, 0
	v_mov_b32_e32 v89, 0
	v_mov_b32_e32 v90, 0
	v_mov_b32_e32 v91, 0
	v_mov_b32_e32 v92, 0
	v_mov_b32_e32 v93, 0
	v_mov_b32_e32 v94, 0
	v_mov_b32_e32 v95, 0
	v_mov_b32_e32 v96, 0
	v_mov_b32_e32 v97, 0
	v_mov_b32_e32 v98, 0
	v_mov_b32_e32 v99, 0
	v_mov_b32_e32 v100, 0
	v_mov_b32_e32 v101, 0
	v_mov_b32_e32 v102, 0
	v_mov_b32_e32 v103, 0
	v_mov_b32_e32 v104, 0
	v_mov_b32_e32 v105, 0
	v_mov_b32_e32 v106, 0
	v_mov_b32_e32 v107, 0
	v_mov_b32_e32 v108, 0
	v_mov_b32_e32 v109, 0
	v_mov_b32_e32 v110, 0
	v_mov_b32_e32 v111, 0
	v_mov_b32_e32 v112, 0
	v_mov_b32_e32 v113, 0
	v_mov_b32_e32 v114, 0
	v_mov_b32_e32 v115, 0
	v_mov_b32_e32 v116, 0
	v_mov_b32_e32 v117, 0
	v_mov_b32_e32 v118, 0
	v_mov_b32_e32 v119, 0
	v_mov_b32_e32 v120, 0
	v_mov_b32_e32 v121, 0
	v_mov_b32_e32 v122, 0
	v_mov_b32_e32 v123, 0
	v_mov_b32_e32 v124, 0
	v_mov_b32_e32 v125, 0
	v_mov_b32_e32 v126, 0
	v_mov_b32_e32 v127, 0
	s_mov_b32 s1, 0
	s_waitcnt vmcnt(10)
	ds_write_b128 v241, v[160:163]
	ds_write_b128 v241, v[164:167] offset:4096
	s_waitcnt lgkmcnt(0)
	s_barrier
.Lg16_gu_k:
	s_add_i32 s8, s1, 2
	s_min_u32 s9, s8, 30
	s_lshl_b32 s96, s9, 13
	v_lshl_add_u64 v[166:167], v[188:189], 0, s[96:97]
	global_load_dwordx4 v[160:163], v[166:167], off offset:-2048
	global_load_dwordx4 v[164:167], v[166:167], off offset:2048
	ds_read_b128 v[196:199], v246 offset:0
	ds_read_b128 v[200:203], v246 offset:1024
	ds_read_b128 v[204:207], v246 offset:2048
	ds_read_b128 v[242:245], v246 offset:3072
	s_lshl_b32 s96, s9, 11
	v_lshl_add_u64 v[248:249], v[184:185], 0, s[96:97]
	v_lshl_add_u64 v[250:251], v[186:187], 0, s[96:97]
	s_waitcnt vmcnt(8) lgkmcnt(3)
	v_mfma_f32_16x16x32_bf16 v[112:115], v[128:131], v[196:199], v[112:115]
	v_mfma_f32_16x16x32_bf16 v[120:123], v[132:135], v[196:199], v[120:123]
	v_mfma_f32_16x16x32_bf16 v[80:83], v[136:139], v[196:199], v[80:83]
	v_mfma_f32_16x16x32_bf16 v[88:91], v[140:143], v[196:199], v[88:91]
	ds_read_b128 v[196:199], v246 offset:4096
	s_waitcnt lgkmcnt(3)
	v_mfma_f32_16x16x32_bf16 v[116:119], v[128:131], v[200:203], v[116:119]
	v_mfma_f32_16x16x32_bf16 v[124:127], v[132:135], v[200:203], v[124:127]
	v_mfma_f32_16x16x32_bf16 v[84:87], v[136:139], v[200:203], v[84:87]
	v_mfma_f32_16x16x32_bf16 v[92:95], v[140:143], v[200:203], v[92:95]
	ds_read_b128 v[200:203], v246 offset:5120
	s_waitcnt lgkmcnt(3)
	v_mfma_f32_16x16x32_bf16 v[96:99], v[128:131], v[204:207], v[96:99]
	v_mfma_f32_16x16x32_bf16 v[104:107], v[132:135], v[204:207], v[104:107]
	v_mfma_f32_16x16x32_bf16 v[64:67], v[136:139], v[204:207], v[64:67]
	v_mfma_f32_16x16x32_bf16 v[72:75], v[140:143], v[204:207], v[72:75]
	ds_read_b128 v[204:207], v246 offset:6144
	s_waitcnt lgkmcnt(3)
	v_mfma_f32_16x16x32_bf16 v[100:103], v[128:131], v[242:245], v[100:103]
	v_mfma_f32_16x16x32_bf16 v[108:111], v[132:135], v[242:245], v[108:111]
	v_mfma_f32_16x16x32_bf16 v[68:71], v[136:139], v[242:245], v[68:71]
	v_mfma_f32_16x16x32_bf16 v[76:79], v[140:143], v[242:245], v[76:79]
	ds_read_b128 v[242:245], v246 offset:7168
	s_waitcnt vmcnt(6)
	ds_write_b128 v241, v[168:171] offset:8192
	ds_write_b128 v241, v[172:175] offset:12288
	s_waitcnt lgkmcnt(5)
	v_mfma_f32_16x16x32_bf16 v[48:51], v[128:131], v[196:199], v[48:51]
	v_mfma_f32_16x16x32_bf16 v[56:59], v[132:135], v[196:199], v[56:59]
	v_mfma_f32_16x16x32_bf16 v[16:19], v[136:139], v[196:199], v[16:19]
	v_mfma_f32_16x16x32_bf16 v[24:27], v[140:143], v[196:199], v[24:27]
	s_waitcnt lgkmcnt(4)
	v_mfma_f32_16x16x32_bf16 v[52:55], v[128:131], v[200:203], v[52:55]
	v_mfma_f32_16x16x32_bf16 v[60:63], v[132:135], v[200:203], v[60:63]
	v_mfma_f32_16x16x32_bf16 v[20:23], v[136:139], v[200:203], v[20:23]
	v_mfma_f32_16x16x32_bf16 v[28:31], v[140:143], v[200:203], v[28:31]
	s_waitcnt lgkmcnt(2)
	v_mfma_f32_16x16x32_bf16 v[32:35], v[128:131], v[204:207], v[32:35]
	v_mfma_f32_16x16x32_bf16 v[36:39], v[128:131], v[242:245], v[36:39]
	global_load_dwordx4 v[128:131], v[248:249], off
	v_mfma_f32_16x16x32_bf16 v[40:43], v[132:135], v[204:207], v[40:43]
	v_mfma_f32_16x16x32_bf16 v[44:47], v[132:135], v[242:245], v[44:47]
	global_load_dwordx4 v[132:135], v[248:249], off offset:256
	v_mfma_f32_16x16x32_bf16 v[0:3], v[136:139], v[204:207], v[0:3]
	v_mfma_f32_16x16x32_bf16 v[4:7], v[136:139], v[242:245], v[4:7]
	global_load_dwordx4 v[136:139], v[250:251], off
	v_mfma_f32_16x16x32_bf16 v[8:11], v[140:143], v[204:207], v[8:11]
	v_mfma_f32_16x16x32_bf16 v[12:15], v[140:143], v[242:245], v[12:15]
	global_load_dwordx4 v[140:143], v[250:251], off offset:256
	s_waitcnt lgkmcnt(0)
	s_barrier
	s_add_i32 s8, s1, 3
	s_min_u32 s9, s8, 31
	s_lshl_b32 s96, s9, 13
	v_lshl_add_u64 v[174:175], v[188:189], 0, s[96:97]
	global_load_dwordx4 v[168:171], v[174:175], off offset:-2048
	global_load_dwordx4 v[172:175], v[174:175], off offset:2048
	ds_read_b128 v[196:199], v246 offset:8192
	ds_read_b128 v[200:203], v246 offset:9216
	ds_read_b128 v[204:207], v246 offset:10240
	ds_read_b128 v[242:245], v246 offset:11264
	s_lshl_b32 s96, s9, 11
	v_lshl_add_u64 v[248:249], v[184:185], 0, s[96:97]
	v_lshl_add_u64 v[250:251], v[186:187], 0, s[96:97]
	s_waitcnt vmcnt(8) lgkmcnt(3)
	v_mfma_f32_16x16x32_bf16 v[112:115], v[144:147], v[196:199], v[112:115]
	v_mfma_f32_16x16x32_bf16 v[120:123], v[148:151], v[196:199], v[120:123]
	v_mfma_f32_16x16x32_bf16 v[80:83], v[152:155], v[196:199], v[80:83]
	v_mfma_f32_16x16x32_bf16 v[88:91], v[156:159], v[196:199], v[88:91]
	ds_read_b128 v[196:199], v246 offset:12288
	s_waitcnt lgkmcnt(3)
	v_mfma_f32_16x16x32_bf16 v[116:119], v[144:147], v[200:203], v[116:119]
	v_mfma_f32_16x16x32_bf16 v[124:127], v[148:151], v[200:203], v[124:127]
	v_mfma_f32_16x16x32_bf16 v[84:87], v[152:155], v[200:203], v[84:87]
	v_mfma_f32_16x16x32_bf16 v[92:95], v[156:159], v[200:203], v[92:95]
	ds_read_b128 v[200:203], v246 offset:13312
	s_waitcnt lgkmcnt(3)
	v_mfma_f32_16x16x32_bf16 v[96:99], v[144:147], v[204:207], v[96:99]
	v_mfma_f32_16x16x32_bf16 v[104:107], v[148:151], v[204:207], v[104:107]
	v_mfma_f32_16x16x32_bf16 v[64:67], v[152:155], v[204:207], v[64:67]
	v_mfma_f32_16x16x32_bf16 v[72:75], v[156:159], v[204:207], v[72:75]
	ds_read_b128 v[204:207], v246 offset:14336
	s_waitcnt lgkmcnt(3)
	v_mfma_f32_16x16x32_bf16 v[100:103], v[144:147], v[242:245], v[100:103]
	v_mfma_f32_16x16x32_bf16 v[108:111], v[148:151], v[242:245], v[108:111]
	v_mfma_f32_16x16x32_bf16 v[68:71], v[152:155], v[242:245], v[68:71]
	v_mfma_f32_16x16x32_bf16 v[76:79], v[156:159], v[242:245], v[76:79]
	ds_read_b128 v[242:245], v246 offset:15360
	s_waitcnt vmcnt(6)
	ds_write_b128 v241, v[160:163] offset:0
	ds_write_b128 v241, v[164:167] offset:4096
	s_waitcnt lgkmcnt(5)
	v_mfma_f32_16x16x32_bf16 v[48:51], v[144:147], v[196:199], v[48:51]
	v_mfma_f32_16x16x32_bf16 v[56:59], v[148:151], v[196:199], v[56:59]
	v_mfma_f32_16x16x32_bf16 v[16:19], v[152:155], v[196:199], v[16:19]
	v_mfma_f32_16x16x32_bf16 v[24:27], v[156:159], v[196:199], v[24:27]
	s_waitcnt lgkmcnt(4)
	v_mfma_f32_16x16x32_bf16 v[52:55], v[144:147], v[200:203], v[52:55]
	v_mfma_f32_16x16x32_bf16 v[60:63], v[148:151], v[200:203], v[60:63]
	v_mfma_f32_16x16x32_bf16 v[20:23], v[152:155], v[200:203], v[20:23]
	v_mfma_f32_16x16x32_bf16 v[28:31], v[156:159], v[200:203], v[28:31]
	s_waitcnt lgkmcnt(2)
	v_mfma_f32_16x16x32_bf16 v[32:35], v[144:147], v[204:207], v[32:35]
	v_mfma_f32_16x16x32_bf16 v[36:39], v[144:147], v[242:245], v[36:39]
	global_load_dwordx4 v[144:147], v[248:249], off
	v_mfma_f32_16x16x32_bf16 v[40:43], v[148:151], v[204:207], v[40:43]
	v_mfma_f32_16x16x32_bf16 v[44:47], v[148:151], v[242:245], v[44:47]
	global_load_dwordx4 v[148:151], v[248:249], off offset:256
	v_mfma_f32_16x16x32_bf16 v[0:3], v[152:155], v[204:207], v[0:3]
	v_mfma_f32_16x16x32_bf16 v[4:7], v[152:155], v[242:245], v[4:7]
	global_load_dwordx4 v[152:155], v[250:251], off
	v_mfma_f32_16x16x32_bf16 v[8:11], v[156:159], v[204:207], v[8:11]
	v_mfma_f32_16x16x32_bf16 v[12:15], v[156:159], v[242:245], v[12:15]
	global_load_dwordx4 v[156:159], v[250:251], off offset:256
	s_add_i32 s1, s1, 2
	s_cmp_lt_u32 s1, 32
	s_waitcnt lgkmcnt(0)
	s_barrier
	s_cbranch_scc1 .Lg16_gu_k
	s_nop 7
	v_permlane16_swap_b32_e32 v112, v116
	v_permlane16_swap_b32_e32 v113, v117
	v_permlane16_swap_b32_e32 v114, v118
	v_permlane16_swap_b32_e32 v115, v119
	v_permlane16_swap_b32_e32 v120, v124
	v_permlane16_swap_b32_e32 v121, v125
	v_permlane16_swap_b32_e32 v122, v126
	v_permlane16_swap_b32_e32 v123, v127
	v_permlane16_swap_b32_e32 v96, v100
	v_permlane16_swap_b32_e32 v97, v101
	v_permlane16_swap_b32_e32 v98, v102
	v_permlane16_swap_b32_e32 v99, v103
	v_permlane16_swap_b32_e32 v104, v108
	v_permlane16_swap_b32_e32 v105, v109
	v_permlane16_swap_b32_e32 v106, v110
	v_permlane16_swap_b32_e32 v107, v111
	v_permlane16_swap_b32_e32 v48, v52
	v_permlane16_swap_b32_e32 v49, v53
	v_permlane16_swap_b32_e32 v50, v54
	v_permlane16_swap_b32_e32 v51, v55
	v_permlane16_swap_b32_e32 v56, v60
	v_permlane16_swap_b32_e32 v57, v61
	v_permlane16_swap_b32_e32 v58, v62
	v_permlane16_swap_b32_e32 v59, v63
	v_permlane16_swap_b32_e32 v32, v36
	v_permlane16_swap_b32_e32 v33, v37
	v_permlane16_swap_b32_e32 v34, v38
	v_permlane16_swap_b32_e32 v35, v39
	v_permlane16_swap_b32_e32 v40, v44
	v_permlane16_swap_b32_e32 v41, v45
	v_permlane16_swap_b32_e32 v42, v46
	v_permlane16_swap_b32_e32 v43, v47
	v_permlane16_swap_b32_e32 v80, v84
	v_permlane16_swap_b32_e32 v81, v85
	v_permlane16_swap_b32_e32 v82, v86
	v_permlane16_swap_b32_e32 v83, v87
	v_permlane16_swap_b32_e32 v88, v92
	v_permlane16_swap_b32_e32 v89, v93
	v_permlane16_swap_b32_e32 v90, v94
	v_permlane16_swap_b32_e32 v91, v95
	v_permlane16_swap_b32_e32 v64, v68
	v_permlane16_swap_b32_e32 v65, v69
	v_permlane16_swap_b32_e32 v66, v70
	v_permlane16_swap_b32_e32 v67, v71
	v_permlane16_swap_b32_e32 v72, v76
	v_permlane16_swap_b32_e32 v73, v77
	v_permlane16_swap_b32_e32 v74, v78
	v_permlane16_swap_b32_e32 v75, v79
	v_permlane16_swap_b32_e32 v16, v20
	v_permlane16_swap_b32_e32 v17, v21
	v_permlane16_swap_b32_e32 v18, v22
	v_permlane16_swap_b32_e32 v19, v23
	v_permlane16_swap_b32_e32 v24, v28
	v_permlane16_swap_b32_e32 v25, v29
	v_permlane16_swap_b32_e32 v26, v30
	v_permlane16_swap_b32_e32 v27, v31
	v_permlane16_swap_b32_e32 v0, v4
	v_permlane16_swap_b32_e32 v1, v5
	v_permlane16_swap_b32_e32 v2, v6
	v_permlane16_swap_b32_e32 v3, v7
	v_permlane16_swap_b32_e32 v8, v12
	v_permlane16_swap_b32_e32 v9, v13
	v_permlane16_swap_b32_e32 v10, v14
	v_permlane16_swap_b32_e32 v11, v15
	v_permlane32_swap_b32_e32 v112, v116
	v_permlane32_swap_b32_e32 v113, v117
	v_permlane32_swap_b32_e32 v114, v118
	v_permlane32_swap_b32_e32 v115, v119
	v_permlane32_swap_b32_e32 v120, v124
	v_permlane32_swap_b32_e32 v121, v125
	v_permlane32_swap_b32_e32 v122, v126
	v_permlane32_swap_b32_e32 v123, v127
	v_permlane32_swap_b32_e32 v96, v100
	v_permlane32_swap_b32_e32 v97, v101
	v_permlane32_swap_b32_e32 v98, v102
	v_permlane32_swap_b32_e32 v99, v103
	v_permlane32_swap_b32_e32 v104, v108
	v_permlane32_swap_b32_e32 v105, v109
	v_permlane32_swap_b32_e32 v106, v110
	v_permlane32_swap_b32_e32 v107, v111
	v_permlane32_swap_b32_e32 v48, v52
	v_permlane32_swap_b32_e32 v49, v53
	v_permlane32_swap_b32_e32 v50, v54
	v_permlane32_swap_b32_e32 v51, v55
	v_permlane32_swap_b32_e32 v56, v60
	v_permlane32_swap_b32_e32 v57, v61
	v_permlane32_swap_b32_e32 v58, v62
	v_permlane32_swap_b32_e32 v59, v63
	v_permlane32_swap_b32_e32 v32, v36
	v_permlane32_swap_b32_e32 v33, v37
	v_permlane32_swap_b32_e32 v34, v38
	v_permlane32_swap_b32_e32 v35, v39
	v_permlane32_swap_b32_e32 v40, v44
	v_permlane32_swap_b32_e32 v41, v45
	v_permlane32_swap_b32_e32 v42, v46
	v_permlane32_swap_b32_e32 v43, v47
	v_permlane32_swap_b32_e32 v80, v84
	v_permlane32_swap_b32_e32 v81, v85
	v_permlane32_swap_b32_e32 v82, v86
	v_permlane32_swap_b32_e32 v83, v87
	v_permlane32_swap_b32_e32 v88, v92
	v_permlane32_swap_b32_e32 v89, v93
	v_permlane32_swap_b32_e32 v90, v94
	v_permlane32_swap_b32_e32 v91, v95
	v_permlane32_swap_b32_e32 v64, v68
	v_permlane32_swap_b32_e32 v65, v69
	v_permlane32_swap_b32_e32 v66, v70
	v_permlane32_swap_b32_e32 v67, v71
	v_permlane32_swap_b32_e32 v72, v76
	v_permlane32_swap_b32_e32 v73, v77
	v_permlane32_swap_b32_e32 v74, v78
	v_permlane32_swap_b32_e32 v75, v79
	v_permlane32_swap_b32_e32 v16, v20
	v_permlane32_swap_b32_e32 v17, v21
	v_permlane32_swap_b32_e32 v18, v22
	v_permlane32_swap_b32_e32 v19, v23
	v_permlane32_swap_b32_e32 v24, v28
	v_permlane32_swap_b32_e32 v25, v29
	v_permlane32_swap_b32_e32 v26, v30
	v_permlane32_swap_b32_e32 v27, v31
	v_permlane32_swap_b32_e32 v0, v4
	v_permlane32_swap_b32_e32 v1, v5
	v_permlane32_swap_b32_e32 v2, v6
	v_permlane32_swap_b32_e32 v3, v7
	v_permlane32_swap_b32_e32 v8, v12
	v_permlane32_swap_b32_e32 v9, v13
	v_permlane32_swap_b32_e32 v10, v14
	v_permlane32_swap_b32_e32 v11, v15
	s_waitcnt vmcnt(0)
	s_waitcnt vmcnt(0)
	v_mul_f32_e32 v133, 0xbfb8aa3b, v112
	v_exp_f32_e32 v133, v133
	s_movk_i32 s1, 0x2400
	v_mul_lo_u32 v128, v238, s1
	v_lshl_or_b32 v131, s0, 6, v181
	v_add_f32_e32 v133, 1.0, v133
	v_lshl_or_b32 v132, v239, 1, v128
	v_and_b32_e32 v129, 0xffffffc0, v237
	v_lshl_or_b32 v128, v181, 1, v128
	v_rcp_f32_e32 v135, v133
	s_nop 0
	v_mul_f32_e32 v112, v112, v135
	v_mul_f32_e32 v96, v96, v112
	v_cvt_pk_bf16_f32 v112, v96, s0
	s_movk_i32 s0, 0x240
	v_mad_u32_u24 v96, v183, s0, v132
	ds_write_b16 v96, v112
	v_mul_f32_e32 v112, 0xbfb8aa3b, v113
	v_exp_f32_e32 v112, v112
	v_lshl_add_u32 v130, s7, 8, v129
	v_lshrrev_b32_e32 v129, 2, v240
	v_mad_u32_u24 v128, v129, s42, v128
	v_add_f32_e32 v112, 1.0, v112
	v_rcp_f32_e32 v133, v112
	s_nop 0
	v_mul_f32_e32 v112, v113, v133
	v_mul_f32_e32 v97, v97, v112
	v_cvt_pk_bf16_f32 v97, v97, s0
	ds_write_b16 v96, v97 offset:144
	v_mul_f32_e32 v97, 0xbfb8aa3b, v114
	v_exp_f32_e32 v97, v97
	s_nop 0
	v_add_f32_e32 v97, 1.0, v97
	v_rcp_f32_e32 v113, v97
	s_nop 0
	v_mul_f32_e32 v97, v114, v113
	v_mul_f32_e32 v97, v98, v97
	v_cvt_pk_bf16_f32 v97, v97, s0
	ds_write_b16 v96, v97 offset:288
	v_mul_f32_e32 v97, 0xbfb8aa3b, v115
	v_exp_f32_e32 v97, v97
	s_nop 0
	v_add_f32_e32 v97, 1.0, v97
	v_rcp_f32_e32 v112, v97
	s_nop 0
	v_mul_f32_e32 v97, v115, v112
	v_mul_f32_e32 v97, v99, v97
	v_cvt_pk_bf16_f32 v97, v97, s0
	ds_write_b16 v96, v97 offset:432
	v_mul_f32_e32 v97, 0xbfb8aa3b, v116
	v_exp_f32_e32 v97, v97
	s_nop 0
	v_add_f32_e32 v97, 1.0, v97
	v_rcp_f32_e32 v99, v97
	s_nop 0
	v_mul_f32_e32 v97, v116, v99
	v_mul_f32_e32 v97, v100, v97
	v_cvt_pk_bf16_f32 v97, v97, s0
	ds_write_b16 v96, v97 offset:1152
	v_mul_f32_e32 v97, 0xbfb8aa3b, v117
	v_exp_f32_e32 v97, v97
	s_nop 0
	v_add_f32_e32 v97, 1.0, v97
	v_rcp_f32_e32 v99, v97
	s_nop 0
	v_mul_f32_e32 v97, v117, v99
	v_mul_f32_e32 v97, v101, v97
	v_cvt_pk_bf16_f32 v97, v97, s0
	ds_write_b16 v96, v97 offset:1296
	v_mul_f32_e32 v97, 0xbfb8aa3b, v118
	v_exp_f32_e32 v97, v97
	s_nop 0
	v_add_f32_e32 v97, 1.0, v97
	v_rcp_f32_e32 v99, v97
	s_nop 0
	v_mul_f32_e32 v97, v118, v99
	v_mul_f32_e32 v97, v102, v97
	v_cvt_pk_bf16_f32 v97, v97, s0
	ds_write_b16 v96, v97 offset:1440
	v_mul_f32_e32 v97, 0xbfb8aa3b, v119
	v_exp_f32_e32 v97, v97
	s_nop 0
	v_add_f32_e32 v97, 1.0, v97
	v_rcp_f32_e32 v99, v97
	s_nop 0
	v_mul_f32_e32 v97, v119, v99
	v_mul_f32_e32 v97, v103, v97
	v_cvt_pk_bf16_f32 v97, v97, s0
	ds_write_b16 v96, v97 offset:1584
	v_mul_f32_e32 v97, 0xbfb8aa3b, v120
	v_exp_f32_e32 v97, v97
	s_nop 0
	v_add_f32_e32 v97, 1.0, v97
	v_rcp_f32_e32 v99, v97
	s_nop 0
	v_mul_f32_e32 v97, v120, v99
	v_mul_f32_e32 v97, v104, v97
	v_cvt_pk_bf16_f32 v97, v97, s0
	ds_write_b16 v96, v97 offset:2304
	v_mul_f32_e32 v97, 0xbfb8aa3b, v121
	v_exp_f32_e32 v97, v97
	s_nop 0
	v_add_f32_e32 v97, 1.0, v97
	v_rcp_f32_e32 v99, v97
	s_nop 0
	v_mul_f32_e32 v97, v121, v99
	v_mul_f32_e32 v97, v105, v97
	v_cvt_pk_bf16_f32 v97, v97, s0
	ds_write_b16 v96, v97 offset:2448
	v_mul_f32_e32 v97, 0xbfb8aa3b, v122
	v_exp_f32_e32 v97, v97
	s_nop 0
	v_add_f32_e32 v97, 1.0, v97
	v_rcp_f32_e32 v99, v97
	s_nop 0
	v_mul_f32_e32 v97, v122, v99
	v_mul_f32_e32 v97, v106, v97
	v_cvt_pk_bf16_f32 v97, v97, s0
	ds_write_b16 v96, v97 offset:2592
	v_mul_f32_e32 v97, 0xbfb8aa3b, v123
	v_exp_f32_e32 v97, v97
	s_nop 0
	v_add_f32_e32 v97, 1.0, v97
	v_rcp_f32_e32 v99, v97
	s_nop 0
	v_mul_f32_e32 v97, v123, v99
	v_mul_f32_e32 v97, v107, v97
	v_cvt_pk_bf16_f32 v97, v97, s0
	ds_write_b16 v96, v97 offset:2736
	v_mul_f32_e32 v97, 0xbfb8aa3b, v124
	v_exp_f32_e32 v97, v97
	s_nop 0
	v_add_f32_e32 v97, 1.0, v97
	v_rcp_f32_e32 v99, v97
	s_nop 0
	v_mul_f32_e32 v97, v124, v99
	v_mul_f32_e32 v97, v108, v97
	v_cvt_pk_bf16_f32 v97, v97, s0
	ds_write_b16 v96, v97 offset:3456
	v_mul_f32_e32 v97, 0xbfb8aa3b, v125
	v_exp_f32_e32 v97, v97
	s_nop 0
	v_add_f32_e32 v97, 1.0, v97
	v_rcp_f32_e32 v99, v97
	s_nop 0
	v_mul_f32_e32 v97, v125, v99
	v_mul_f32_e32 v97, v109, v97
	v_cvt_pk_bf16_f32 v97, v97, s0
	ds_write_b16 v96, v97 offset:3600
	v_mul_f32_e32 v97, 0xbfb8aa3b, v126
	v_exp_f32_e32 v97, v97
	s_nop 0
	v_add_f32_e32 v97, 1.0, v97
	v_rcp_f32_e32 v99, v97
	s_nop 0
	v_mul_f32_e32 v97, v126, v99
	v_mul_f32_e32 v97, v110, v97
	v_cvt_pk_bf16_f32 v97, v97, s0
	ds_write_b16 v96, v97 offset:3744
	v_mul_f32_e32 v97, 0xbfb8aa3b, v127
	v_exp_f32_e32 v97, v97
	s_nop 0
	v_add_f32_e32 v97, 1.0, v97
	v_rcp_f32_e32 v99, v97
	s_nop 0
	v_mul_f32_e32 v97, v127, v99
	v_mul_f32_e32 v97, v111, v97
	v_cvt_pk_bf16_f32 v97, v97, s0
	ds_write_b16 v96, v97 offset:3888
	v_mul_f32_e32 v97, 0xbfb8aa3b, v80
	v_exp_f32_e32 v97, v97
	s_nop 0
	v_add_f32_e32 v97, 1.0, v97
	v_rcp_f32_e32 v99, v97
	s_nop 0
	v_mul_f32_e32 v80, v80, v99
	v_mul_f32_e32 v64, v64, v80
	v_cvt_pk_bf16_f32 v64, v64, s0
	ds_write_b16 v96, v64 offset:4608
	v_mul_f32_e32 v64, 0xbfb8aa3b, v81
	v_exp_f32_e32 v64, v64
	s_nop 0
	v_add_f32_e32 v64, 1.0, v64
	v_rcp_f32_e32 v97, v64
	s_nop 0
	v_mul_f32_e32 v64, v81, v97
	v_mul_f32_e32 v64, v65, v64
	v_cvt_pk_bf16_f32 v64, v64, s0
	ds_write_b16 v96, v64 offset:4752
	v_mul_f32_e32 v64, 0xbfb8aa3b, v82
	v_exp_f32_e32 v64, v64
	s_nop 0
	v_add_f32_e32 v64, 1.0, v64
	v_rcp_f32_e32 v80, v64
	s_nop 0
	v_mul_f32_e32 v64, v82, v80
	v_mul_f32_e32 v64, v66, v64
	v_cvt_pk_bf16_f32 v64, v64, s0
	ds_write_b16 v96, v64 offset:4896
	v_mul_f32_e32 v64, 0xbfb8aa3b, v83
	v_exp_f32_e32 v64, v64
	s_nop 0
	v_add_f32_e32 v64, 1.0, v64
	v_rcp_f32_e32 v66, v64
	s_nop 0
	v_mul_f32_e32 v64, v83, v66
	v_mul_f32_e32 v64, v67, v64
	v_cvt_pk_bf16_f32 v64, v64, s0
	ds_write_b16 v96, v64 offset:5040
	v_mul_f32_e32 v64, 0xbfb8aa3b, v84
	v_exp_f32_e32 v64, v64
	s_nop 0
	v_add_f32_e32 v64, 1.0, v64
	v_rcp_f32_e32 v66, v64
	s_nop 0
	v_mul_f32_e32 v64, v84, v66
	v_mul_f32_e32 v64, v68, v64
	v_cvt_pk_bf16_f32 v64, v64, s0
	ds_write_b16 v96, v64 offset:5760
	v_mul_f32_e32 v64, 0xbfb8aa3b, v85
	v_exp_f32_e32 v64, v64
	s_nop 0
	v_add_f32_e32 v64, 1.0, v64
	v_rcp_f32_e32 v66, v64
	s_nop 0
	v_mul_f32_e32 v64, v85, v66
	v_mul_f32_e32 v64, v69, v64
	v_cvt_pk_bf16_f32 v64, v64, s0
	ds_write_b16 v96, v64 offset:5904
	v_mul_f32_e32 v64, 0xbfb8aa3b, v86
	v_exp_f32_e32 v64, v64
	s_nop 0
	v_add_f32_e32 v64, 1.0, v64
	v_rcp_f32_e32 v66, v64
	s_nop 0
	v_mul_f32_e32 v64, v86, v66
	v_mul_f32_e32 v64, v70, v64
	v_cvt_pk_bf16_f32 v64, v64, s0
	ds_write_b16 v96, v64 offset:6048
	v_mul_f32_e32 v64, 0xbfb8aa3b, v87
	v_exp_f32_e32 v64, v64
	s_nop 0
	v_add_f32_e32 v64, 1.0, v64
	v_rcp_f32_e32 v66, v64
	s_nop 0
	v_mul_f32_e32 v64, v87, v66
	v_mul_f32_e32 v64, v71, v64
	v_cvt_pk_bf16_f32 v64, v64, s0
	ds_write_b16 v96, v64 offset:6192
	v_mul_f32_e32 v64, 0xbfb8aa3b, v88
	v_exp_f32_e32 v64, v64
	v_ashrrev_i32_e32 v71, 5, v130
	v_or_b32_e32 v70, 1, v71
	v_add_f32_e32 v64, 1.0, v64
	v_rcp_f32_e32 v66, v64
	s_nop 0
	v_mul_f32_e32 v64, v88, v66
	v_mul_f32_e32 v64, v72, v64
	v_cvt_pk_bf16_f32 v64, v64, s0
	ds_write_b16 v96, v64 offset:6912
	v_mul_f32_e32 v64, 0xbfb8aa3b, v89
	v_exp_f32_e32 v64, v64
	s_nop 0
	v_add_f32_e32 v64, 1.0, v64
	v_rcp_f32_e32 v66, v64
	s_nop 0
	v_mul_f32_e32 v64, v89, v66
	v_mul_f32_e32 v64, v73, v64
	v_cvt_pk_bf16_f32 v64, v64, s0
	ds_write_b16 v96, v64 offset:7056
	v_mul_f32_e32 v64, 0xbfb8aa3b, v90
	v_exp_f32_e32 v64, v64
	s_nop 0
	v_add_f32_e32 v64, 1.0, v64
	v_rcp_f32_e32 v66, v64
	s_nop 0
	v_mul_f32_e32 v64, v90, v66
	v_mul_f32_e32 v64, v74, v64
	v_cvt_pk_bf16_f32 v64, v64, s0
	ds_write_b16 v96, v64 offset:7200
	v_mul_f32_e32 v64, 0xbfb8aa3b, v91
	v_exp_f32_e32 v64, v64
	s_nop 0
	v_add_f32_e32 v64, 1.0, v64
	v_rcp_f32_e32 v66, v64
	s_nop 0
	v_mul_f32_e32 v64, v91, v66
	v_mul_f32_e32 v64, v75, v64
	v_cvt_pk_bf16_f32 v64, v64, s0
	ds_write_b16 v96, v64 offset:7344
	v_mul_f32_e32 v64, 0xbfb8aa3b, v92
	v_exp_f32_e32 v64, v64
	s_nop 0
	v_add_f32_e32 v64, 1.0, v64
	v_rcp_f32_e32 v66, v64
	s_nop 0
	v_mul_f32_e32 v64, v92, v66
	v_mul_f32_e32 v64, v76, v64
	v_cvt_pk_bf16_f32 v64, v64, s0
	ds_write_b16 v96, v64 offset:8064
	v_mul_f32_e32 v64, 0xbfb8aa3b, v93
	v_exp_f32_e32 v64, v64
	s_nop 0
	v_add_f32_e32 v64, 1.0, v64
	v_rcp_f32_e32 v66, v64
	s_nop 0
	v_mul_f32_e32 v64, v93, v66
	v_mul_f32_e32 v64, v77, v64
	v_cvt_pk_bf16_f32 v64, v64, s0
	ds_write_b16 v96, v64 offset:8208
	v_mul_f32_e32 v64, 0xbfb8aa3b, v94
	v_exp_f32_e32 v64, v64
	s_nop 0
	v_add_f32_e32 v64, 1.0, v64
	v_rcp_f32_e32 v66, v64
	s_nop 0
	v_mul_f32_e32 v64, v94, v66
	v_mul_f32_e32 v64, v78, v64
	v_cvt_pk_bf16_f32 v64, v64, s0
	ds_write_b16 v96, v64 offset:8352
	v_mul_f32_e32 v64, 0xbfb8aa3b, v95
	v_exp_f32_e32 v64, v64
	s_nop 0
	v_add_f32_e32 v64, 1.0, v64
	v_rcp_f32_e32 v66, v64
	s_nop 0
	v_mul_f32_e32 v64, v95, v66
	v_mul_f32_e32 v64, v79, v64
	v_cvt_pk_bf16_f32 v64, v64, s0
	ds_write_b16 v96, v64 offset:8496
	v_ashrrev_i32_e32 v68, 4, v131
	s_waitcnt lgkmcnt(0)
	v_ashrrev_i32_e32 v69, 31, v68
	ds_read_b128 v[72:75], v128
	v_mad_i64_i32 v[64:65], s[0:1], v71, s23, v[68:69]
	v_lshlrev_b64 v[64:65], 10, v[64:65]
	v_lshlrev_b32_e32 v66, 6, v181
	v_lshl_add_u64 v[64:65], s[66:67], 0, v[64:65]
	v_and_b32_e32 v176, 0x200, v66
	v_lshl_add_u64 v[76:77], v[64:65], 0, v[176:177]
	v_lshlrev_b32_e32 v66, 4, v129
	v_mov_b32_e32 v67, v177
	v_lshl_add_u64 v[64:65], v[76:77], 0, v[66:67]
	s_waitcnt lgkmcnt(0)
	global_store_dwordx4 v[64:65], v[72:75], off
	ds_read_b128 v[72:75], v128 offset:2304
	v_or_b32_e32 v64, 0x100, v66
	v_mov_b32_e32 v65, v177
	v_lshl_add_u64 v[76:77], v[76:77], 0, v[64:65]
	s_waitcnt lgkmcnt(0)
	global_store_dwordx4 v[76:77], v[72:75], off
	ds_read_b128 v[72:75], v128 offset:4608
	v_mad_i64_i32 v[76:77], s[0:1], v70, s23, v[68:69]
	v_lshlrev_b64 v[76:77], 10, v[76:77]
	v_lshl_add_u64 v[76:77], s[66:67], 0, v[76:77]
	v_lshl_add_u64 v[76:77], v[76:77], 0, v[176:177]
	v_lshl_add_u64 v[78:79], v[76:77], 0, v[66:67]
	v_mul_f32_e32 v69, 0xbfb8aa3b, v48
	s_waitcnt lgkmcnt(0)
	global_store_dwordx4 v[78:79], v[72:75], off
	ds_read_b128 v[72:75], v128 offset:6912
	v_exp_f32_e32 v69, v69
	v_lshl_add_u64 v[76:77], v[76:77], 0, v[64:65]
	v_add_f32_e32 v69, 1.0, v69
	s_waitcnt lgkmcnt(0)
	global_store_dwordx4 v[76:77], v[72:75], off
	s_waitcnt lgkmcnt(0)
	s_nop 1
	v_rcp_f32_e32 v73, v69
	s_nop 0
	v_mul_f32_e32 v48, v48, v73
	v_mul_f32_e32 v32, v32, v48
	v_cvt_pk_bf16_f32 v32, v32, s0
	ds_write_b16 v96, v32
	v_mul_f32_e32 v32, 0xbfb8aa3b, v49
	v_exp_f32_e32 v32, v32
	s_nop 0
	v_add_f32_e32 v32, 1.0, v32
	v_rcp_f32_e32 v69, v32
	s_nop 0
	v_mul_f32_e32 v32, v49, v69
	v_mul_f32_e32 v32, v33, v32
	v_cvt_pk_bf16_f32 v32, v32, s0
	ds_write_b16 v96, v32 offset:144
	v_mul_f32_e32 v32, 0xbfb8aa3b, v50
	v_exp_f32_e32 v32, v32
	s_nop 0
	v_add_f32_e32 v32, 1.0, v32
	v_rcp_f32_e32 v48, v32
	s_nop 0
	v_mul_f32_e32 v32, v50, v48
	v_mul_f32_e32 v32, v34, v32
	v_cvt_pk_bf16_f32 v32, v32, s0
	ds_write_b16 v96, v32 offset:288
	v_mul_f32_e32 v32, 0xbfb8aa3b, v51
	v_exp_f32_e32 v32, v32
	s_nop 0
	v_add_f32_e32 v32, 1.0, v32
	v_rcp_f32_e32 v34, v32
	s_nop 0
	v_mul_f32_e32 v32, v51, v34
	v_mul_f32_e32 v32, v35, v32
	v_cvt_pk_bf16_f32 v32, v32, s0
	ds_write_b16 v96, v32 offset:432
	v_mul_f32_e32 v32, 0xbfb8aa3b, v52
	v_exp_f32_e32 v32, v32
	s_nop 0
	v_add_f32_e32 v32, 1.0, v32
	v_rcp_f32_e32 v34, v32
	s_nop 0
	v_mul_f32_e32 v32, v52, v34
	v_mul_f32_e32 v32, v36, v32
	v_cvt_pk_bf16_f32 v32, v32, s0
	ds_write_b16 v96, v32 offset:1152
	v_mul_f32_e32 v32, 0xbfb8aa3b, v53
	v_exp_f32_e32 v32, v32
	s_nop 0
	v_add_f32_e32 v32, 1.0, v32
	v_rcp_f32_e32 v34, v32
	s_nop 0
	v_mul_f32_e32 v32, v53, v34
	v_mul_f32_e32 v32, v37, v32
	v_cvt_pk_bf16_f32 v32, v32, s0
	ds_write_b16 v96, v32 offset:1296
	v_mul_f32_e32 v32, 0xbfb8aa3b, v54
	v_exp_f32_e32 v32, v32
	s_nop 0
	v_add_f32_e32 v32, 1.0, v32
	v_rcp_f32_e32 v34, v32
	s_nop 0
	v_mul_f32_e32 v32, v54, v34
	v_mul_f32_e32 v32, v38, v32
	v_cvt_pk_bf16_f32 v32, v32, s0
	ds_write_b16 v96, v32 offset:1440
	v_mul_f32_e32 v32, 0xbfb8aa3b, v55
	v_exp_f32_e32 v32, v32
	s_nop 0
	v_add_f32_e32 v32, 1.0, v32
	v_rcp_f32_e32 v34, v32
	s_nop 0
	v_mul_f32_e32 v32, v55, v34
	v_mul_f32_e32 v32, v39, v32
	v_cvt_pk_bf16_f32 v32, v32, s0
	ds_write_b16 v96, v32 offset:1584
	v_mul_f32_e32 v32, 0xbfb8aa3b, v56
	v_exp_f32_e32 v32, v32
	s_nop 0
	v_add_f32_e32 v32, 1.0, v32
	v_rcp_f32_e32 v34, v32
	s_nop 0
	v_mul_f32_e32 v32, v56, v34
	v_mul_f32_e32 v32, v40, v32
	v_cvt_pk_bf16_f32 v32, v32, s0
	ds_write_b16 v96, v32 offset:2304
	v_mul_f32_e32 v32, 0xbfb8aa3b, v57
	v_exp_f32_e32 v32, v32
	s_nop 0
	v_add_f32_e32 v32, 1.0, v32
	v_rcp_f32_e32 v34, v32
	s_nop 0
	v_mul_f32_e32 v32, v57, v34
	v_mul_f32_e32 v32, v41, v32
	v_cvt_pk_bf16_f32 v32, v32, s0
	ds_write_b16 v96, v32 offset:2448
	v_mul_f32_e32 v32, 0xbfb8aa3b, v58
	v_exp_f32_e32 v32, v32
	s_nop 0
	v_add_f32_e32 v32, 1.0, v32
	v_rcp_f32_e32 v34, v32
	s_nop 0
	v_mul_f32_e32 v32, v58, v34
	v_mul_f32_e32 v32, v42, v32
	v_cvt_pk_bf16_f32 v32, v32, s0
	ds_write_b16 v96, v32 offset:2592
	v_mul_f32_e32 v32, 0xbfb8aa3b, v59
	v_exp_f32_e32 v32, v32
	s_nop 0
	v_add_f32_e32 v32, 1.0, v32
	v_rcp_f32_e32 v34, v32
	s_nop 0
	v_mul_f32_e32 v32, v59, v34
	v_mul_f32_e32 v32, v43, v32
	v_cvt_pk_bf16_f32 v32, v32, s0
	ds_write_b16 v96, v32 offset:2736
	v_mul_f32_e32 v32, 0xbfb8aa3b, v60
	v_exp_f32_e32 v32, v32
	s_nop 0
	v_add_f32_e32 v32, 1.0, v32
	v_rcp_f32_e32 v34, v32
	s_nop 0
	v_mul_f32_e32 v32, v60, v34
	v_mul_f32_e32 v32, v44, v32
	v_cvt_pk_bf16_f32 v32, v32, s0
	ds_write_b16 v96, v32 offset:3456
	v_mul_f32_e32 v32, 0xbfb8aa3b, v61
	v_exp_f32_e32 v32, v32
	s_nop 0
	v_add_f32_e32 v32, 1.0, v32
	v_rcp_f32_e32 v34, v32
	s_nop 0
	v_mul_f32_e32 v32, v61, v34
	v_mul_f32_e32 v32, v45, v32
	v_cvt_pk_bf16_f32 v32, v32, s0
	ds_write_b16 v96, v32 offset:3600
	v_mul_f32_e32 v32, 0xbfb8aa3b, v62
	v_exp_f32_e32 v32, v32
	s_nop 0
	v_add_f32_e32 v32, 1.0, v32
	v_rcp_f32_e32 v34, v32
	s_nop 0
	v_mul_f32_e32 v32, v62, v34
	v_mul_f32_e32 v32, v46, v32
	v_cvt_pk_bf16_f32 v32, v32, s0
	ds_write_b16 v96, v32 offset:3744
	v_mul_f32_e32 v32, 0xbfb8aa3b, v63
	v_exp_f32_e32 v32, v32
	s_nop 0
	v_add_f32_e32 v32, 1.0, v32
	v_rcp_f32_e32 v34, v32
	s_nop 0
	v_mul_f32_e32 v32, v63, v34
	v_mul_f32_e32 v32, v47, v32
	v_cvt_pk_bf16_f32 v32, v32, s0
	ds_write_b16 v96, v32 offset:3888
	v_mul_f32_e32 v32, 0xbfb8aa3b, v16
	v_exp_f32_e32 v32, v32
	s_nop 0
	v_add_f32_e32 v32, 1.0, v32
	v_rcp_f32_e32 v34, v32
	s_nop 0
	v_mul_f32_e32 v16, v16, v34
	v_mul_f32_e32 v0, v0, v16
	v_cvt_pk_bf16_f32 v0, v0, s0
	ds_write_b16 v96, v0 offset:4608
	v_mul_f32_e32 v0, 0xbfb8aa3b, v17
	v_exp_f32_e32 v0, v0
	s_nop 0
	v_add_f32_e32 v0, 1.0, v0
	v_rcp_f32_e32 v32, v0
	s_nop 0
	v_mul_f32_e32 v0, v17, v32
	v_mul_f32_e32 v0, v1, v0
	v_cvt_pk_bf16_f32 v0, v0, s0
	ds_write_b16 v96, v0 offset:4752
	v_mul_f32_e32 v0, 0xbfb8aa3b, v18
	v_exp_f32_e32 v0, v0
	s_nop 0
	v_add_f32_e32 v0, 1.0, v0
	v_rcp_f32_e32 v16, v0
	s_nop 0
	v_mul_f32_e32 v0, v18, v16
	v_mul_f32_e32 v0, v2, v0
	v_cvt_pk_bf16_f32 v0, v0, s0
	ds_write_b16 v96, v0 offset:4896
	v_mul_f32_e32 v0, 0xbfb8aa3b, v19
	v_exp_f32_e32 v0, v0
	s_nop 0
	v_add_f32_e32 v0, 1.0, v0
	v_rcp_f32_e32 v2, v0
	s_nop 0
	v_mul_f32_e32 v0, v19, v2
	v_mul_f32_e32 v0, v3, v0
	v_cvt_pk_bf16_f32 v0, v0, s0
	ds_write_b16 v96, v0 offset:5040
	v_mul_f32_e32 v0, 0xbfb8aa3b, v20
	v_exp_f32_e32 v0, v0
	s_nop 0
	v_add_f32_e32 v0, 1.0, v0
	v_rcp_f32_e32 v2, v0
	s_nop 0
	v_mul_f32_e32 v0, v20, v2
	v_mul_f32_e32 v0, v4, v0
	v_cvt_pk_bf16_f32 v0, v0, s0
	ds_write_b16 v96, v0 offset:5760
	v_mul_f32_e32 v0, 0xbfb8aa3b, v21
	v_exp_f32_e32 v0, v0
	s_nop 0
	v_add_f32_e32 v0, 1.0, v0
	v_rcp_f32_e32 v2, v0
	s_nop 0
	v_mul_f32_e32 v0, v21, v2
	v_mul_f32_e32 v0, v5, v0
	v_cvt_pk_bf16_f32 v0, v0, s0
	ds_write_b16 v96, v0 offset:5904
	v_mul_f32_e32 v0, 0xbfb8aa3b, v22
	v_exp_f32_e32 v0, v0
	s_nop 0
	v_add_f32_e32 v0, 1.0, v0
	v_rcp_f32_e32 v2, v0
	s_nop 0
	v_mul_f32_e32 v0, v22, v2
	v_mul_f32_e32 v0, v6, v0
	v_cvt_pk_bf16_f32 v0, v0, s0
	ds_write_b16 v96, v0 offset:6048
	v_mul_f32_e32 v0, 0xbfb8aa3b, v23
	v_exp_f32_e32 v0, v0
	s_nop 0
	v_add_f32_e32 v0, 1.0, v0
	v_rcp_f32_e32 v2, v0
	s_nop 0
	v_mul_f32_e32 v0, v23, v2
	v_mul_f32_e32 v0, v7, v0
	v_cvt_pk_bf16_f32 v0, v0, s0
	ds_write_b16 v96, v0 offset:6192
	v_mul_f32_e32 v0, 0xbfb8aa3b, v24
	v_exp_f32_e32 v0, v0
	s_nop 0
	v_add_f32_e32 v0, 1.0, v0
	v_rcp_f32_e32 v2, v0
	s_nop 0
	v_mul_f32_e32 v0, v24, v2
	v_mul_f32_e32 v0, v8, v0
	v_cvt_pk_bf16_f32 v0, v0, s0
	ds_write_b16 v96, v0 offset:6912
	v_mul_f32_e32 v0, 0xbfb8aa3b, v25
	v_exp_f32_e32 v0, v0
	s_nop 0
	v_add_f32_e32 v0, 1.0, v0
	v_rcp_f32_e32 v2, v0
	s_nop 0
	v_mul_f32_e32 v0, v25, v2
	v_mul_f32_e32 v0, v9, v0
	v_cvt_pk_bf16_f32 v0, v0, s0
	ds_write_b16 v96, v0 offset:7056
	v_mul_f32_e32 v0, 0xbfb8aa3b, v26
	v_exp_f32_e32 v0, v0
	s_nop 0
	v_add_f32_e32 v0, 1.0, v0
	v_rcp_f32_e32 v2, v0
	s_nop 0
	v_mul_f32_e32 v0, v26, v2
	v_mul_f32_e32 v0, v10, v0
	v_cvt_pk_bf16_f32 v0, v0, s0
	ds_write_b16 v96, v0 offset:7200
	v_mul_f32_e32 v0, 0xbfb8aa3b, v27
	v_exp_f32_e32 v0, v0
	s_nop 0
	v_add_f32_e32 v0, 1.0, v0
	v_rcp_f32_e32 v2, v0
	s_nop 0
	v_mul_f32_e32 v0, v27, v2
	v_mul_f32_e32 v0, v11, v0
	v_cvt_pk_bf16_f32 v0, v0, s0
	ds_write_b16 v96, v0 offset:7344
	v_mul_f32_e32 v0, 0xbfb8aa3b, v28
	v_exp_f32_e32 v0, v0
	s_nop 0
	v_add_f32_e32 v0, 1.0, v0
	v_rcp_f32_e32 v2, v0
	s_nop 0
	v_mul_f32_e32 v0, v28, v2
	v_mul_f32_e32 v0, v12, v0
	v_cvt_pk_bf16_f32 v0, v0, s0
	ds_write_b16 v96, v0 offset:8064
	v_mul_f32_e32 v0, 0xbfb8aa3b, v29
	v_exp_f32_e32 v0, v0
	s_nop 0
	v_add_f32_e32 v0, 1.0, v0
	v_rcp_f32_e32 v2, v0
	s_nop 0
	v_mul_f32_e32 v0, v29, v2
	v_mul_f32_e32 v0, v13, v0
	v_cvt_pk_bf16_f32 v0, v0, s0
	ds_write_b16 v96, v0 offset:8208
	v_mul_f32_e32 v0, 0xbfb8aa3b, v30
	v_exp_f32_e32 v0, v0
	s_nop 0
	v_add_f32_e32 v0, 1.0, v0
	v_rcp_f32_e32 v2, v0
	s_nop 0
	v_mul_f32_e32 v0, v30, v2
	v_mul_f32_e32 v0, v14, v0
	v_cvt_pk_bf16_f32 v0, v0, s0
	ds_write_b16 v96, v0 offset:8352
	v_mul_f32_e32 v0, 0xbfb8aa3b, v31
	v_exp_f32_e32 v0, v0
	s_nop 0
	v_add_f32_e32 v0, 1.0, v0
	v_rcp_f32_e32 v2, v0
	s_nop 0
	v_mul_f32_e32 v0, v31, v2
	v_mul_f32_e32 v0, v15, v0
	v_cvt_pk_bf16_f32 v0, v0, s0
	ds_write_b16 v96, v0 offset:8496
	v_or_b32_e32 v4, 2, v68
	s_waitcnt lgkmcnt(0)
	v_ashrrev_i32_e32 v5, 31, v4
	ds_read_b128 v[0:3], v128
	v_mad_i64_i32 v[6:7], s[0:1], v71, s23, v[4:5]
	v_lshlrev_b64 v[6:7], 10, v[6:7]
	v_lshl_add_u64 v[6:7], s[66:67], 0, v[6:7]
	v_lshl_add_u64 v[6:7], v[6:7], 0, v[176:177]
	v_lshl_add_u64 v[8:9], v[6:7], 0, v[66:67]
	s_waitcnt lgkmcnt(0)
	global_store_dwordx4 v[8:9], v[0:3], off
	ds_read_b128 v[0:3], v128 offset:2304
	v_lshl_add_u64 v[6:7], v[6:7], 0, v[64:65]
	v_mad_i64_i32 v[4:5], s[0:1], v70, s23, v[4:5]
	v_lshlrev_b64 v[4:5], 10, v[4:5]
	s_waitcnt lgkmcnt(0)
	global_store_dwordx4 v[6:7], v[0:3], off
	ds_read_b128 v[0:3], v128 offset:4608
	v_lshl_add_u64 v[4:5], s[66:67], 0, v[4:5]
	v_lshl_add_u64 v[4:5], v[4:5], 0, v[176:177]
	v_lshl_add_u64 v[6:7], v[4:5], 0, v[66:67]
	v_lshl_add_u64 v[4:5], v[4:5], 0, v[64:65]
	s_waitcnt lgkmcnt(0)
	global_store_dwordx4 v[6:7], v[0:3], off
	ds_read_b128 v[0:3], v128 offset:6912
	v_readlane_b32 s0, v254, 11
	s_add_i32 s2, s2, s0
	s_cmp_lt_i32 s2, s3
	s_waitcnt lgkmcnt(0)
	global_store_dwordx4 v[4:5], v[0:3], off
	s_waitcnt lgkmcnt(0)
	s_barrier
	s_cbranch_scc1 .LBB0_1031

.LBB0_1086:
	s_ashr_i32 s6, s2, 31
	s_lshr_b32 s6, s6, 26
	s_add_i32 s6, s2, s6
	s_ashr_i32 s7, s6, 6
	s_lshl_b32 s7, s7, 3
	s_sub_i32 s8, s25, s7
	s_min_i32 s8, s8, 8
	s_abs_i32 s9, s8
	v_cvt_f32_u32_e32 v0, s9
	s_sub_i32 s12, 0, s9
	s_andn2_b32 s6, s6, 63
	s_sub_i32 s10, s2, s6
	v_rcp_iflag_f32_e32 v0, v0
	s_abs_i32 s6, s10
	s_xor_b32 s11, s10, s8
	s_ashr_i32 s11, s11, 31
	v_mul_f32_e32 v0, 0x4f7ffffe, v0
	v_cvt_u32_f32_e32 v0, v0
	v_mov_b32_e32 v181, v179
	v_readfirstlane_b32 s13, v0
	s_mul_i32 s12, s12, s13
	s_mul_hi_u32 s12, s13, s12
	s_add_i32 s13, s13, s12
	s_mul_hi_u32 s12, s6, s13
	s_mul_i32 s13, s12, s9
	s_sub_i32 s6, s6, s13
	s_add_i32 s14, s12, 1
	s_sub_i32 s13, s6, s9
	s_cmp_ge_u32 s6, s9
	s_cselect_b32 s12, s14, s12
	s_cselect_b32 s6, s13, s6
	s_add_i32 s13, s12, 1
	s_cmp_ge_u32 s6, s9
	s_cselect_b32 s6, s13, s12
	s_xor_b32 s6, s6, s11
	s_sub_i32 s6, s6, s11
	s_mul_i32 s8, s8, s6
	s_add_i32 s7, s7, s5
	s_sub_i32 s8, s10, s8
	v_ashrrev_i32_e32 v237, 6, v181
	s_add_i32 s7, s7, s8
	v_lshlrev_b32_e32 v0, 1, v237
	v_bfe_u32 v183, v181, 5, 1
	v_lshl_add_u32 v2, s7, 3, v0
	v_mov_b64_e32 v[0:1], s[66:67]
	v_and_b32_e32 v238, 31, v181
	v_mad_i64_i32 v[0:1], s[8:9], v2, s24, v[0:1]
	v_lshlrev_b32_e32 v176, 9, v183
	v_lshl_add_u64 v[0:1], v[0:1], 0, v[176:177]
	v_lshlrev_b32_e32 v176, 4, v238
	v_ashrrev_i32_e32 v38, 2, v181
	s_mul_i32 s8, s6, 0xb0000
	v_lshl_add_u64 v[184:185], v[0:1], 0, v[176:177]
	s_mul_hi_i32 s9, s6, 0xb0000
	s_add_u32 s8, s3, s8
	v_lshlrev_b32_e32 v0, 5, v38
	s_addc_u32 s9, s4, s9
	v_ashrrev_i32_e32 v1, 31, v0
	v_lshlrev_b32_e32 v2, 4, v181
	v_lshl_add_u64 v[0:1], v[0:1], 1, s[8:9]
	v_and_b32_e32 v176, 48, v2
	v_lshl_add_u64 v[186:187], v[0:1], 0, v[176:177]
	s_movk_i32 s8, 0x2000
	v_add_co_u32_e32 v34, vcc, s8, v186
	v_mul_u32_u24_e32 v36, 40, v238
	s_nop 0
	v_addc_co_u32_e32 v35, vcc, 0, v187, vcc
	v_lshlrev_b32_e32 v37, 4, v183
	v_lshl_add_u32 v240, v36, 1, v37
	v_add_co_u32_e32 v36, vcc, s24, v184
	s_movk_i32 s9, 0x50
	s_nop 0
	v_addc_co_u32_e32 v37, vcc, 0, v185, vcc
	v_and_b32_e32 v239, 63, v181
	v_mov_b32_e32 v176, 0x800
	v_lshl_add_u64 v[188:189], v[186:187], 0, v[176:177]
	v_bfe_u32 v247, v181, 4, 1
	v_lshlrev_b32_e32 v176, 9, v183
	v_lshl_add_u32 v176, v247, 8, v176
	v_lshl_add_u64 v[184:185], v[184:185], 0, v[176:177]
	v_lshrrev_b32_e32 v241, 2, v181
	v_bfe_u32 v247, v181, 4, 2
	v_lshlrev_b32_e32 v247, 1, v247
	v_mov_b32_e32 v176, 0x78
	v_lshrrev_b32_e32 v247, v247, v176
	v_and_b32_e32 v247, 3, v247
	v_and_b32_e32 v246, 3, v181
	v_xor_b32_e32 v247, v247, v246
	v_lshlrev_b32_e32 v247, 4, v247
	v_lshl_add_u32 v241, v241, 6, v247
	v_bfe_u32 v247, v181, 2, 2
	v_lshlrev_b32_e32 v247, 1, v247
	v_lshrrev_b32_e32 v247, v247, v176
	v_and_b32_e32 v247, 3, v247
	v_bfe_u32 v246, v181, 4, 2
	v_xor_b32_e32 v247, v247, v246
	v_lshlrev_b32_e32 v247, 4, v247
	v_and_b32_e32 v246, 15, v181
	v_lshl_add_u32 v246, v246, 6, v247
	v_mov_b32_e32 v176, s24
	v_lshl_add_u64 v[186:187], v[184:185], 0, v[176:177]
	s_mov_b32 s96, 0
	v_lshl_add_u64 v[166:167], v[188:189], 0, s[96:97]
	global_load_dwordx4 v[160:163], v[166:167], off offset:-2048
	global_load_dwordx4 v[164:167], v[166:167], off offset:2048
	v_lshl_add_u64 v[248:249], v[184:185], 0, s[96:97]
	v_lshl_add_u64 v[250:251], v[186:187], 0, s[96:97]
	global_load_dwordx4 v[128:131], v[248:249], off
	global_load_dwordx4 v[132:135], v[248:249], off offset:256
	global_load_dwordx4 v[136:139], v[250:251], off
	global_load_dwordx4 v[140:143], v[250:251], off offset:256
	s_movk_i32 s96, 0x2000
	v_lshl_add_u64 v[174:175], v[188:189], 0, s[96:97]
	global_load_dwordx4 v[168:171], v[174:175], off offset:-2048
	global_load_dwordx4 v[172:175], v[174:175], off offset:2048
	s_movk_i32 s96, 0x800
	v_lshl_add_u64 v[248:249], v[184:185], 0, s[96:97]
	v_lshl_add_u64 v[250:251], v[186:187], 0, s[96:97]
	global_load_dwordx4 v[144:147], v[248:249], off
	global_load_dwordx4 v[148:151], v[248:249], off offset:256
	global_load_dwordx4 v[152:155], v[250:251], off
	global_load_dwordx4 v[156:159], v[250:251], off offset:256
	v_mov_b32_e32 v0, 0
	v_mov_b32_e32 v1, 0
	v_mov_b32_e32 v2, 0
	v_mov_b32_e32 v3, 0
	v_mov_b32_e32 v4, 0
	v_mov_b32_e32 v5, 0
	v_mov_b32_e32 v6, 0
	v_mov_b32_e32 v7, 0
	v_mov_b32_e32 v8, 0
	v_mov_b32_e32 v9, 0
	v_mov_b32_e32 v10, 0
	v_mov_b32_e32 v11, 0
	v_mov_b32_e32 v12, 0
	v_mov_b32_e32 v13, 0
	v_mov_b32_e32 v14, 0
	v_mov_b32_e32 v15, 0
	v_mov_b32_e32 v16, 0
	v_mov_b32_e32 v17, 0
	v_mov_b32_e32 v18, 0
	v_mov_b32_e32 v19, 0
	v_mov_b32_e32 v20, 0
	v_mov_b32_e32 v21, 0
	v_mov_b32_e32 v22, 0
	v_mov_b32_e32 v23, 0
	v_mov_b32_e32 v24, 0
	v_mov_b32_e32 v25, 0
	v_mov_b32_e32 v26, 0
	v_mov_b32_e32 v27, 0
	v_mov_b32_e32 v28, 0
	v_mov_b32_e32 v29, 0
	v_mov_b32_e32 v30, 0
	v_mov_b32_e32 v31, 0
	v_mov_b32_e32 v32, 0
	v_mov_b32_e32 v33, 0
	v_mov_b32_e32 v34, 0
	v_mov_b32_e32 v35, 0
	v_mov_b32_e32 v36, 0
	v_mov_b32_e32 v37, 0
	v_mov_b32_e32 v38, 0
	v_mov_b32_e32 v39, 0
	v_mov_b32_e32 v40, 0
	v_mov_b32_e32 v41, 0
	v_mov_b32_e32 v42, 0
	v_mov_b32_e32 v43, 0
	v_mov_b32_e32 v44, 0
	v_mov_b32_e32 v45, 0
	v_mov_b32_e32 v46, 0
	v_mov_b32_e32 v47, 0
	v_mov_b32_e32 v48, 0
	v_mov_b32_e32 v49, 0
	v_mov_b32_e32 v50, 0
	v_mov_b32_e32 v51, 0
	v_mov_b32_e32 v52, 0
	v_mov_b32_e32 v53, 0
	v_mov_b32_e32 v54, 0
	v_mov_b32_e32 v55, 0
	v_mov_b32_e32 v56, 0
	v_mov_b32_e32 v57, 0
	v_mov_b32_e32 v58, 0
	v_mov_b32_e32 v59, 0
	v_mov_b32_e32 v60, 0
	v_mov_b32_e32 v61, 0
	v_mov_b32_e32 v62, 0
	v_mov_b32_e32 v63, 0
	v_mov_b32_e32 v64, 0
	v_mov_b32_e32 v65, 0
	v_mov_b32_e32 v66, 0
	v_mov_b32_e32 v67, 0
	v_mov_b32_e32 v68, 0
	v_mov_b32_e32 v69, 0
	v_mov_b32_e32 v70, 0
	v_mov_b32_e32 v71, 0
	v_mov_b32_e32 v72, 0
	v_mov_b32_e32 v73, 0
	v_mov_b32_e32 v74, 0
	v_mov_b32_e32 v75, 0
	v_mov_b32_e32 v76, 0
	v_mov_b32_e32 v77, 0
	v_mov_b32_e32 v78, 0
	v_mov_b32_e32 v79, 0
	v_mov_b32_e32 v80, 0
	v_mov_b32_e32 v81, 0
	v_mov_b32_e32 v82, 0
	v_mov_b32_e32 v83, 0
	v_mov_b32_e32 v84, 0
	v_mov_b32_e32 v85, 0
	v_mov_b32_e32 v86, 0
	v_mov_b32_e32 v87, 0
	v_mov_b32_e32 v88, 0
	v_mov_b32_e32 v89, 0
	v_mov_b32_e32 v90, 0
	v_mov_b32_e32 v91, 0
	v_mov_b32_e32 v92, 0
	v_mov_b32_e32 v93, 0
	v_mov_b32_e32 v94, 0
	v_mov_b32_e32 v95, 0
	v_mov_b32_e32 v96, 0
	v_mov_b32_e32 v97, 0
	v_mov_b32_e32 v98, 0
	v_mov_b32_e32 v99, 0
	v_mov_b32_e32 v100, 0
	v_mov_b32_e32 v101, 0
	v_mov_b32_e32 v102, 0
	v_mov_b32_e32 v103, 0
	v_mov_b32_e32 v104, 0
	v_mov_b32_e32 v105, 0
	v_mov_b32_e32 v106, 0
	v_mov_b32_e32 v107, 0
	v_mov_b32_e32 v108, 0
	v_mov_b32_e32 v109, 0
	v_mov_b32_e32 v110, 0
	v_mov_b32_e32 v111, 0
	v_mov_b32_e32 v112, 0
	v_mov_b32_e32 v113, 0
	v_mov_b32_e32 v114, 0
	v_mov_b32_e32 v115, 0
	v_mov_b32_e32 v116, 0
	v_mov_b32_e32 v117, 0
	v_mov_b32_e32 v118, 0
	v_mov_b32_e32 v119, 0
	v_mov_b32_e32 v120, 0
	v_mov_b32_e32 v121, 0
	v_mov_b32_e32 v122, 0
	v_mov_b32_e32 v123, 0
	v_mov_b32_e32 v124, 0
	v_mov_b32_e32 v125, 0
	v_mov_b32_e32 v126, 0
	v_mov_b32_e32 v127, 0
	s_mov_b32 s8, 0
	s_waitcnt vmcnt(10)
	ds_write_b128 v241, v[160:163]
	ds_write_b128 v241, v[164:167] offset:4096
	s_waitcnt lgkmcnt(0)
	s_barrier
.Lg16_down_k:
	s_add_i32 s9, s8, 2
	s_min_u32 s10, s9, 86
	s_lshl_b32 s96, s10, 13
	v_lshl_add_u64 v[166:167], v[188:189], 0, s[96:97]
	global_load_dwordx4 v[160:163], v[166:167], off offset:-2048
	global_load_dwordx4 v[164:167], v[166:167], off offset:2048
	ds_read_b128 v[196:199], v246 offset:0
	ds_read_b128 v[200:203], v246 offset:1024
	ds_read_b128 v[204:207], v246 offset:2048
	ds_read_b128 v[242:245], v246 offset:3072
	s_lshl_b32 s96, s10, 11
	v_lshl_add_u64 v[248:249], v[184:185], 0, s[96:97]
	v_lshl_add_u64 v[250:251], v[186:187], 0, s[96:97]
	s_waitcnt vmcnt(8) lgkmcnt(3)
	v_mfma_f32_16x16x32_bf16 v[112:115], v[128:131], v[196:199], v[112:115]
	v_mfma_f32_16x16x32_bf16 v[120:123], v[132:135], v[196:199], v[120:123]
	v_mfma_f32_16x16x32_bf16 v[48:51], v[136:139], v[196:199], v[48:51]
	v_mfma_f32_16x16x32_bf16 v[56:59], v[140:143], v[196:199], v[56:59]
	ds_read_b128 v[196:199], v246 offset:4096
	s_waitcnt lgkmcnt(3)
	v_mfma_f32_16x16x32_bf16 v[116:119], v[128:131], v[200:203], v[116:119]
	v_mfma_f32_16x16x32_bf16 v[124:127], v[132:135], v[200:203], v[124:127]
	v_mfma_f32_16x16x32_bf16 v[52:55], v[136:139], v[200:203], v[52:55]
	v_mfma_f32_16x16x32_bf16 v[60:63], v[140:143], v[200:203], v[60:63]
	ds_read_b128 v[200:203], v246 offset:5120
	s_waitcnt lgkmcnt(3)
	v_mfma_f32_16x16x32_bf16 v[96:99], v[128:131], v[204:207], v[96:99]
	v_mfma_f32_16x16x32_bf16 v[104:107], v[132:135], v[204:207], v[104:107]
	v_mfma_f32_16x16x32_bf16 v[32:35], v[136:139], v[204:207], v[32:35]
	v_mfma_f32_16x16x32_bf16 v[40:43], v[140:143], v[204:207], v[40:43]
	ds_read_b128 v[204:207], v246 offset:6144
	s_waitcnt lgkmcnt(3)
	v_mfma_f32_16x16x32_bf16 v[100:103], v[128:131], v[242:245], v[100:103]
	v_mfma_f32_16x16x32_bf16 v[108:111], v[132:135], v[242:245], v[108:111]
	v_mfma_f32_16x16x32_bf16 v[36:39], v[136:139], v[242:245], v[36:39]
	v_mfma_f32_16x16x32_bf16 v[44:47], v[140:143], v[242:245], v[44:47]
	ds_read_b128 v[242:245], v246 offset:7168
	s_waitcnt vmcnt(6)
	ds_write_b128 v241, v[168:171] offset:8192
	ds_write_b128 v241, v[172:175] offset:12288
	s_waitcnt lgkmcnt(5)
	v_mfma_f32_16x16x32_bf16 v[80:83], v[128:131], v[196:199], v[80:83]
	v_mfma_f32_16x16x32_bf16 v[88:91], v[132:135], v[196:199], v[88:91]
	v_mfma_f32_16x16x32_bf16 v[16:19], v[136:139], v[196:199], v[16:19]
	v_mfma_f32_16x16x32_bf16 v[24:27], v[140:143], v[196:199], v[24:27]
	s_waitcnt lgkmcnt(4)
	v_mfma_f32_16x16x32_bf16 v[84:87], v[128:131], v[200:203], v[84:87]
	v_mfma_f32_16x16x32_bf16 v[92:95], v[132:135], v[200:203], v[92:95]
	v_mfma_f32_16x16x32_bf16 v[20:23], v[136:139], v[200:203], v[20:23]
	v_mfma_f32_16x16x32_bf16 v[28:31], v[140:143], v[200:203], v[28:31]
	s_waitcnt lgkmcnt(2)
	v_mfma_f32_16x16x32_bf16 v[64:67], v[128:131], v[204:207], v[64:67]
	v_mfma_f32_16x16x32_bf16 v[68:71], v[128:131], v[242:245], v[68:71]
	global_load_dwordx4 v[128:131], v[248:249], off
	v_mfma_f32_16x16x32_bf16 v[72:75], v[132:135], v[204:207], v[72:75]
	v_mfma_f32_16x16x32_bf16 v[76:79], v[132:135], v[242:245], v[76:79]
	global_load_dwordx4 v[132:135], v[248:249], off offset:256
	v_mfma_f32_16x16x32_bf16 v[0:3], v[136:139], v[204:207], v[0:3]
	v_mfma_f32_16x16x32_bf16 v[4:7], v[136:139], v[242:245], v[4:7]
	global_load_dwordx4 v[136:139], v[250:251], off
	v_mfma_f32_16x16x32_bf16 v[8:11], v[140:143], v[204:207], v[8:11]
	v_mfma_f32_16x16x32_bf16 v[12:15], v[140:143], v[242:245], v[12:15]
	global_load_dwordx4 v[140:143], v[250:251], off offset:256
	s_waitcnt lgkmcnt(0)
	s_barrier
	s_add_i32 s9, s8, 3
	s_min_u32 s10, s9, 87
	s_lshl_b32 s96, s10, 13
	v_lshl_add_u64 v[174:175], v[188:189], 0, s[96:97]
	global_load_dwordx4 v[168:171], v[174:175], off offset:-2048
	global_load_dwordx4 v[172:175], v[174:175], off offset:2048
	ds_read_b128 v[196:199], v246 offset:8192
	ds_read_b128 v[200:203], v246 offset:9216
	ds_read_b128 v[204:207], v246 offset:10240
	ds_read_b128 v[242:245], v246 offset:11264
	s_lshl_b32 s96, s10, 11
	v_lshl_add_u64 v[248:249], v[184:185], 0, s[96:97]
	v_lshl_add_u64 v[250:251], v[186:187], 0, s[96:97]
	s_waitcnt vmcnt(8) lgkmcnt(3)
	v_mfma_f32_16x16x32_bf16 v[112:115], v[144:147], v[196:199], v[112:115]
	v_mfma_f32_16x16x32_bf16 v[120:123], v[148:151], v[196:199], v[120:123]
	v_mfma_f32_16x16x32_bf16 v[48:51], v[152:155], v[196:199], v[48:51]
	v_mfma_f32_16x16x32_bf16 v[56:59], v[156:159], v[196:199], v[56:59]
	ds_read_b128 v[196:199], v246 offset:12288
	s_waitcnt lgkmcnt(3)
	v_mfma_f32_16x16x32_bf16 v[116:119], v[144:147], v[200:203], v[116:119]
	v_mfma_f32_16x16x32_bf16 v[124:127], v[148:151], v[200:203], v[124:127]
	v_mfma_f32_16x16x32_bf16 v[52:55], v[152:155], v[200:203], v[52:55]
	v_mfma_f32_16x16x32_bf16 v[60:63], v[156:159], v[200:203], v[60:63]
	ds_read_b128 v[200:203], v246 offset:13312
	s_waitcnt lgkmcnt(3)
	v_mfma_f32_16x16x32_bf16 v[96:99], v[144:147], v[204:207], v[96:99]
	v_mfma_f32_16x16x32_bf16 v[104:107], v[148:151], v[204:207], v[104:107]
	v_mfma_f32_16x16x32_bf16 v[32:35], v[152:155], v[204:207], v[32:35]
	v_mfma_f32_16x16x32_bf16 v[40:43], v[156:159], v[204:207], v[40:43]
	ds_read_b128 v[204:207], v246 offset:14336
	s_waitcnt lgkmcnt(3)
	v_mfma_f32_16x16x32_bf16 v[100:103], v[144:147], v[242:245], v[100:103]
	v_mfma_f32_16x16x32_bf16 v[108:111], v[148:151], v[242:245], v[108:111]
	v_mfma_f32_16x16x32_bf16 v[36:39], v[152:155], v[242:245], v[36:39]
	v_mfma_f32_16x16x32_bf16 v[44:47], v[156:159], v[242:245], v[44:47]
	ds_read_b128 v[242:245], v246 offset:15360
	s_waitcnt vmcnt(6)
	ds_write_b128 v241, v[160:163] offset:0
	ds_write_b128 v241, v[164:167] offset:4096
	s_waitcnt lgkmcnt(5)
	v_mfma_f32_16x16x32_bf16 v[80:83], v[144:147], v[196:199], v[80:83]
	v_mfma_f32_16x16x32_bf16 v[88:91], v[148:151], v[196:199], v[88:91]
	v_mfma_f32_16x16x32_bf16 v[16:19], v[152:155], v[196:199], v[16:19]
	v_mfma_f32_16x16x32_bf16 v[24:27], v[156:159], v[196:199], v[24:27]
	s_waitcnt lgkmcnt(4)
	v_mfma_f32_16x16x32_bf16 v[84:87], v[144:147], v[200:203], v[84:87]
	v_mfma_f32_16x16x32_bf16 v[92:95], v[148:151], v[200:203], v[92:95]
	v_mfma_f32_16x16x32_bf16 v[20:23], v[152:155], v[200:203], v[20:23]
	v_mfma_f32_16x16x32_bf16 v[28:31], v[156:159], v[200:203], v[28:31]
	s_waitcnt lgkmcnt(2)
	v_mfma_f32_16x16x32_bf16 v[64:67], v[144:147], v[204:207], v[64:67]
	v_mfma_f32_16x16x32_bf16 v[68:71], v[144:147], v[242:245], v[68:71]
	global_load_dwordx4 v[144:147], v[248:249], off
	v_mfma_f32_16x16x32_bf16 v[72:75], v[148:151], v[204:207], v[72:75]
	v_mfma_f32_16x16x32_bf16 v[76:79], v[148:151], v[242:245], v[76:79]
	global_load_dwordx4 v[148:151], v[248:249], off offset:256
	v_mfma_f32_16x16x32_bf16 v[0:3], v[152:155], v[204:207], v[0:3]
	v_mfma_f32_16x16x32_bf16 v[4:7], v[152:155], v[242:245], v[4:7]
	global_load_dwordx4 v[152:155], v[250:251], off
	v_mfma_f32_16x16x32_bf16 v[8:11], v[156:159], v[204:207], v[8:11]
	v_mfma_f32_16x16x32_bf16 v[12:15], v[156:159], v[242:245], v[12:15]
	global_load_dwordx4 v[156:159], v[250:251], off offset:256
	s_add_i32 s8, s8, 2
	s_cmp_lt_u32 s8, 88
	s_waitcnt lgkmcnt(0)
	s_barrier
	s_cbranch_scc1 .Lg16_down_k
	s_nop 7
	v_permlane16_swap_b32_e32 v112, v116
	v_permlane16_swap_b32_e32 v113, v117
	v_permlane16_swap_b32_e32 v114, v118
	v_permlane16_swap_b32_e32 v115, v119
	v_permlane16_swap_b32_e32 v120, v124
	v_permlane16_swap_b32_e32 v121, v125
	v_permlane16_swap_b32_e32 v122, v126
	v_permlane16_swap_b32_e32 v123, v127
	v_permlane16_swap_b32_e32 v96, v100
	v_permlane16_swap_b32_e32 v97, v101
	v_permlane16_swap_b32_e32 v98, v102
	v_permlane16_swap_b32_e32 v99, v103
	v_permlane16_swap_b32_e32 v104, v108
	v_permlane16_swap_b32_e32 v105, v109
	v_permlane16_swap_b32_e32 v106, v110
	v_permlane16_swap_b32_e32 v107, v111
	v_permlane16_swap_b32_e32 v80, v84
	v_permlane16_swap_b32_e32 v81, v85
	v_permlane16_swap_b32_e32 v82, v86
	v_permlane16_swap_b32_e32 v83, v87
	v_permlane16_swap_b32_e32 v88, v92
	v_permlane16_swap_b32_e32 v89, v93
	v_permlane16_swap_b32_e32 v90, v94
	v_permlane16_swap_b32_e32 v91, v95
	v_permlane16_swap_b32_e32 v64, v68
	v_permlane16_swap_b32_e32 v65, v69
	v_permlane16_swap_b32_e32 v66, v70
	v_permlane16_swap_b32_e32 v67, v71
	v_permlane16_swap_b32_e32 v72, v76
	v_permlane16_swap_b32_e32 v73, v77
	v_permlane16_swap_b32_e32 v74, v78
	v_permlane16_swap_b32_e32 v75, v79
	v_permlane16_swap_b32_e32 v48, v52
	v_permlane16_swap_b32_e32 v49, v53
	v_permlane16_swap_b32_e32 v50, v54
	v_permlane16_swap_b32_e32 v51, v55
	v_permlane16_swap_b32_e32 v56, v60
	v_permlane16_swap_b32_e32 v57, v61
	v_permlane16_swap_b32_e32 v58, v62
	v_permlane16_swap_b32_e32 v59, v63
	v_permlane16_swap_b32_e32 v32, v36
	v_permlane16_swap_b32_e32 v33, v37
	v_permlane16_swap_b32_e32 v34, v38
	v_permlane16_swap_b32_e32 v35, v39
	v_permlane16_swap_b32_e32 v40, v44
	v_permlane16_swap_b32_e32 v41, v45
	v_permlane16_swap_b32_e32 v42, v46
	v_permlane16_swap_b32_e32 v43, v47
	v_permlane16_swap_b32_e32 v16, v20
	v_permlane16_swap_b32_e32 v17, v21
	v_permlane16_swap_b32_e32 v18, v22
	v_permlane16_swap_b32_e32 v19, v23
	v_permlane16_swap_b32_e32 v24, v28
	v_permlane16_swap_b32_e32 v25, v29
	v_permlane16_swap_b32_e32 v26, v30
	v_permlane16_swap_b32_e32 v27, v31
	v_permlane16_swap_b32_e32 v0, v4
	v_permlane16_swap_b32_e32 v1, v5
	v_permlane16_swap_b32_e32 v2, v6
	v_permlane16_swap_b32_e32 v3, v7
	v_permlane16_swap_b32_e32 v8, v12
	v_permlane16_swap_b32_e32 v9, v13
	v_permlane16_swap_b32_e32 v10, v14
	v_permlane16_swap_b32_e32 v11, v15
	v_permlane32_swap_b32_e32 v112, v116
	v_permlane32_swap_b32_e32 v113, v117
	v_permlane32_swap_b32_e32 v114, v118
	v_permlane32_swap_b32_e32 v115, v119
	v_permlane32_swap_b32_e32 v120, v124
	v_permlane32_swap_b32_e32 v121, v125
	v_permlane32_swap_b32_e32 v122, v126
	v_permlane32_swap_b32_e32 v123, v127
	v_permlane32_swap_b32_e32 v96, v100
	v_permlane32_swap_b32_e32 v97, v101
	v_permlane32_swap_b32_e32 v98, v102
	v_permlane32_swap_b32_e32 v99, v103
	v_permlane32_swap_b32_e32 v104, v108
	v_permlane32_swap_b32_e32 v105, v109
	v_permlane32_swap_b32_e32 v106, v110
	v_permlane32_swap_b32_e32 v107, v111
	v_permlane32_swap_b32_e32 v80, v84
	v_permlane32_swap_b32_e32 v81, v85
	v_permlane32_swap_b32_e32 v82, v86
	v_permlane32_swap_b32_e32 v83, v87
	v_permlane32_swap_b32_e32 v88, v92
	v_permlane32_swap_b32_e32 v89, v93
	v_permlane32_swap_b32_e32 v90, v94
	v_permlane32_swap_b32_e32 v91, v95
	v_permlane32_swap_b32_e32 v64, v68
	v_permlane32_swap_b32_e32 v65, v69
	v_permlane32_swap_b32_e32 v66, v70
	v_permlane32_swap_b32_e32 v67, v71
	v_permlane32_swap_b32_e32 v72, v76
	v_permlane32_swap_b32_e32 v73, v77
	v_permlane32_swap_b32_e32 v74, v78
	v_permlane32_swap_b32_e32 v75, v79
	v_permlane32_swap_b32_e32 v48, v52
	v_permlane32_swap_b32_e32 v49, v53
	v_permlane32_swap_b32_e32 v50, v54
	v_permlane32_swap_b32_e32 v51, v55
	v_permlane32_swap_b32_e32 v56, v60
	v_permlane32_swap_b32_e32 v57, v61
	v_permlane32_swap_b32_e32 v58, v62
	v_permlane32_swap_b32_e32 v59, v63
	v_permlane32_swap_b32_e32 v32, v36
	v_permlane32_swap_b32_e32 v33, v37
	v_permlane32_swap_b32_e32 v34, v38
	v_permlane32_swap_b32_e32 v35, v39
	v_permlane32_swap_b32_e32 v40, v44
	v_permlane32_swap_b32_e32 v41, v45
	v_permlane32_swap_b32_e32 v42, v46
	v_permlane32_swap_b32_e32 v43, v47
	v_permlane32_swap_b32_e32 v16, v20
	v_permlane32_swap_b32_e32 v17, v21
	v_permlane32_swap_b32_e32 v18, v22
	v_permlane32_swap_b32_e32 v19, v23
	v_permlane32_swap_b32_e32 v24, v28
	v_permlane32_swap_b32_e32 v25, v29
	v_permlane32_swap_b32_e32 v26, v30
	v_permlane32_swap_b32_e32 v27, v31
	v_permlane32_swap_b32_e32 v0, v4
	v_permlane32_swap_b32_e32 v1, v5
	v_permlane32_swap_b32_e32 v2, v6
	v_permlane32_swap_b32_e32 v3, v7
	v_permlane32_swap_b32_e32 v8, v12
	v_permlane32_swap_b32_e32 v9, v13
	v_permlane32_swap_b32_e32 v10, v14
	v_permlane32_swap_b32_e32 v11, v15
	s_waitcnt vmcnt(0)
	s_movk_i32 s8, 0x2400
	s_waitcnt vmcnt(0)
	v_and_b32_e32 v132, 0xffffffc0, v181
	v_mul_lo_u32 v129, v237, s8
	v_lshlrev_b32_e32 v130, 2, v238
	v_lshl_add_u32 v156, s7, 8, v132
	v_mul_u32_u24_e32 v132, 0x110, v183
	v_or_b32_e32 v131, v129, v130
	v_lshlrev_b32_e32 v132, 2, v132
	v_add_u32_e32 v131, v131, v132
	v_add3_u32 v132, v129, v132, v130
	v_readlane_b32 s8, v253, 36
	v_lshlrev_b32_e32 v128, 2, v181
	v_add_u32_e32 v133, 0x800, v131
	v_add_u32_e32 v134, 0x800, v132
	v_lshrrev_b32_e32 v155, 4, v239
	v_readlane_b32 s12, v253, 40
	v_readlane_b32 s13, v253, 41
	v_readlane_b32 s14, v253, 42
	v_readlane_b32 s15, v253, 43
	v_readlane_b32 s16, v253, 44
	v_readlane_b32 s17, v253, 45
	v_readlane_b32 s18, v253, 46
	v_readlane_b32 s19, v253, 47
	v_and_b32_e32 v128, 60, v128
	ds_write2_b32 v131, v112, v113 offset1:68
	ds_write2_b32 v132, v96, v97 offset0:32 offset1:100
	ds_write2_b32 v131, v114, v115 offset0:136 offset1:204
	ds_write2_b32 v132, v98, v99 offset0:168 offset1:236
	ds_write2_b32 v133, v116, v117 offset0:32 offset1:100
	ds_write2_b32 v134, v100, v101 offset0:64 offset1:132
	ds_write2_b32 v133, v118, v119 offset0:168 offset1:236
	v_or_b32_e32 v100, v156, v155
	v_readlane_b32 s20, v253, 48
	v_readlane_b32 s21, v253, 49
	v_readlane_b32 s22, v253, 50
	v_readlane_b32 s23, v253, 51
	s_mov_b64 s[12:13], s[16:17]
	v_lshl_or_b32 v144, v128, 2, v129
	v_lshl_or_b32 v128, s6, 7, v128
	s_movk_i32 s6, 0x110
	v_cmp_gt_i32_e32 vcc, s39, v100
	v_add_u32_e32 v96, 0xffff8000, v100
	v_ashrrev_i32_e32 v97, 31, v100
	s_mov_b64 s[14:15], s[18:19]
	v_mad_u32_u24 v130, v155, s6, v144
	v_cndmask_b32_e32 v97, 0, v97, vcc
	v_cndmask_b32_e32 v96, v96, v100, vcc
	v_mov_b32_e32 v144, s63
	v_mov_b32_e32 v145, s15
	v_mov_b32_e32 v146, s62
	v_mov_b32_e32 v147, s14
	v_min_i32_e32 v100, 0x8000, v100
	v_add_u32_e32 v135, 0xa00, v132
	v_add_u32_e32 v136, 0x1000, v131
	v_add_u32_e32 v137, 0x1000, v132
	v_add_u32_e32 v138, 0x1200, v131
	v_add_u32_e32 v139, 0x1200, v132
	v_add_u32_e32 v140, 0x1800, v131
	v_add_u32_e32 v141, 0x1800, v132
	v_add_u32_e32 v142, 0x1a00, v131
	v_add_u32_e32 v143, 0x1c00, v132
	v_ashrrev_i32_e32 v129, 31, v128
	v_cndmask_b32_e32 v99, v144, v145, vcc
	v_cndmask_b32_e32 v98, v146, v147, vcc
	v_lshlrev_b64 v[96:97], 12, v[96:97]
	v_ashrrev_i32_e32 v100, 12, v100
	ds_write2_b32 v135, v102, v103 offset0:72 offset1:140
	ds_write2_b32 v136, v120, v121 offset0:64 offset1:132
	ds_write2_b32 v137, v104, v105 offset0:96 offset1:164
	ds_write2_b32 v138, v122, v123 offset0:72 offset1:140
	ds_write2_b32 v139, v106, v107 offset0:104 offset1:172
	ds_write2_b32 v140, v124, v125 offset0:96 offset1:164
	ds_write2_b32 v141, v108, v109 offset0:128 offset1:196
	ds_write2_b32 v142, v126, v127 offset0:104 offset1:172
	ds_write2_b32 v143, v110, v111 offset0:8 offset1:76
	v_lshl_add_u64 v[98:99], v[98:99], 0, v[96:97]
	v_lshlrev_b64 v[96:97], 2, v[128:129]
	v_mul_hi_i32_i24_e32 v101, 0x6000, v100
	v_mul_i32_i24_e32 v100, 0x6000, v100
	s_waitcnt lgkmcnt(0)
	v_lshl_add_u64 v[98:99], v[98:99], 0, v[96:97]
	v_lshl_add_u64 v[100:101], s[0:1], 0, v[100:101]
	v_lshl_add_u64 v[100:101], v[100:101], 0, v[96:97]
	ds_read_b128 v[102:105], v130
	global_load_dwordx4 v[106:109], v[98:99], off
	global_load_dwordx4 v[110:113], v[100:101], off
	v_or_b32_e32 v148, 4, v155
	v_or_b32_e32 v149, 8, v155
	v_or_b32_e32 v150, 12, v155
	v_or_b32_e32 v151, 16, v155
	v_or_b32_e32 v152, 20, v155
	v_or_b32_e32 v153, 24, v155
	v_or_b32_e32 v154, 28, v155
	v_or_b32_e32 v157, v156, v154
	v_readlane_b32 s6, v254, 11
	s_add_i32 s2, s2, s6
	s_cmp_lt_i32 s2, s26
	v_readlane_b32 s9, v253, 37
	v_readlane_b32 s10, v253, 38
	v_readlane_b32 s11, v253, 39
	s_mov_b64 s[16:17], s[20:21]
	s_mov_b64 s[18:19], s[22:23]
	s_waitcnt vmcnt(0) lgkmcnt(0)
	v_pk_fma_f32 v[102:103], v[102:103], v[110:111], v[106:107]
	v_pk_fma_f32 v[104:105], v[104:105], v[112:113], v[108:109]
	v_or_b32_e32 v106, v156, v148
	global_store_dwordx4 v[98:99], v[102:105], off
	v_cmp_gt_i32_e32 vcc, s39, v106
	s_nop 0
	v_ashrrev_i32_e32 v102, 31, v106
	v_add_u32_e32 v104, 0xffff8000, v106
	v_cndmask_b32_e32 v103, 0, v102, vcc
	v_cndmask_b32_e32 v102, v104, v106, vcc
	v_cndmask_b32_e32 v105, v144, v145, vcc
	v_cndmask_b32_e32 v104, v146, v147, vcc
	v_lshlrev_b64 v[102:103], 12, v[102:103]
	v_lshl_add_u64 v[102:103], v[104:105], 0, v[102:103]
	v_min_i32_e32 v104, 0x8000, v106
	v_ashrrev_i32_e32 v104, 12, v104
	v_mul_hi_i32_i24_e32 v105, 0x6000, v104
	v_mul_i32_i24_e32 v104, 0x6000, v104
	v_lshl_add_u64 v[102:103], v[102:103], 0, v[96:97]
	v_lshl_add_u64 v[104:105], s[0:1], 0, v[104:105]
	v_lshl_add_u64 v[104:105], v[104:105], 0, v[96:97]
	ds_read_b128 v[106:109], v130 offset:1088
	global_load_dwordx4 v[110:113], v[102:103], off
	global_load_dwordx4 v[114:117], v[104:105], off
	s_waitcnt vmcnt(0) lgkmcnt(0)
	v_pk_fma_f32 v[106:107], v[106:107], v[114:115], v[110:111]
	v_pk_fma_f32 v[108:109], v[108:109], v[116:117], v[112:113]
	v_or_b32_e32 v110, v156, v149
	global_store_dwordx4 v[102:103], v[106:109], off
	v_cmp_gt_i32_e32 vcc, s39, v110
	s_nop 0
	v_ashrrev_i32_e32 v106, 31, v110
	v_add_u32_e32 v108, 0xffff8000, v110
	v_cndmask_b32_e32 v107, 0, v106, vcc
	v_cndmask_b32_e32 v106, v108, v110, vcc
	v_cndmask_b32_e32 v109, v144, v145, vcc
	v_cndmask_b32_e32 v108, v146, v147, vcc
	v_lshlrev_b64 v[106:107], 12, v[106:107]
	v_lshl_add_u64 v[106:107], v[108:109], 0, v[106:107]
	v_min_i32_e32 v108, 0x8000, v110
	v_ashrrev_i32_e32 v108, 12, v108
	v_mul_hi_i32_i24_e32 v109, 0x6000, v108
	v_mul_i32_i24_e32 v108, 0x6000, v108
	v_lshl_add_u64 v[106:107], v[106:107], 0, v[96:97]
	v_lshl_add_u64 v[108:109], s[0:1], 0, v[108:109]
	v_lshl_add_u64 v[108:109], v[108:109], 0, v[96:97]
	ds_read_b128 v[110:113], v130 offset:2176
	global_load_dwordx4 v[114:117], v[106:107], off
	global_load_dwordx4 v[118:121], v[108:109], off
	s_waitcnt vmcnt(0) lgkmcnt(0)
	v_pk_fma_f32 v[110:111], v[110:111], v[118:119], v[114:115]
	v_pk_fma_f32 v[112:113], v[112:113], v[120:121], v[116:117]
	v_or_b32_e32 v114, v156, v150
	global_store_dwordx4 v[106:107], v[110:113], off
	v_cmp_gt_i32_e32 vcc, s39, v114
	s_nop 0
	v_ashrrev_i32_e32 v110, 31, v114
	v_add_u32_e32 v112, 0xffff8000, v114
	v_cndmask_b32_e32 v111, 0, v110, vcc
	v_cndmask_b32_e32 v110, v112, v114, vcc
	v_cndmask_b32_e32 v113, v144, v145, vcc
	v_cndmask_b32_e32 v112, v146, v147, vcc
	v_lshlrev_b64 v[110:111], 12, v[110:111]
	v_lshl_add_u64 v[110:111], v[112:113], 0, v[110:111]
	v_min_i32_e32 v112, 0x8000, v114
	v_ashrrev_i32_e32 v112, 12, v112
	v_mul_hi_i32_i24_e32 v113, 0x6000, v112
	v_mul_i32_i24_e32 v112, 0x6000, v112
	v_lshl_add_u64 v[110:111], v[110:111], 0, v[96:97]
	v_lshl_add_u64 v[112:113], s[0:1], 0, v[112:113]
	v_lshl_add_u64 v[112:113], v[112:113], 0, v[96:97]
	ds_read_b128 v[114:117], v130 offset:3264
	global_load_dwordx4 v[118:121], v[110:111], off
	global_load_dwordx4 v[122:125], v[112:113], off
	s_waitcnt vmcnt(0) lgkmcnt(0)
	v_pk_fma_f32 v[114:115], v[114:115], v[122:123], v[118:119]
	v_pk_fma_f32 v[116:117], v[116:117], v[124:125], v[120:121]
	v_or_b32_e32 v118, v156, v151
	global_store_dwordx4 v[110:111], v[114:117], off
	v_cmp_gt_i32_e32 vcc, s39, v118
	s_nop 0
	v_ashrrev_i32_e32 v114, 31, v118
	v_add_u32_e32 v116, 0xffff8000, v118
	v_cndmask_b32_e32 v115, 0, v114, vcc
	v_cndmask_b32_e32 v114, v116, v118, vcc
	v_cndmask_b32_e32 v117, v144, v145, vcc
	v_cndmask_b32_e32 v116, v146, v147, vcc
	v_lshlrev_b64 v[114:115], 12, v[114:115]
	v_lshl_add_u64 v[114:115], v[116:117], 0, v[114:115]
	v_min_i32_e32 v116, 0x8000, v118
	v_ashrrev_i32_e32 v116, 12, v116
	v_mul_hi_i32_i24_e32 v117, 0x6000, v116
	v_mul_i32_i24_e32 v116, 0x6000, v116
	v_lshl_add_u64 v[114:115], v[114:115], 0, v[96:97]
	v_lshl_add_u64 v[116:117], s[0:1], 0, v[116:117]
	v_lshl_add_u64 v[116:117], v[116:117], 0, v[96:97]
	ds_read_b128 v[118:121], v130 offset:4352
	global_load_dwordx4 v[122:125], v[114:115], off
	global_load_dwordx4 v[126:129], v[116:117], off
	s_waitcnt vmcnt(0) lgkmcnt(0)
	v_pk_fma_f32 v[118:119], v[118:119], v[126:127], v[122:123]
	v_pk_fma_f32 v[120:121], v[120:121], v[128:129], v[124:125]
	v_or_b32_e32 v122, v156, v152
	global_store_dwordx4 v[114:115], v[118:121], off
	v_cmp_gt_i32_e32 vcc, s39, v122
	s_nop 0
	v_ashrrev_i32_e32 v118, 31, v122
	v_add_u32_e32 v120, 0xffff8000, v122
	v_cndmask_b32_e32 v119, 0, v118, vcc
	v_cndmask_b32_e32 v118, v120, v122, vcc
	v_cndmask_b32_e32 v121, v144, v145, vcc
	v_cndmask_b32_e32 v120, v146, v147, vcc
	v_lshlrev_b64 v[118:119], 12, v[118:119]
	v_lshl_add_u64 v[118:119], v[120:121], 0, v[118:119]
	v_min_i32_e32 v120, 0x8000, v122
	v_ashrrev_i32_e32 v120, 12, v120
	v_mul_hi_i32_i24_e32 v121, 0x6000, v120
	v_mul_i32_i24_e32 v120, 0x6000, v120
	v_lshl_add_u64 v[118:119], v[118:119], 0, v[96:97]
	v_lshl_add_u64 v[120:121], s[0:1], 0, v[120:121]
	v_lshl_add_u64 v[120:121], v[120:121], 0, v[96:97]
	ds_read_b128 v[122:125], v130 offset:5440
	global_load_dwordx4 v[126:129], v[118:119], off
	global_load_dwordx4 v[158:161], v[120:121], off
	s_waitcnt vmcnt(0) lgkmcnt(0)
	v_pk_fma_f32 v[122:123], v[122:123], v[158:159], v[126:127]
	v_pk_fma_f32 v[124:125], v[124:125], v[160:161], v[128:129]
	v_or_b32_e32 v126, v156, v153
	global_store_dwordx4 v[118:119], v[122:125], off
	v_cmp_gt_i32_e32 vcc, s39, v126
	s_nop 0
	v_ashrrev_i32_e32 v122, 31, v126
	v_add_u32_e32 v124, 0xffff8000, v126
	v_cndmask_b32_e32 v123, 0, v122, vcc
	v_cndmask_b32_e32 v122, v124, v126, vcc
	v_cndmask_b32_e32 v125, v144, v145, vcc
	v_cndmask_b32_e32 v124, v146, v147, vcc
	v_lshlrev_b64 v[122:123], 12, v[122:123]
	v_lshl_add_u64 v[122:123], v[124:125], 0, v[122:123]
	v_min_i32_e32 v124, 0x8000, v126
	v_ashrrev_i32_e32 v124, 12, v124
	v_mul_hi_i32_i24_e32 v125, 0x6000, v124
	v_mul_i32_i24_e32 v124, 0x6000, v124
	v_lshl_add_u64 v[122:123], v[122:123], 0, v[96:97]
	v_lshl_add_u64 v[124:125], s[0:1], 0, v[124:125]
	v_lshl_add_u64 v[124:125], v[124:125], 0, v[96:97]
	ds_read_b128 v[126:129], v130 offset:6528
	global_load_dwordx4 v[158:161], v[122:123], off
	global_load_dwordx4 v[162:165], v[124:125], off
	v_cmp_gt_i32_e32 vcc, s39, v157
	s_waitcnt vmcnt(0) lgkmcnt(0)
	v_pk_fma_f32 v[126:127], v[126:127], v[162:163], v[158:159]
	v_pk_fma_f32 v[128:129], v[128:129], v[164:165], v[160:161]
	global_store_dwordx4 v[122:123], v[126:129], off
	ds_read_b128 v[158:161], v130 offset:7616
	s_nop 0
	v_ashrrev_i32_e32 v126, 31, v157
	v_add_u32_e32 v128, 0xffff8000, v157
	v_cndmask_b32_e32 v127, 0, v126, vcc
	v_cndmask_b32_e32 v126, v128, v157, vcc
	v_cndmask_b32_e32 v129, v144, v145, vcc
	v_cndmask_b32_e32 v128, v146, v147, vcc
	v_lshlrev_b64 v[126:127], 12, v[126:127]
	v_lshl_add_u64 v[126:127], v[128:129], 0, v[126:127]
	v_min_i32_e32 v128, 0x8000, v157
	v_ashrrev_i32_e32 v128, 12, v128
	v_mul_hi_i32_i24_e32 v129, 0x6000, v128
	v_mul_i32_i24_e32 v128, 0x6000, v128
	v_lshl_add_u64 v[126:127], v[126:127], 0, v[96:97]
	v_lshl_add_u64 v[128:129], s[0:1], 0, v[128:129]
	v_lshl_add_u64 v[128:129], v[128:129], 0, v[96:97]
	global_load_dwordx4 v[162:165], v[126:127], off
	global_load_dwordx4 v[166:169], v[128:129], off
	s_waitcnt vmcnt(0) lgkmcnt(0)
	v_pk_fma_f32 v[158:159], v[158:159], v[166:167], v[162:163]
	v_pk_fma_f32 v[160:161], v[160:161], v[168:169], v[164:165]
	global_store_dwordx4 v[126:127], v[158:161], off
	s_waitcnt lgkmcnt(0)
	ds_write2_b32 v131, v80, v81 offset1:68
	ds_write2_b32 v132, v64, v65 offset0:32 offset1:100
	ds_write2_b32 v131, v82, v83 offset0:136 offset1:204
	ds_write2_b32 v132, v66, v67 offset0:168 offset1:236
	ds_write2_b32 v133, v84, v85 offset0:32 offset1:100
	ds_write2_b32 v134, v68, v69 offset0:64 offset1:132
	ds_write2_b32 v133, v86, v87 offset0:168 offset1:236
	ds_write2_b32 v135, v70, v71 offset0:72 offset1:140
	ds_write2_b32 v136, v88, v89 offset0:64 offset1:132
	ds_write2_b32 v137, v72, v73 offset0:96 offset1:164
	ds_write2_b32 v138, v90, v91 offset0:72 offset1:140
	ds_write2_b32 v139, v74, v75 offset0:104 offset1:172
	ds_write2_b32 v140, v92, v93 offset0:96 offset1:164
	ds_write2_b32 v141, v76, v77 offset0:128 offset1:196
	ds_write2_b32 v142, v94, v95 offset0:104 offset1:172
	ds_write2_b32 v143, v78, v79 offset0:8 offset1:76
	s_waitcnt lgkmcnt(0)
	ds_read_b128 v[64:67], v130
	global_load_dwordx4 v[68:71], v[98:99], off offset:256
	global_load_dwordx4 v[72:75], v[100:101], off offset:256
	s_waitcnt vmcnt(0) lgkmcnt(0)
	v_pk_fma_f32 v[64:65], v[64:65], v[72:73], v[68:69]
	v_pk_fma_f32 v[66:67], v[66:67], v[74:75], v[70:71]
	global_store_dwordx4 v[98:99], v[64:67], off offset:256
	ds_read_b128 v[64:67], v130 offset:1088
	global_load_dwordx4 v[68:71], v[102:103], off offset:256
	global_load_dwordx4 v[72:75], v[104:105], off offset:256
	s_waitcnt vmcnt(0) lgkmcnt(0)
	v_pk_fma_f32 v[64:65], v[64:65], v[72:73], v[68:69]
	v_pk_fma_f32 v[66:67], v[66:67], v[74:75], v[70:71]
	global_store_dwordx4 v[102:103], v[64:67], off offset:256
	ds_read_b128 v[64:67], v130 offset:2176
	global_load_dwordx4 v[68:71], v[106:107], off offset:256
	global_load_dwordx4 v[72:75], v[108:109], off offset:256
	s_waitcnt vmcnt(0) lgkmcnt(0)
	v_pk_fma_f32 v[64:65], v[64:65], v[72:73], v[68:69]
	v_pk_fma_f32 v[66:67], v[66:67], v[74:75], v[70:71]
	global_store_dwordx4 v[106:107], v[64:67], off offset:256
	ds_read_b128 v[64:67], v130 offset:3264
	global_load_dwordx4 v[68:71], v[110:111], off offset:256
	global_load_dwordx4 v[72:75], v[112:113], off offset:256
	s_waitcnt vmcnt(0) lgkmcnt(0)
	v_pk_fma_f32 v[64:65], v[64:65], v[72:73], v[68:69]
	v_pk_fma_f32 v[66:67], v[66:67], v[74:75], v[70:71]
	global_store_dwordx4 v[110:111], v[64:67], off offset:256
	ds_read_b128 v[64:67], v130 offset:4352
	global_load_dwordx4 v[68:71], v[114:115], off offset:256
	global_load_dwordx4 v[72:75], v[116:117], off offset:256
	s_waitcnt vmcnt(0) lgkmcnt(0)
	v_pk_fma_f32 v[64:65], v[64:65], v[72:73], v[68:69]
	v_pk_fma_f32 v[66:67], v[66:67], v[74:75], v[70:71]
	global_store_dwordx4 v[114:115], v[64:67], off offset:256
	ds_read_b128 v[64:67], v130 offset:5440
	global_load_dwordx4 v[68:71], v[118:119], off offset:256
	global_load_dwordx4 v[72:75], v[120:121], off offset:256
	s_waitcnt vmcnt(0) lgkmcnt(0)
	v_pk_fma_f32 v[64:65], v[64:65], v[72:73], v[68:69]
	v_pk_fma_f32 v[66:67], v[66:67], v[74:75], v[70:71]
	global_store_dwordx4 v[118:119], v[64:67], off offset:256
	ds_read_b128 v[64:67], v130 offset:6528
	global_load_dwordx4 v[68:71], v[122:123], off offset:256
	global_load_dwordx4 v[72:75], v[124:125], off offset:256
	s_waitcnt vmcnt(0) lgkmcnt(0)
	v_pk_fma_f32 v[64:65], v[64:65], v[72:73], v[68:69]
	v_pk_fma_f32 v[66:67], v[66:67], v[74:75], v[70:71]
	global_store_dwordx4 v[122:123], v[64:67], off offset:256
	ds_read_b128 v[64:67], v130 offset:7616
	global_load_dwordx4 v[68:71], v[126:127], off offset:256
	global_load_dwordx4 v[72:75], v[128:129], off offset:256
	s_waitcnt vmcnt(0) lgkmcnt(0)
	v_pk_fma_f32 v[64:65], v[64:65], v[72:73], v[68:69]
	v_pk_fma_f32 v[66:67], v[66:67], v[74:75], v[70:71]
	global_store_dwordx4 v[126:127], v[64:67], off offset:256
	s_waitcnt lgkmcnt(0)
	ds_write2_b32 v131, v48, v49 offset1:68
	ds_write2_b32 v132, v32, v33 offset0:32 offset1:100
	ds_write2_b32 v131, v50, v51 offset0:136 offset1:204
	ds_write2_b32 v132, v34, v35 offset0:168 offset1:236
	ds_write2_b32 v133, v52, v53 offset0:32 offset1:100
	ds_write2_b32 v134, v36, v37 offset0:64 offset1:132
	ds_write2_b32 v133, v54, v55 offset0:168 offset1:236
	ds_write2_b32 v135, v38, v39 offset0:72 offset1:140
	ds_write2_b32 v136, v56, v57 offset0:64 offset1:132
	ds_write2_b32 v137, v40, v41 offset0:96 offset1:164
	ds_write2_b32 v138, v58, v59 offset0:72 offset1:140
	ds_write2_b32 v139, v42, v43 offset0:104 offset1:172
	ds_write2_b32 v140, v60, v61 offset0:96 offset1:164
	ds_write2_b32 v141, v44, v45 offset0:128 offset1:196
	ds_write2_b32 v142, v62, v63 offset0:104 offset1:172
	ds_write2_b32 v143, v46, v47 offset0:8 offset1:76
	v_or_b32_e32 v64, 32, v156
	v_or_b32_e32 v36, v64, v155
	v_cmp_gt_i32_e32 vcc, s39, v36
	v_ashrrev_i32_e32 v32, 31, v36
	v_add_u32_e32 v34, 0xffff8000, v36
	v_cndmask_b32_e32 v33, 0, v32, vcc
	v_cndmask_b32_e32 v32, v34, v36, vcc
	v_cndmask_b32_e32 v35, v144, v145, vcc
	v_cndmask_b32_e32 v34, v146, v147, vcc
	v_lshlrev_b64 v[32:33], 12, v[32:33]
	v_lshl_add_u64 v[32:33], v[34:35], 0, v[32:33]
	v_min_i32_e32 v34, 0x8000, v36
	v_ashrrev_i32_e32 v34, 12, v34
	v_mul_hi_i32_i24_e32 v35, 0x6000, v34
	v_mul_i32_i24_e32 v34, 0x6000, v34
	s_waitcnt lgkmcnt(0)
	v_lshl_add_u64 v[32:33], v[32:33], 0, v[96:97]
	v_lshl_add_u64 v[34:35], s[0:1], 0, v[34:35]
	v_lshl_add_u64 v[34:35], v[34:35], 0, v[96:97]
	ds_read_b128 v[36:39], v130
	global_load_dwordx4 v[40:43], v[32:33], off
	global_load_dwordx4 v[44:47], v[34:35], off
	s_waitcnt vmcnt(0) lgkmcnt(0)
	v_pk_fma_f32 v[36:37], v[36:37], v[44:45], v[40:41]
	v_pk_fma_f32 v[38:39], v[38:39], v[46:47], v[42:43]
	v_or_b32_e32 v40, v64, v148
	global_store_dwordx4 v[32:33], v[36:39], off
	v_cmp_gt_i32_e32 vcc, s39, v40
	s_nop 0
	v_ashrrev_i32_e32 v36, 31, v40
	v_add_u32_e32 v38, 0xffff8000, v40
	v_cndmask_b32_e32 v37, 0, v36, vcc
	v_cndmask_b32_e32 v36, v38, v40, vcc
	v_cndmask_b32_e32 v39, v144, v145, vcc
	v_cndmask_b32_e32 v38, v146, v147, vcc
	v_lshlrev_b64 v[36:37], 12, v[36:37]
	v_lshl_add_u64 v[36:37], v[38:39], 0, v[36:37]
	v_min_i32_e32 v38, 0x8000, v40
	v_ashrrev_i32_e32 v38, 12, v38
	v_mul_hi_i32_i24_e32 v39, 0x6000, v38
	v_mul_i32_i24_e32 v38, 0x6000, v38
	v_lshl_add_u64 v[36:37], v[36:37], 0, v[96:97]
	v_lshl_add_u64 v[38:39], s[0:1], 0, v[38:39]
	v_lshl_add_u64 v[38:39], v[38:39], 0, v[96:97]
	ds_read_b128 v[40:43], v130 offset:1088
	global_load_dwordx4 v[44:47], v[36:37], off
	global_load_dwordx4 v[48:51], v[38:39], off
	s_waitcnt vmcnt(0) lgkmcnt(0)
	v_pk_fma_f32 v[40:41], v[40:41], v[48:49], v[44:45]
	v_pk_fma_f32 v[42:43], v[42:43], v[50:51], v[46:47]
	v_or_b32_e32 v44, v64, v149
	global_store_dwordx4 v[36:37], v[40:43], off
	v_cmp_gt_i32_e32 vcc, s39, v44
	s_nop 0
	v_ashrrev_i32_e32 v40, 31, v44
	v_add_u32_e32 v42, 0xffff8000, v44
	v_cndmask_b32_e32 v41, 0, v40, vcc
	v_cndmask_b32_e32 v40, v42, v44, vcc
	v_cndmask_b32_e32 v43, v144, v145, vcc
	v_cndmask_b32_e32 v42, v146, v147, vcc
	v_lshlrev_b64 v[40:41], 12, v[40:41]
	v_lshl_add_u64 v[40:41], v[42:43], 0, v[40:41]
	v_min_i32_e32 v42, 0x8000, v44
	v_ashrrev_i32_e32 v42, 12, v42
	v_mul_hi_i32_i24_e32 v43, 0x6000, v42
	v_mul_i32_i24_e32 v42, 0x6000, v42
	v_lshl_add_u64 v[40:41], v[40:41], 0, v[96:97]
	v_lshl_add_u64 v[42:43], s[0:1], 0, v[42:43]
	v_lshl_add_u64 v[42:43], v[42:43], 0, v[96:97]
	ds_read_b128 v[44:47], v130 offset:2176
	global_load_dwordx4 v[48:51], v[40:41], off
	global_load_dwordx4 v[52:55], v[42:43], off
	s_waitcnt vmcnt(0) lgkmcnt(0)
	v_pk_fma_f32 v[44:45], v[44:45], v[52:53], v[48:49]
	v_pk_fma_f32 v[46:47], v[46:47], v[54:55], v[50:51]
	v_or_b32_e32 v48, v64, v150
	global_store_dwordx4 v[40:41], v[44:47], off
	v_cmp_gt_i32_e32 vcc, s39, v48
	s_nop 0
	v_ashrrev_i32_e32 v44, 31, v48
	v_add_u32_e32 v46, 0xffff8000, v48
	v_cndmask_b32_e32 v45, 0, v44, vcc
	v_cndmask_b32_e32 v44, v46, v48, vcc
	v_cndmask_b32_e32 v47, v144, v145, vcc
	v_cndmask_b32_e32 v46, v146, v147, vcc
	v_lshlrev_b64 v[44:45], 12, v[44:45]
	v_lshl_add_u64 v[44:45], v[46:47], 0, v[44:45]
	v_min_i32_e32 v46, 0x8000, v48
	v_ashrrev_i32_e32 v46, 12, v46
	v_mul_hi_i32_i24_e32 v47, 0x6000, v46
	v_mul_i32_i24_e32 v46, 0x6000, v46
	v_lshl_add_u64 v[44:45], v[44:45], 0, v[96:97]
	v_lshl_add_u64 v[46:47], s[0:1], 0, v[46:47]
	v_lshl_add_u64 v[46:47], v[46:47], 0, v[96:97]
	ds_read_b128 v[48:51], v130 offset:3264
	global_load_dwordx4 v[52:55], v[44:45], off
	global_load_dwordx4 v[56:59], v[46:47], off
	s_waitcnt vmcnt(0) lgkmcnt(0)
	v_pk_fma_f32 v[48:49], v[48:49], v[56:57], v[52:53]
	v_pk_fma_f32 v[50:51], v[50:51], v[58:59], v[54:55]
	v_or_b32_e32 v52, v64, v151
	global_store_dwordx4 v[44:45], v[48:51], off
	v_cmp_gt_i32_e32 vcc, s39, v52
	s_nop 0
	v_ashrrev_i32_e32 v48, 31, v52
	v_add_u32_e32 v50, 0xffff8000, v52
	v_cndmask_b32_e32 v49, 0, v48, vcc
	v_cndmask_b32_e32 v48, v50, v52, vcc
	v_cndmask_b32_e32 v51, v144, v145, vcc
	v_cndmask_b32_e32 v50, v146, v147, vcc
	v_lshlrev_b64 v[48:49], 12, v[48:49]
	v_lshl_add_u64 v[48:49], v[50:51], 0, v[48:49]
	v_min_i32_e32 v50, 0x8000, v52
	v_ashrrev_i32_e32 v50, 12, v50
	v_mul_hi_i32_i24_e32 v51, 0x6000, v50
	v_mul_i32_i24_e32 v50, 0x6000, v50
	v_lshl_add_u64 v[48:49], v[48:49], 0, v[96:97]
	v_lshl_add_u64 v[50:51], s[0:1], 0, v[50:51]
	v_lshl_add_u64 v[50:51], v[50:51], 0, v[96:97]
	ds_read_b128 v[52:55], v130 offset:4352
	global_load_dwordx4 v[56:59], v[48:49], off
	global_load_dwordx4 v[60:63], v[50:51], off
	s_waitcnt vmcnt(0) lgkmcnt(0)
	v_pk_fma_f32 v[52:53], v[52:53], v[60:61], v[56:57]
	v_pk_fma_f32 v[54:55], v[54:55], v[62:63], v[58:59]
	v_or_b32_e32 v56, v64, v152
	global_store_dwordx4 v[48:49], v[52:55], off
	v_cmp_gt_i32_e32 vcc, s39, v56
	s_nop 0
	v_ashrrev_i32_e32 v52, 31, v56
	v_add_u32_e32 v54, 0xffff8000, v56
	v_cndmask_b32_e32 v53, 0, v52, vcc
	v_cndmask_b32_e32 v52, v54, v56, vcc
	v_cndmask_b32_e32 v55, v144, v145, vcc
	v_cndmask_b32_e32 v54, v146, v147, vcc
	v_lshlrev_b64 v[52:53], 12, v[52:53]
	v_lshl_add_u64 v[52:53], v[54:55], 0, v[52:53]
	v_min_i32_e32 v54, 0x8000, v56
	v_ashrrev_i32_e32 v54, 12, v54
	v_mul_hi_i32_i24_e32 v55, 0x6000, v54
	v_mul_i32_i24_e32 v54, 0x6000, v54
	v_lshl_add_u64 v[52:53], v[52:53], 0, v[96:97]
	v_lshl_add_u64 v[54:55], s[0:1], 0, v[54:55]
	v_lshl_add_u64 v[54:55], v[54:55], 0, v[96:97]
	ds_read_b128 v[56:59], v130 offset:5440
	global_load_dwordx4 v[60:63], v[52:53], off
	global_load_dwordx4 v[66:69], v[54:55], off
	s_waitcnt vmcnt(0) lgkmcnt(0)
	v_pk_fma_f32 v[56:57], v[56:57], v[66:67], v[60:61]
	v_pk_fma_f32 v[58:59], v[58:59], v[68:69], v[62:63]
	v_or_b32_e32 v60, v64, v153
	global_store_dwordx4 v[52:53], v[56:59], off
	v_cmp_gt_i32_e32 vcc, s39, v60
	v_or_b32_e32 v64, v64, v154
	v_ashrrev_i32_e32 v56, 31, v60
	v_add_u32_e32 v58, 0xffff8000, v60
	v_cndmask_b32_e32 v57, 0, v56, vcc
	v_cndmask_b32_e32 v56, v58, v60, vcc
	v_cndmask_b32_e32 v59, v144, v145, vcc
	v_cndmask_b32_e32 v58, v146, v147, vcc
	v_lshlrev_b64 v[56:57], 12, v[56:57]
	v_lshl_add_u64 v[56:57], v[58:59], 0, v[56:57]
	v_min_i32_e32 v58, 0x8000, v60
	v_ashrrev_i32_e32 v58, 12, v58
	v_mul_hi_i32_i24_e32 v59, 0x6000, v58
	v_mul_i32_i24_e32 v58, 0x6000, v58
	v_lshl_add_u64 v[56:57], v[56:57], 0, v[96:97]
	v_lshl_add_u64 v[58:59], s[0:1], 0, v[58:59]
	v_lshl_add_u64 v[58:59], v[58:59], 0, v[96:97]
	ds_read_b128 v[60:63], v130 offset:6528
	global_load_dwordx4 v[66:69], v[56:57], off
	global_load_dwordx4 v[70:73], v[58:59], off
	v_cmp_gt_i32_e32 vcc, s39, v64
	s_waitcnt vmcnt(0) lgkmcnt(0)
	v_pk_fma_f32 v[60:61], v[60:61], v[70:71], v[66:67]
	v_pk_fma_f32 v[62:63], v[62:63], v[72:73], v[68:69]
	global_store_dwordx4 v[56:57], v[60:63], off
	s_nop 1
	v_ashrrev_i32_e32 v60, 31, v64
	v_add_u32_e32 v62, 0xffff8000, v64
	v_cndmask_b32_e32 v61, 0, v60, vcc
	v_cndmask_b32_e32 v60, v62, v64, vcc
	v_cndmask_b32_e32 v63, v144, v145, vcc
	v_cndmask_b32_e32 v62, v146, v147, vcc
	v_lshlrev_b64 v[60:61], 12, v[60:61]
	v_lshl_add_u64 v[60:61], v[62:63], 0, v[60:61]
	v_min_i32_e32 v62, 0x8000, v64
	v_ashrrev_i32_e32 v62, 12, v62
	v_mul_hi_i32_i24_e32 v63, 0x6000, v62
	v_mul_i32_i24_e32 v62, 0x6000, v62
	v_lshl_add_u64 v[60:61], v[60:61], 0, v[96:97]
	v_lshl_add_u64 v[62:63], s[0:1], 0, v[62:63]
	v_lshl_add_u64 v[62:63], v[62:63], 0, v[96:97]
	ds_read_b128 v[64:67], v130 offset:7616
	global_load_dwordx4 v[68:71], v[60:61], off
	global_load_dwordx4 v[72:75], v[62:63], off
	s_waitcnt vmcnt(0) lgkmcnt(0)
	v_pk_fma_f32 v[64:65], v[64:65], v[72:73], v[68:69]
	v_pk_fma_f32 v[66:67], v[66:67], v[74:75], v[70:71]
	global_store_dwordx4 v[60:61], v[64:67], off
	s_waitcnt lgkmcnt(0)
	ds_write2_b32 v131, v16, v17 offset1:68
	ds_write2_b32 v132, v0, v1 offset0:32 offset1:100
	ds_write2_b32 v131, v18, v19 offset0:136 offset1:204
	ds_write2_b32 v132, v2, v3 offset0:168 offset1:236
	ds_write2_b32 v133, v20, v21 offset0:32 offset1:100
	ds_write2_b32 v134, v4, v5 offset0:64 offset1:132
	ds_write2_b32 v133, v22, v23 offset0:168 offset1:236
	ds_write2_b32 v135, v6, v7 offset0:72 offset1:140
	ds_write2_b32 v136, v24, v25 offset0:64 offset1:132
	ds_write2_b32 v137, v8, v9 offset0:96 offset1:164
	ds_write2_b32 v138, v26, v27 offset0:72 offset1:140
	ds_write2_b32 v139, v10, v11 offset0:104 offset1:172
	ds_write2_b32 v140, v28, v29 offset0:96 offset1:164
	ds_write2_b32 v141, v12, v13 offset0:128 offset1:196
	ds_write2_b32 v142, v30, v31 offset0:104 offset1:172
	ds_write2_b32 v143, v14, v15 offset0:8 offset1:76
	s_waitcnt lgkmcnt(0)
	ds_read_b128 v[0:3], v130
	global_load_dwordx4 v[4:7], v[32:33], off offset:256
	global_load_dwordx4 v[8:11], v[34:35], off offset:256
	s_waitcnt vmcnt(0) lgkmcnt(0)
	v_pk_fma_f32 v[0:1], v[0:1], v[8:9], v[4:5]
	v_pk_fma_f32 v[2:3], v[2:3], v[10:11], v[6:7]
	global_store_dwordx4 v[32:33], v[0:3], off offset:256
	ds_read_b128 v[0:3], v130 offset:1088
	global_load_dwordx4 v[4:7], v[36:37], off offset:256
	global_load_dwordx4 v[8:11], v[38:39], off offset:256
	s_waitcnt vmcnt(0) lgkmcnt(0)
	v_pk_fma_f32 v[0:1], v[0:1], v[8:9], v[4:5]
	v_pk_fma_f32 v[2:3], v[2:3], v[10:11], v[6:7]
	global_store_dwordx4 v[36:37], v[0:3], off offset:256
	ds_read_b128 v[0:3], v130 offset:2176
	global_load_dwordx4 v[4:7], v[40:41], off offset:256
	global_load_dwordx4 v[8:11], v[42:43], off offset:256
	s_waitcnt vmcnt(0) lgkmcnt(0)
	v_pk_fma_f32 v[0:1], v[0:1], v[8:9], v[4:5]
	v_pk_fma_f32 v[2:3], v[2:3], v[10:11], v[6:7]
	global_store_dwordx4 v[40:41], v[0:3], off offset:256
	ds_read_b128 v[0:3], v130 offset:3264
	global_load_dwordx4 v[4:7], v[44:45], off offset:256
	global_load_dwordx4 v[8:11], v[46:47], off offset:256
	s_waitcnt vmcnt(0) lgkmcnt(0)
	v_pk_fma_f32 v[0:1], v[0:1], v[8:9], v[4:5]
	v_pk_fma_f32 v[2:3], v[2:3], v[10:11], v[6:7]
	global_store_dwordx4 v[44:45], v[0:3], off offset:256
	ds_read_b128 v[0:3], v130 offset:4352
	global_load_dwordx4 v[4:7], v[48:49], off offset:256
	global_load_dwordx4 v[8:11], v[50:51], off offset:256
	s_waitcnt vmcnt(0) lgkmcnt(0)
	v_pk_fma_f32 v[0:1], v[0:1], v[8:9], v[4:5]
	v_pk_fma_f32 v[2:3], v[2:3], v[10:11], v[6:7]
	global_store_dwordx4 v[48:49], v[0:3], off offset:256
	ds_read_b128 v[0:3], v130 offset:5440
	global_load_dwordx4 v[4:7], v[52:53], off offset:256
	global_load_dwordx4 v[8:11], v[54:55], off offset:256
	s_waitcnt vmcnt(0) lgkmcnt(0)
	v_pk_fma_f32 v[0:1], v[0:1], v[8:9], v[4:5]
	v_pk_fma_f32 v[2:3], v[2:3], v[10:11], v[6:7]
	global_store_dwordx4 v[52:53], v[0:3], off offset:256
	ds_read_b128 v[0:3], v130 offset:6528
	global_load_dwordx4 v[4:7], v[56:57], off offset:256
	global_load_dwordx4 v[8:11], v[58:59], off offset:256
	s_waitcnt vmcnt(0) lgkmcnt(0)
	v_pk_fma_f32 v[0:1], v[0:1], v[8:9], v[4:5]
	v_pk_fma_f32 v[2:3], v[2:3], v[10:11], v[6:7]
	global_store_dwordx4 v[56:57], v[0:3], off offset:256
	ds_read_b128 v[0:3], v130 offset:7616
	global_load_dwordx4 v[4:7], v[60:61], off offset:256
	global_load_dwordx4 v[8:11], v[62:63], off offset:256
	s_waitcnt vmcnt(0) lgkmcnt(0)
	v_pk_fma_f32 v[0:1], v[0:1], v[8:9], v[4:5]
	v_pk_fma_f32 v[2:3], v[2:3], v[10:11], v[6:7]
	global_store_dwordx4 v[60:61], v[0:3], off offset:256
	s_waitcnt lgkmcnt(0)
	s_barrier
	s_cbranch_scc1 .LBB0_1086
